# ffn1 dense+moe SwiGLU epilogues rewritten (f32 v_exp+v_rcp silu, LDS transpose, 16B row stores)
# speedup vs baseline: 1.1348x; 1.0066x over previous
; DI int otid512() { int t = threadIdx.x; asm volatile("" : "+v"(t)); return t; }
; template <bool GATHER>
; DI void gemm256_main(const h16* __restrict__ A, int lda, const int* __restrict__ idx, int m0,
;                      const h16* __restrict__ B, int ldb, int n0, int K, h16* lds, f16v (&acc)[4][2]) {
;   const int tid = otid512(), lane = tid & 63, wv = tid >> 6, wm = wv >> 2, wn = wv & 3;
;   const int lr = tid >> 1, lc = (tid & 1) * 32;
;   unsigned ao = (unsigned)(GATHER ? idx[m0 + lr] : (m0 + lr)) * (unsigned)lda + lc;
;   unsigned bo = (unsigned)(n0 + lr) * (unsigned)ldb + lc;
;   const h16* ap = A; const h16* bp = B;
;     ...
;   u4v ra[4], rb[4];
;   const int nk = K >> 6;
;   __syncthreads();
; #pragma unroll
;   for (int i = 0; i < 4; ++i) { ra[i] = *(const u4v*)(AP_ + 8 * i); rb[i] = *(const u4v*)(BP_ + 8 * i); }
;   ao += 64; bo += 64;
; #pragma unroll
;   for (int i = 0; i < 4; ++i) { *(u4v*)&lds[lr * LDH + lc + 8 * i] = ra[i]; *(u4v*)&lds[(256 + lr) * LDH + lc + 8 * i] = rb[i]; }
; #pragma unroll
;   for (int i = 0; i < 4; ++i) { ra[i] = *(const u4v*)(AP_ + 8 * i); rb[i] = *(const u4v*)(BP_ + 8 * i); }
;   ao += 64; bo += 64;
;   __syncthreads();
; DI void phase_ffn1_moe(const Params& p, int bid, int nb, h16* lds) {
;     ...
;   for (int u = bid; u < ntl; u += nb) {
;     const int mt = u / 11, m0 = mt * 256, n0 = (u % 11) * 256;
;     int e = 0;
; #pragma unroll
;     for (int i = 1; i < 8; ++i) if (m0 >= ps[i]) e = i;
;     f16v acc[4][2]; acc256_zero(acc);
;     gemm256_main<true>(x16, DM, st, m0, w13 + (size_t)e * 2816 * 1024, 1024, n0, 1024, lds, acc);
.LBB0_1520:
	s_mul_hi_i32 s6, s5, 0x2e8ba2e9
	s_lshr_b32 s7, s6, 31
	s_ashr_i32 s6, s6, 1
	s_add_i32 s7, s6, s7
	v_mov_b32_e32 v34, v180
	s_lshl_b32 s6, s7, 8
	s_cmp_lt_i32 s6, s2
	v_ashrrev_i32_e32 v35, 1, v34
	v_lshlrev_b32_e32 v4, 5, v34
	v_and_b32_e32 v36, 32, v4
	v_add_u32_e32 v4, s6, v35
	v_ashrrev_i32_e32 v5, 31, v4
	v_lshl_add_u64 v[4:5], v[4:5], 2, s[16:17]
	global_load_dword v4, v[4:5], off
	s_cselect_b32 s8, 0, 0x2c0000
	s_cmp_lt_i32 s6, s3
	s_cselect_b32 s8, s8, 0x580000
	v_cmp_lt_i32_e32 vcc, s6, v1
	v_mov_b32_e32 v2, s8
	s_mulk_i32 s7, 0xb00
	v_cndmask_b32_e32 v2, v206, v2, vcc
	v_cmp_lt_i32_e32 vcc, s6, v171
	v_subrev_u32_e32 v5, s7, v35
	v_mov_b32_e32 v3, v0
	v_cndmask_b32_e32 v2, v207, v2, vcc
	v_cmp_lt_i32_e32 vcc, s6, v178
	v_add_u32_e32 v5, s4, v5
	v_lshl_or_b32 v6, v5, 10, v36
	v_cndmask_b32_e32 v2, v208, v2, vcc
	v_cmp_lt_i32_e32 vcc, s6, v179
	v_mov_b32_e32 v5, v0
	v_mov_b32_e32 v7, v0
	v_cndmask_b32_e32 v2, v209, v2, vcc
	v_cmp_lt_i32_e32 vcc, s6, v215
	s_barrier
	s_nop 0
	v_cndmask_b32_e32 v2, v210, v2, vcc
	v_lshlrev_b64 v[2:3], 1, v[2:3]
	v_lshl_add_u64 v[2:3], s[18:19], 0, v[2:3]
	v_lshl_add_u64 v[176:177], v[6:7], 1, v[2:3]
	v_mul_lo_u32 v37, v35, s33
	s_add_i32 s8, 16, 0x12000
	s_add_i32 s9, 16, 0x1b000
	s_add_i32 s5, s5, s22
	s_waitcnt vmcnt(0)
	v_lshl_or_b32 v4, v4, 10, v36
	v_lshl_add_u64 v[174:175], v[4:5], 1, s[20:21]
	global_load_dwordx4 v[2:5], v[174:175], off offset:48
	global_load_dwordx4 v[6:9], v[174:175], off offset:32
	global_load_dwordx4 v[10:13], v[174:175], off offset:16
	global_load_dwordx4 v[14:17], v[174:175], off
	global_load_dwordx4 v[18:21], v[176:177], off offset:48
	global_load_dwordx4 v[22:25], v[176:177], off offset:32
	global_load_dwordx4 v[26:29], v[176:177], off offset:16
	global_load_dwordx4 v[30:33], v[176:177], off
	v_lshlrev_b32_e32 v36, 1, v36
	v_add3_u32 v221, 16, v37, v36
	v_add_u32_e32 v219, 0x12000, v221
	v_add_u32_e32 v220, 0x1b000, v221
	v_and_b32_e32 v36, 31, v34
	v_and_or_b32 v35, v35, s34, v36
	v_mul_lo_u32 v223, v35, s33
	v_and_b32_e32 v36, 0xdf, v34
	v_mul_u32_u24_e32 v222, 0x90, v36
	s_waitcnt vmcnt(4)
	ds_write_b128 v221, v[14:17]
	s_waitcnt vmcnt(0)
	ds_write_b128 v221, v[30:33] offset:36864
	ds_write_b128 v221, v[10:13] offset:16
	ds_write_b128 v221, v[26:29] offset:36880
	ds_write_b128 v221, v[6:9] offset:32
	ds_write_b128 v221, v[22:25] offset:36896
	ds_write_b128 v221, v[2:5] offset:48
	ds_write_b128 v221, v[18:21] offset:36912
	global_load_dwordx4 v[2:5], v[174:175], off offset:176
	global_load_dwordx4 v[6:9], v[174:175], off offset:160
	global_load_dwordx4 v[10:13], v[174:175], off offset:144
	global_load_dwordx4 v[14:17], v[174:175], off offset:128
	global_load_dwordx4 v[18:21], v[176:177], off offset:176
	global_load_dwordx4 v[22:25], v[176:177], off offset:160
	global_load_dwordx4 v[26:29], v[176:177], off offset:144
	global_load_dwordx4 v[30:33], v[176:177], off offset:128
	s_waitcnt lgkmcnt(0)
	s_barrier
	s_waitcnt vmcnt(4)
	ds_write_b128 v219, v[14:17]
	s_waitcnt vmcnt(0)
	ds_write_b128 v220, v[30:33]
	ds_write_b128 v219, v[10:13] offset:16
	ds_write_b128 v220, v[26:29] offset:16
	ds_write_b128 v219, v[6:9] offset:32
	ds_write_b128 v220, v[22:25] offset:32
	ds_write_b128 v219, v[2:5] offset:48
	ds_write_b128 v220, v[18:21] offset:48
	global_load_dwordx4 v[130:133], v[176:177], off offset:304
	global_load_dwordx4 v[134:137], v[176:177], off offset:288
	global_load_dwordx4 v[142:145], v[176:177], off offset:272
	global_load_dwordx4 v[150:153], v[176:177], off offset:256
	global_load_dwordx4 v[138:141], v[174:175], off offset:304
	global_load_dwordx4 v[146:149], v[174:175], off offset:288
	global_load_dwordx4 v[154:157], v[174:175], off offset:272
	global_load_dwordx4 v[158:161], v[174:175], off offset:256
	v_lshrrev_b32_e32 v2, 1, v34
	v_and_b32_e32 v224, 16, v2
	v_add_u32_e32 v10, 16, v224
	v_add_u32_e32 v218, v10, v223
	ds_read_b128 v[6:9], v218 offset:4608
	ds_read_b128 v[2:5], v218 offset:9216
	ds_read_b128 v[18:21], v218 offset:13824
	v_mad_u32_u24 v217, v36, s33, v10
	ds_read_b128 v[22:25], v217 offset:41472
	ds_read_b128 v[10:13], v218
	ds_read_b128 v[162:165], v218 offset:32
	ds_read_b128 v[14:17], v217 offset:36864
	ds_read_b128 v[226:229], v217 offset:36896
	s_waitcnt lgkmcnt(1)
	v_mfma_f32_32x32x16_f16 v[98:113], v[14:17], v[10:13], 0
	ds_read_b128 v[230:233], v218 offset:4640
	ds_read_b128 v[234:237], v218 offset:9248
	ds_read_b128 v[238:241], v218 offset:13856
	ds_read_b128 v[242:245], v217 offset:41504
	v_mfma_f32_32x32x16_f16 v[114:129], v[22:25], v[10:13], 0
	v_mfma_f32_32x32x16_f16 v[66:81], v[14:17], v[6:9], 0
	v_mfma_f32_32x32x16_f16 v[82:97], v[22:25], v[6:9], 0
	v_mfma_f32_32x32x16_f16 v[34:49], v[14:17], v[2:5], 0
	v_mfma_f32_32x32x16_f16 v[50:65], v[22:25], v[2:5], 0
	v_mfma_f32_32x32x16_f16 v[2:17], v[14:17], v[18:21], 0
	v_mfma_f32_32x32x16_f16 v[18:33], v[22:25], v[18:21], 0
	s_waitcnt lgkmcnt(4)
	v_mfma_f32_32x32x16_f16 v[98:113], v[226:229], v[162:165], v[98:113]
	s_waitcnt lgkmcnt(0)
	v_mfma_f32_32x32x16_f16 v[114:129], v[242:245], v[162:165], v[114:129]
	v_mfma_f32_32x32x16_f16 v[66:81], v[226:229], v[230:233], v[66:81]
	v_mfma_f32_32x32x16_f16 v[82:97], v[242:245], v[230:233], v[82:97]
	v_mfma_f32_32x32x16_f16 v[34:49], v[226:229], v[234:237], v[34:49]
	v_mfma_f32_32x32x16_f16 v[50:65], v[242:245], v[234:237], v[50:65]
	v_mfma_f32_32x32x16_f16 v[2:17], v[226:229], v[238:241], v[2:17]
	v_mfma_f32_32x32x16_f16 v[18:33], v[242:245], v[238:241], v[18:33]
	ds_read_b128 v[162:165], v218 offset:64
	ds_read_b128 v[226:229], v218 offset:4672
	ds_read_b128 v[230:233], v218 offset:9280
	ds_read_b128 v[234:237], v218 offset:13888
	ds_read_b128 v[238:241], v217 offset:36928
	ds_read_b128 v[242:245], v217 offset:41536
	s_waitcnt lgkmcnt(1)
	v_mfma_f32_32x32x16_f16 v[98:113], v[238:241], v[162:165], v[98:113]
	s_waitcnt lgkmcnt(0)
	v_mfma_f32_32x32x16_f16 v[114:129], v[242:245], v[162:165], v[114:129]
	v_mfma_f32_32x32x16_f16 v[66:81], v[238:241], v[226:229], v[66:81]
	v_mfma_f32_32x32x16_f16 v[82:97], v[242:245], v[226:229], v[82:97]
	v_mfma_f32_32x32x16_f16 v[34:49], v[238:241], v[230:233], v[34:49]
	v_mfma_f32_32x32x16_f16 v[50:65], v[242:245], v[230:233], v[50:65]
	v_mfma_f32_32x32x16_f16 v[2:17], v[238:241], v[234:237], v[2:17]
	v_mfma_f32_32x32x16_f16 v[18:33], v[242:245], v[234:237], v[18:33]
	ds_read_b128 v[162:165], v218 offset:96
	ds_read_b128 v[226:229], v218 offset:4704
	ds_read_b128 v[230:233], v218 offset:9312
	ds_read_b128 v[234:237], v218 offset:13920
	ds_read_b128 v[238:241], v217 offset:36960
	ds_read_b128 v[242:245], v217 offset:41568
	s_waitcnt lgkmcnt(0)
	s_barrier
; DI f16v mfma32(h8v a, h8v b, f16v c) { return __builtin_amdgcn_mfma_f32_32x32x16_f16(a, b, c, 0, 0, 0); }
; template <bool GATHER>
; DI void gemm256_main(const h16* __restrict__ A, int lda, const int* __restrict__ idx, int m0,
;                      const h16* __restrict__ B, int ldb, int n0, int K, h16* lds, f16v (&acc)[4][2]) {
;     ...
;   for (int kt = 0; kt < nk; ++kt) {
;     const h16* As = lds + (kt & 1) * (512 * LDH);
;     const h16* Bs = As + 256 * LDH;
;     h16* Wn = lds + ((kt & 1) ^ 1) * (512 * LDH);
;     if (kt + 1 < nk) {
; #pragma unroll
;       for (int i = 0; i < 4; ++i) { *(u4v*)&Wn[lr * LDH + lc + 8 * i] = ra[i]; *(u4v*)&Wn[(256 + lr) * LDH + lc + 8 * i] = rb[i]; }
;     }
;     if (kt + 2 < nk) {
; #pragma unroll
;       for (int i = 0; i < 4; ++i) { ra[i] = *(const u4v*)(AP_ + 8 * i); rb[i] = *(const u4v*)(BP_ + 8 * i); }
;       ao += 64; bo += 64;
;     }
; #pragma unroll
;     for (int ks = 0; ks < 4; ++ks) {
;       h8v af[4], bf[2];
; #pragma unroll
;       for (int i = 0; i < 4; ++i) af[i] = *(const h8v*)&As[(wm * 128 + i * 32 + (lane & 31)) * LDH + ks * 16 + 8 * (lane >> 5)];
; #pragma unroll
;       for (int j = 0; j < 2; ++j) bf[j] = *(const h8v*)&Bs[(wn * 64 + j * 32 + (lane & 31)) * LDH + ks * 16 + 8 * (lane >> 5)];
; #pragma unroll
;       for (int i = 0; i < 4; ++i)
; #pragma unroll
;         for (int j = 0; j < 2; ++j) acc[i][j] = mfma32(bf[j], af[i], acc[i][j]);
;     }
;     __syncthreads();
;   }
	s_waitcnt vmcnt(0)
	ds_write_b128 v221, v[158:161]
	ds_write_b128 v221, v[150:153] offset:36864
	ds_write_b128 v221, v[154:157] offset:16
	ds_write_b128 v221, v[142:145] offset:36880
	ds_write_b128 v221, v[146:149] offset:32
	ds_write_b128 v221, v[134:137] offset:36896
	ds_write_b128 v221, v[138:141] offset:48
	ds_write_b128 v221, v[130:133] offset:36912
	global_load_dwordx4 v[130:133], v[176:177], off offset:432
	global_load_dwordx4 v[134:137], v[176:177], off offset:416
	global_load_dwordx4 v[142:145], v[176:177], off offset:400
	global_load_dwordx4 v[150:153], v[176:177], off offset:384
	global_load_dwordx4 v[138:141], v[174:175], off offset:432
	global_load_dwordx4 v[146:149], v[174:175], off offset:416
	global_load_dwordx4 v[154:157], v[174:175], off offset:400
	global_load_dwordx4 v[158:161], v[174:175], off offset:384
	v_mfma_f32_32x32x16_f16 v[98:113], v[238:241], v[162:165], v[98:113]
	v_mfma_f32_32x32x16_f16 v[114:129], v[242:245], v[162:165], v[114:129]
	v_add3_u32 v162, s8, v224, v223
	v_add3_u32 v163, s9, v224, v222
	v_mfma_f32_32x32x16_f16 v[66:81], v[238:241], v[226:229], v[66:81]
	v_mfma_f32_32x32x16_f16 v[82:97], v[242:245], v[226:229], v[82:97]
	v_mfma_f32_32x32x16_f16 v[34:49], v[238:241], v[230:233], v[34:49]
	v_mfma_f32_32x32x16_f16 v[50:65], v[242:245], v[230:233], v[50:65]
	v_mfma_f32_32x32x16_f16 v[2:17], v[238:241], v[234:237], v[2:17]
	v_mfma_f32_32x32x16_f16 v[18:33], v[242:245], v[234:237], v[18:33]
	ds_read_b128 v[226:229], v162 offset:4608
	ds_read_b128 v[230:233], v162 offset:9216
	ds_read_b128 v[234:237], v162 offset:13824
	ds_read_b128 v[222:225], v163 offset:4608
	ds_read_b128 v[238:241], v162
	ds_read_b128 v[242:245], v162 offset:32
	ds_read_b128 v[246:249], v163
	ds_read_b128 v[200:203], v163 offset:32
	s_waitcnt lgkmcnt(1)
	v_mfma_f32_32x32x16_f16 v[98:113], v[246:249], v[238:241], v[98:113]
	v_mfma_f32_32x32x16_f16 v[114:129], v[222:225], v[238:241], v[114:129]
	v_mfma_f32_32x32x16_f16 v[66:81], v[246:249], v[226:229], v[66:81]
	v_mfma_f32_32x32x16_f16 v[82:97], v[222:225], v[226:229], v[82:97]
	v_mfma_f32_32x32x16_f16 v[34:49], v[246:249], v[230:233], v[34:49]
	v_mfma_f32_32x32x16_f16 v[50:65], v[222:225], v[230:233], v[50:65]
	v_mfma_f32_32x32x16_f16 v[2:17], v[246:249], v[234:237], v[2:17]
	v_mfma_f32_32x32x16_f16 v[18:33], v[222:225], v[234:237], v[18:33]
	ds_read_b128 v[222:225], v162 offset:4640
	ds_read_b128 v[226:229], v162 offset:9248
	ds_read_b128 v[230:233], v162 offset:13856
	ds_read_b128 v[234:237], v163 offset:4640
	s_waitcnt lgkmcnt(4)
	v_mfma_f32_32x32x16_f16 v[98:113], v[200:203], v[242:245], v[98:113]
	s_waitcnt lgkmcnt(0)
	v_mfma_f32_32x32x16_f16 v[114:129], v[234:237], v[242:245], v[114:129]
	v_mfma_f32_32x32x16_f16 v[66:81], v[200:203], v[222:225], v[66:81]
	v_mfma_f32_32x32x16_f16 v[82:97], v[234:237], v[222:225], v[82:97]
	v_mfma_f32_32x32x16_f16 v[34:49], v[200:203], v[226:229], v[34:49]
	v_mfma_f32_32x32x16_f16 v[50:65], v[234:237], v[226:229], v[50:65]
	v_mfma_f32_32x32x16_f16 v[2:17], v[200:203], v[230:233], v[2:17]
	v_mfma_f32_32x32x16_f16 v[18:33], v[234:237], v[230:233], v[18:33]
	ds_read_b128 v[200:203], v162 offset:64
	ds_read_b128 v[222:225], v162 offset:4672
	ds_read_b128 v[226:229], v162 offset:9280
	ds_read_b128 v[230:233], v162 offset:13888
	ds_read_b128 v[234:237], v163 offset:64
	ds_read_b128 v[238:241], v163 offset:4672
	s_waitcnt lgkmcnt(1)
	v_mfma_f32_32x32x16_f16 v[98:113], v[234:237], v[200:203], v[98:113]
	s_waitcnt lgkmcnt(0)
	v_mfma_f32_32x32x16_f16 v[114:129], v[238:241], v[200:203], v[114:129]
	v_mfma_f32_32x32x16_f16 v[66:81], v[234:237], v[222:225], v[66:81]
	v_mfma_f32_32x32x16_f16 v[82:97], v[238:241], v[222:225], v[82:97]
	v_mfma_f32_32x32x16_f16 v[34:49], v[234:237], v[226:229], v[34:49]
	v_mfma_f32_32x32x16_f16 v[50:65], v[238:241], v[226:229], v[50:65]
	v_mfma_f32_32x32x16_f16 v[2:17], v[234:237], v[230:233], v[2:17]
	v_mfma_f32_32x32x16_f16 v[18:33], v[238:241], v[230:233], v[18:33]
	ds_read_b128 v[200:203], v162 offset:96
	ds_read_b128 v[222:225], v162 offset:4704
	ds_read_b128 v[226:229], v162 offset:9312
	ds_read_b128 v[230:233], v162 offset:13920
	ds_read_b128 v[234:237], v163 offset:96
	ds_read_b128 v[238:241], v163 offset:4704
	s_waitcnt lgkmcnt(0)
	s_barrier
; DI f16v mfma32(h8v a, h8v b, f16v c) { return __builtin_amdgcn_mfma_f32_32x32x16_f16(a, b, c, 0, 0, 0); }
; template <bool GATHER>
; DI void gemm256_main(const h16* __restrict__ A, int lda, const int* __restrict__ idx, int m0,
;                      const h16* __restrict__ B, int ldb, int n0, int K, h16* lds, f16v (&acc)[4][2]) {
;     ...
;   for (int kt = 0; kt < nk; ++kt) {
;     const h16* As = lds + (kt & 1) * (512 * LDH);
;     const h16* Bs = As + 256 * LDH;
;     h16* Wn = lds + ((kt & 1) ^ 1) * (512 * LDH);
;     if (kt + 1 < nk) {
; #pragma unroll
;       for (int i = 0; i < 4; ++i) { *(u4v*)&Wn[lr * LDH + lc + 8 * i] = ra[i]; *(u4v*)&Wn[(256 + lr) * LDH + lc + 8 * i] = rb[i]; }
;     }
;     if (kt + 2 < nk) {
; #pragma unroll
;       for (int i = 0; i < 4; ++i) { ra[i] = *(const u4v*)(AP_ + 8 * i); rb[i] = *(const u4v*)(BP_ + 8 * i); }
;       ao += 64; bo += 64;
;     }
; #pragma unroll
;     for (int ks = 0; ks < 4; ++ks) {
;       h8v af[4], bf[2];
; #pragma unroll
;       for (int i = 0; i < 4; ++i) af[i] = *(const h8v*)&As[(wm * 128 + i * 32 + (lane & 31)) * LDH + ks * 16 + 8 * (lane >> 5)];
; #pragma unroll
;       for (int j = 0; j < 2; ++j) bf[j] = *(const h8v*)&Bs[(wn * 64 + j * 32 + (lane & 31)) * LDH + ks * 16 + 8 * (lane >> 5)];
; #pragma unroll
;       for (int i = 0; i < 4; ++i)
; #pragma unroll
;         for (int j = 0; j < 2; ++j) acc[i][j] = mfma32(bf[j], af[i], acc[i][j]);
;     }
;     __syncthreads();
;   }
	s_waitcnt vmcnt(0)
	ds_write_b128 v219, v[158:161]
	ds_write_b128 v220, v[150:153]
	ds_write_b128 v219, v[154:157] offset:16
	ds_write_b128 v220, v[142:145] offset:16
	ds_write_b128 v219, v[146:149] offset:32
	ds_write_b128 v220, v[134:137] offset:32
	ds_write_b128 v219, v[138:141] offset:48
	ds_write_b128 v220, v[130:133] offset:48
	global_load_dwordx4 v[130:133], v[176:177], off offset:560
	global_load_dwordx4 v[134:137], v[176:177], off offset:544
	global_load_dwordx4 v[142:145], v[176:177], off offset:528
	global_load_dwordx4 v[150:153], v[176:177], off offset:512
	global_load_dwordx4 v[138:141], v[174:175], off offset:560
	global_load_dwordx4 v[146:149], v[174:175], off offset:544
	global_load_dwordx4 v[154:157], v[174:175], off offset:528
	global_load_dwordx4 v[158:161], v[174:175], off offset:512
	v_mfma_f32_32x32x16_f16 v[98:113], v[234:237], v[200:203], v[98:113]
	v_mfma_f32_32x32x16_f16 v[114:129], v[238:241], v[200:203], v[114:129]
	v_mfma_f32_32x32x16_f16 v[66:81], v[234:237], v[222:225], v[66:81]
	v_mfma_f32_32x32x16_f16 v[82:97], v[238:241], v[222:225], v[82:97]
	v_mfma_f32_32x32x16_f16 v[34:49], v[234:237], v[226:229], v[34:49]
	v_mfma_f32_32x32x16_f16 v[50:65], v[238:241], v[226:229], v[50:65]
	v_mfma_f32_32x32x16_f16 v[2:17], v[234:237], v[230:233], v[2:17]
	v_mfma_f32_32x32x16_f16 v[18:33], v[238:241], v[230:233], v[18:33]
	ds_read_b128 v[200:203], v218 offset:4608
	ds_read_b128 v[222:225], v218 offset:9216
	ds_read_b128 v[226:229], v218 offset:13824
	ds_read_b128 v[230:233], v217 offset:41472
	ds_read_b128 v[234:237], v218
	ds_read_b128 v[238:241], v218 offset:32
	ds_read_b128 v[242:245], v217 offset:36864
	ds_read_b128 v[246:249], v217 offset:36896
	s_waitcnt lgkmcnt(1)
	v_mfma_f32_32x32x16_f16 v[98:113], v[242:245], v[234:237], v[98:113]
	v_mfma_f32_32x32x16_f16 v[114:129], v[230:233], v[234:237], v[114:129]
	v_mfma_f32_32x32x16_f16 v[66:81], v[242:245], v[200:203], v[66:81]
	v_mfma_f32_32x32x16_f16 v[82:97], v[230:233], v[200:203], v[82:97]
	v_mfma_f32_32x32x16_f16 v[34:49], v[242:245], v[222:225], v[34:49]
	v_mfma_f32_32x32x16_f16 v[50:65], v[230:233], v[222:225], v[50:65]
	v_mfma_f32_32x32x16_f16 v[2:17], v[242:245], v[226:229], v[2:17]
	v_mfma_f32_32x32x16_f16 v[18:33], v[230:233], v[226:229], v[18:33]
	ds_read_b128 v[200:203], v218 offset:4640
	ds_read_b128 v[222:225], v218 offset:9248
	ds_read_b128 v[226:229], v218 offset:13856
	ds_read_b128 v[230:233], v217 offset:41504
	s_waitcnt lgkmcnt(4)
	v_mfma_f32_32x32x16_f16 v[98:113], v[246:249], v[238:241], v[98:113]
	s_waitcnt lgkmcnt(0)
	v_mfma_f32_32x32x16_f16 v[114:129], v[230:233], v[238:241], v[114:129]
	v_mfma_f32_32x32x16_f16 v[66:81], v[246:249], v[200:203], v[66:81]
	v_mfma_f32_32x32x16_f16 v[82:97], v[230:233], v[200:203], v[82:97]
	v_mfma_f32_32x32x16_f16 v[34:49], v[246:249], v[222:225], v[34:49]
	v_mfma_f32_32x32x16_f16 v[50:65], v[230:233], v[222:225], v[50:65]
	v_mfma_f32_32x32x16_f16 v[2:17], v[246:249], v[226:229], v[2:17]
	v_mfma_f32_32x32x16_f16 v[18:33], v[230:233], v[226:229], v[18:33]
	ds_read_b128 v[200:203], v218 offset:64
	ds_read_b128 v[222:225], v218 offset:4672
	ds_read_b128 v[226:229], v218 offset:9280
	ds_read_b128 v[230:233], v218 offset:13888
	ds_read_b128 v[234:237], v217 offset:36928
	ds_read_b128 v[238:241], v217 offset:41536
	s_waitcnt lgkmcnt(1)
	v_mfma_f32_32x32x16_f16 v[98:113], v[234:237], v[200:203], v[98:113]
	s_waitcnt lgkmcnt(0)
	v_mfma_f32_32x32x16_f16 v[114:129], v[238:241], v[200:203], v[114:129]
	v_mfma_f32_32x32x16_f16 v[66:81], v[234:237], v[222:225], v[66:81]
	v_mfma_f32_32x32x16_f16 v[82:97], v[238:241], v[222:225], v[82:97]
	v_mfma_f32_32x32x16_f16 v[34:49], v[234:237], v[226:229], v[34:49]
	v_mfma_f32_32x32x16_f16 v[50:65], v[238:241], v[226:229], v[50:65]
	v_mfma_f32_32x32x16_f16 v[2:17], v[234:237], v[230:233], v[2:17]
	v_mfma_f32_32x32x16_f16 v[18:33], v[238:241], v[230:233], v[18:33]
	ds_read_b128 v[200:203], v218 offset:96
	ds_read_b128 v[222:225], v218 offset:4704
	ds_read_b128 v[226:229], v218 offset:9312
	ds_read_b128 v[230:233], v218 offset:13920
	ds_read_b128 v[234:237], v217 offset:36960
	ds_read_b128 v[238:241], v217 offset:41568
	s_waitcnt lgkmcnt(0)
	s_barrier
	s_waitcnt vmcnt(0)
	ds_write_b128 v221, v[158:161]
	ds_write_b128 v221, v[150:153] offset:36864
	ds_write_b128 v221, v[154:157] offset:16
	ds_write_b128 v221, v[142:145] offset:36880
	ds_write_b128 v221, v[146:149] offset:32
	ds_write_b128 v221, v[134:137] offset:36896
	ds_write_b128 v221, v[138:141] offset:48
	ds_write_b128 v221, v[130:133] offset:36912
	global_load_dwordx4 v[130:133], v[176:177], off offset:688
	global_load_dwordx4 v[134:137], v[176:177], off offset:672
	global_load_dwordx4 v[142:145], v[176:177], off offset:656
	global_load_dwordx4 v[150:153], v[176:177], off offset:640
	global_load_dwordx4 v[138:141], v[174:175], off offset:688
	global_load_dwordx4 v[146:149], v[174:175], off offset:672
	global_load_dwordx4 v[154:157], v[174:175], off offset:656
	global_load_dwordx4 v[158:161], v[174:175], off offset:640
	v_mfma_f32_32x32x16_f16 v[98:113], v[234:237], v[200:203], v[98:113]
	v_mfma_f32_32x32x16_f16 v[114:129], v[238:241], v[200:203], v[114:129]
	v_mfma_f32_32x32x16_f16 v[66:81], v[234:237], v[222:225], v[66:81]
	v_mfma_f32_32x32x16_f16 v[82:97], v[238:241], v[222:225], v[82:97]
	v_mfma_f32_32x32x16_f16 v[34:49], v[234:237], v[226:229], v[34:49]
	v_mfma_f32_32x32x16_f16 v[50:65], v[238:241], v[226:229], v[50:65]
	v_mfma_f32_32x32x16_f16 v[2:17], v[234:237], v[230:233], v[2:17]
	v_mfma_f32_32x32x16_f16 v[18:33], v[238:241], v[230:233], v[18:33]
	ds_read_b128 v[200:203], v162 offset:4608
	ds_read_b128 v[222:225], v162 offset:9216
	ds_read_b128 v[226:229], v162 offset:13824
	ds_read_b128 v[230:233], v163 offset:4608
	ds_read_b128 v[234:237], v162
	ds_read_b128 v[238:241], v162 offset:32
	ds_read_b128 v[242:245], v163
	ds_read_b128 v[246:249], v163 offset:32
	s_waitcnt lgkmcnt(1)
; DI f16v mfma32(h8v a, h8v b, f16v c) { return __builtin_amdgcn_mfma_f32_32x32x16_f16(a, b, c, 0, 0, 0); }
; template <bool GATHER>
; DI void gemm256_main(const h16* __restrict__ A, int lda, const int* __restrict__ idx, int m0,
;                      const h16* __restrict__ B, int ldb, int n0, int K, h16* lds, f16v (&acc)[4][2]) {
;     ...
;   for (int kt = 0; kt < nk; ++kt) {
;     const h16* As = lds + (kt & 1) * (512 * LDH);
;     const h16* Bs = As + 256 * LDH;
;     h16* Wn = lds + ((kt & 1) ^ 1) * (512 * LDH);
;     if (kt + 1 < nk) {
; #pragma unroll
;       for (int i = 0; i < 4; ++i) { *(u4v*)&Wn[lr * LDH + lc + 8 * i] = ra[i]; *(u4v*)&Wn[(256 + lr) * LDH + lc + 8 * i] = rb[i]; }
;     }
;     if (kt + 2 < nk) {
; #pragma unroll
;       for (int i = 0; i < 4; ++i) { ra[i] = *(const u4v*)(AP_ + 8 * i); rb[i] = *(const u4v*)(BP_ + 8 * i); }
;       ao += 64; bo += 64;
;     }
; #pragma unroll
;     for (int ks = 0; ks < 4; ++ks) {
;       h8v af[4], bf[2];
; #pragma unroll
;       for (int i = 0; i < 4; ++i) af[i] = *(const h8v*)&As[(wm * 128 + i * 32 + (lane & 31)) * LDH + ks * 16 + 8 * (lane >> 5)];
; #pragma unroll
;       for (int j = 0; j < 2; ++j) bf[j] = *(const h8v*)&Bs[(wn * 64 + j * 32 + (lane & 31)) * LDH + ks * 16 + 8 * (lane >> 5)];
; #pragma unroll
;       for (int i = 0; i < 4; ++i)
; #pragma unroll
;         for (int j = 0; j < 2; ++j) acc[i][j] = mfma32(bf[j], af[i], acc[i][j]);
;     }
;     __syncthreads();
;   }
	v_mfma_f32_32x32x16_f16 v[98:113], v[242:245], v[234:237], v[98:113]
	v_mfma_f32_32x32x16_f16 v[114:129], v[230:233], v[234:237], v[114:129]
	v_mfma_f32_32x32x16_f16 v[66:81], v[242:245], v[200:203], v[66:81]
	v_mfma_f32_32x32x16_f16 v[82:97], v[230:233], v[200:203], v[82:97]
	v_mfma_f32_32x32x16_f16 v[34:49], v[242:245], v[222:225], v[34:49]
	v_mfma_f32_32x32x16_f16 v[50:65], v[230:233], v[222:225], v[50:65]
	v_mfma_f32_32x32x16_f16 v[2:17], v[242:245], v[226:229], v[2:17]
	v_mfma_f32_32x32x16_f16 v[18:33], v[230:233], v[226:229], v[18:33]
	ds_read_b128 v[200:203], v162 offset:4640
	ds_read_b128 v[222:225], v162 offset:9248
	ds_read_b128 v[226:229], v162 offset:13856
	ds_read_b128 v[230:233], v163 offset:4640
	s_waitcnt lgkmcnt(4)
	v_mfma_f32_32x32x16_f16 v[98:113], v[246:249], v[238:241], v[98:113]
	s_waitcnt lgkmcnt(0)
	v_mfma_f32_32x32x16_f16 v[114:129], v[230:233], v[238:241], v[114:129]
	v_mfma_f32_32x32x16_f16 v[66:81], v[246:249], v[200:203], v[66:81]
	v_mfma_f32_32x32x16_f16 v[82:97], v[230:233], v[200:203], v[82:97]
	v_mfma_f32_32x32x16_f16 v[34:49], v[246:249], v[222:225], v[34:49]
	v_mfma_f32_32x32x16_f16 v[50:65], v[230:233], v[222:225], v[50:65]
	v_mfma_f32_32x32x16_f16 v[2:17], v[246:249], v[226:229], v[2:17]
	v_mfma_f32_32x32x16_f16 v[18:33], v[230:233], v[226:229], v[18:33]
	ds_read_b128 v[200:203], v162 offset:64
	ds_read_b128 v[222:225], v162 offset:4672
	ds_read_b128 v[226:229], v162 offset:9280
	ds_read_b128 v[230:233], v162 offset:13888
	ds_read_b128 v[234:237], v163 offset:64
	ds_read_b128 v[238:241], v163 offset:4672
	s_waitcnt lgkmcnt(1)
	v_mfma_f32_32x32x16_f16 v[98:113], v[234:237], v[200:203], v[98:113]
	s_waitcnt lgkmcnt(0)
	v_mfma_f32_32x32x16_f16 v[114:129], v[238:241], v[200:203], v[114:129]
	v_mfma_f32_32x32x16_f16 v[66:81], v[234:237], v[222:225], v[66:81]
	v_mfma_f32_32x32x16_f16 v[82:97], v[238:241], v[222:225], v[82:97]
	v_mfma_f32_32x32x16_f16 v[34:49], v[234:237], v[226:229], v[34:49]
	v_mfma_f32_32x32x16_f16 v[50:65], v[238:241], v[226:229], v[50:65]
	v_mfma_f32_32x32x16_f16 v[2:17], v[234:237], v[230:233], v[2:17]
	v_mfma_f32_32x32x16_f16 v[18:33], v[238:241], v[230:233], v[18:33]
	ds_read_b128 v[200:203], v162 offset:96
	ds_read_b128 v[222:225], v162 offset:4704
	ds_read_b128 v[226:229], v162 offset:9312
	ds_read_b128 v[230:233], v162 offset:13920
	ds_read_b128 v[234:237], v163 offset:96
	ds_read_b128 v[238:241], v163 offset:4704
	s_waitcnt lgkmcnt(0)
	s_barrier
	s_waitcnt vmcnt(0)
	ds_write_b128 v219, v[158:161]
	ds_write_b128 v220, v[150:153]
	ds_write_b128 v219, v[154:157] offset:16
	ds_write_b128 v220, v[142:145] offset:16
	ds_write_b128 v219, v[146:149] offset:32
	ds_write_b128 v220, v[134:137] offset:32
	ds_write_b128 v219, v[138:141] offset:48
	ds_write_b128 v220, v[130:133] offset:48
	global_load_dwordx4 v[130:133], v[176:177], off offset:816
	global_load_dwordx4 v[134:137], v[176:177], off offset:800
	global_load_dwordx4 v[142:145], v[176:177], off offset:784
	global_load_dwordx4 v[150:153], v[176:177], off offset:768
	global_load_dwordx4 v[138:141], v[174:175], off offset:816
	global_load_dwordx4 v[146:149], v[174:175], off offset:800
	global_load_dwordx4 v[154:157], v[174:175], off offset:784
	global_load_dwordx4 v[158:161], v[174:175], off offset:768
	v_mfma_f32_32x32x16_f16 v[98:113], v[234:237], v[200:203], v[98:113]
	v_mfma_f32_32x32x16_f16 v[114:129], v[238:241], v[200:203], v[114:129]
	v_mfma_f32_32x32x16_f16 v[66:81], v[234:237], v[222:225], v[66:81]
	v_mfma_f32_32x32x16_f16 v[82:97], v[238:241], v[222:225], v[82:97]
	v_mfma_f32_32x32x16_f16 v[34:49], v[234:237], v[226:229], v[34:49]
	v_mfma_f32_32x32x16_f16 v[50:65], v[238:241], v[226:229], v[50:65]
	v_mfma_f32_32x32x16_f16 v[2:17], v[234:237], v[230:233], v[2:17]
	v_mfma_f32_32x32x16_f16 v[18:33], v[238:241], v[230:233], v[18:33]
	ds_read_b128 v[200:203], v218 offset:4608
	ds_read_b128 v[222:225], v218 offset:9216
	ds_read_b128 v[226:229], v218 offset:13824
	ds_read_b128 v[230:233], v217 offset:41472
	ds_read_b128 v[234:237], v218
	ds_read_b128 v[238:241], v218 offset:32
	ds_read_b128 v[242:245], v217 offset:36864
	ds_read_b128 v[246:249], v217 offset:36896
	s_waitcnt lgkmcnt(1)
	v_mfma_f32_32x32x16_f16 v[98:113], v[242:245], v[234:237], v[98:113]
	v_mfma_f32_32x32x16_f16 v[114:129], v[230:233], v[234:237], v[114:129]
	v_mfma_f32_32x32x16_f16 v[66:81], v[242:245], v[200:203], v[66:81]
	v_mfma_f32_32x32x16_f16 v[82:97], v[230:233], v[200:203], v[82:97]
	v_mfma_f32_32x32x16_f16 v[34:49], v[242:245], v[222:225], v[34:49]
	v_mfma_f32_32x32x16_f16 v[50:65], v[230:233], v[222:225], v[50:65]
	v_mfma_f32_32x32x16_f16 v[2:17], v[242:245], v[226:229], v[2:17]
	v_mfma_f32_32x32x16_f16 v[18:33], v[230:233], v[226:229], v[18:33]
	ds_read_b128 v[200:203], v218 offset:4640
	ds_read_b128 v[222:225], v218 offset:9248
	ds_read_b128 v[226:229], v218 offset:13856
	ds_read_b128 v[230:233], v217 offset:41504
	s_waitcnt lgkmcnt(4)
	v_mfma_f32_32x32x16_f16 v[98:113], v[246:249], v[238:241], v[98:113]
	s_waitcnt lgkmcnt(0)
	v_mfma_f32_32x32x16_f16 v[114:129], v[230:233], v[238:241], v[114:129]
	v_mfma_f32_32x32x16_f16 v[66:81], v[246:249], v[200:203], v[66:81]
	v_mfma_f32_32x32x16_f16 v[82:97], v[230:233], v[200:203], v[82:97]
	v_mfma_f32_32x32x16_f16 v[34:49], v[246:249], v[222:225], v[34:49]
	v_mfma_f32_32x32x16_f16 v[50:65], v[230:233], v[222:225], v[50:65]
	v_mfma_f32_32x32x16_f16 v[2:17], v[246:249], v[226:229], v[2:17]
	v_mfma_f32_32x32x16_f16 v[18:33], v[230:233], v[226:229], v[18:33]
	ds_read_b128 v[200:203], v218 offset:64
	ds_read_b128 v[222:225], v218 offset:4672
	ds_read_b128 v[226:229], v218 offset:9280
	ds_read_b128 v[230:233], v218 offset:13888
	ds_read_b128 v[234:237], v217 offset:36928
	ds_read_b128 v[238:241], v217 offset:41536
	s_waitcnt lgkmcnt(1)
	v_mfma_f32_32x32x16_f16 v[98:113], v[234:237], v[200:203], v[98:113]
	s_waitcnt lgkmcnt(0)
	v_mfma_f32_32x32x16_f16 v[114:129], v[238:241], v[200:203], v[114:129]
	v_mfma_f32_32x32x16_f16 v[66:81], v[234:237], v[222:225], v[66:81]
	v_mfma_f32_32x32x16_f16 v[82:97], v[238:241], v[222:225], v[82:97]
	v_mfma_f32_32x32x16_f16 v[34:49], v[234:237], v[226:229], v[34:49]
	v_mfma_f32_32x32x16_f16 v[50:65], v[238:241], v[226:229], v[50:65]
	v_mfma_f32_32x32x16_f16 v[2:17], v[234:237], v[230:233], v[2:17]
	v_mfma_f32_32x32x16_f16 v[18:33], v[238:241], v[230:233], v[18:33]
	ds_read_b128 v[200:203], v218 offset:96
	ds_read_b128 v[222:225], v218 offset:4704
	ds_read_b128 v[226:229], v218 offset:9312
	ds_read_b128 v[230:233], v218 offset:13920
	ds_read_b128 v[234:237], v217 offset:36960
	ds_read_b128 v[238:241], v217 offset:41568
	s_waitcnt lgkmcnt(0)
	s_barrier
; DI f16v mfma32(h8v a, h8v b, f16v c) { return __builtin_amdgcn_mfma_f32_32x32x16_f16(a, b, c, 0, 0, 0); }
; template <bool GATHER>
; DI void gemm256_main(const h16* __restrict__ A, int lda, const int* __restrict__ idx, int m0,
;                      const h16* __restrict__ B, int ldb, int n0, int K, h16* lds, f16v (&acc)[4][2]) {
;     ...
;   for (int kt = 0; kt < nk; ++kt) {
;     const h16* As = lds + (kt & 1) * (512 * LDH);
;     const h16* Bs = As + 256 * LDH;
;     h16* Wn = lds + ((kt & 1) ^ 1) * (512 * LDH);
;     if (kt + 1 < nk) {
; #pragma unroll
;       for (int i = 0; i < 4; ++i) { *(u4v*)&Wn[lr * LDH + lc + 8 * i] = ra[i]; *(u4v*)&Wn[(256 + lr) * LDH + lc + 8 * i] = rb[i]; }
;     }
;     if (kt + 2 < nk) {
; #pragma unroll
;       for (int i = 0; i < 4; ++i) { ra[i] = *(const u4v*)(AP_ + 8 * i); rb[i] = *(const u4v*)(BP_ + 8 * i); }
;       ao += 64; bo += 64;
;     }
; #pragma unroll
;     for (int ks = 0; ks < 4; ++ks) {
;       h8v af[4], bf[2];
; #pragma unroll
;       for (int i = 0; i < 4; ++i) af[i] = *(const h8v*)&As[(wm * 128 + i * 32 + (lane & 31)) * LDH + ks * 16 + 8 * (lane >> 5)];
; #pragma unroll
;       for (int j = 0; j < 2; ++j) bf[j] = *(const h8v*)&Bs[(wn * 64 + j * 32 + (lane & 31)) * LDH + ks * 16 + 8 * (lane >> 5)];
; #pragma unroll
;       for (int i = 0; i < 4; ++i)
; #pragma unroll
;         for (int j = 0; j < 2; ++j) acc[i][j] = mfma32(bf[j], af[i], acc[i][j]);
;     }
;     __syncthreads();
;   }
	s_waitcnt vmcnt(0)
	ds_write_b128 v221, v[158:161]
	ds_write_b128 v221, v[150:153] offset:36864
	ds_write_b128 v221, v[154:157] offset:16
	ds_write_b128 v221, v[142:145] offset:36880
	ds_write_b128 v221, v[146:149] offset:32
	ds_write_b128 v221, v[134:137] offset:36896
	ds_write_b128 v221, v[138:141] offset:48
	ds_write_b128 v221, v[130:133] offset:36912
	global_load_dwordx4 v[130:133], v[176:177], off offset:944
	global_load_dwordx4 v[134:137], v[176:177], off offset:928
	global_load_dwordx4 v[142:145], v[176:177], off offset:912
	global_load_dwordx4 v[150:153], v[176:177], off offset:896
	global_load_dwordx4 v[138:141], v[174:175], off offset:944
	global_load_dwordx4 v[146:149], v[174:175], off offset:928
	global_load_dwordx4 v[154:157], v[174:175], off offset:912
	global_load_dwordx4 v[158:161], v[174:175], off offset:896
	v_mfma_f32_32x32x16_f16 v[98:113], v[234:237], v[200:203], v[98:113]
	v_mfma_f32_32x32x16_f16 v[114:129], v[238:241], v[200:203], v[114:129]
	v_mfma_f32_32x32x16_f16 v[66:81], v[234:237], v[222:225], v[66:81]
	v_mfma_f32_32x32x16_f16 v[82:97], v[238:241], v[222:225], v[82:97]
	v_mfma_f32_32x32x16_f16 v[34:49], v[234:237], v[226:229], v[34:49]
	v_mfma_f32_32x32x16_f16 v[50:65], v[238:241], v[226:229], v[50:65]
	v_mfma_f32_32x32x16_f16 v[2:17], v[234:237], v[230:233], v[2:17]
	v_mfma_f32_32x32x16_f16 v[18:33], v[238:241], v[230:233], v[18:33]
	ds_read_b128 v[200:203], v162 offset:4608
	ds_read_b128 v[222:225], v162 offset:9216
	ds_read_b128 v[226:229], v162 offset:13824
	ds_read_b128 v[230:233], v163 offset:4608
	ds_read_b128 v[234:237], v162
	ds_read_b128 v[238:241], v162 offset:32
	ds_read_b128 v[242:245], v163
	ds_read_b128 v[246:249], v163 offset:32
	s_waitcnt lgkmcnt(1)
	v_mfma_f32_32x32x16_f16 v[98:113], v[242:245], v[234:237], v[98:113]
	v_mfma_f32_32x32x16_f16 v[114:129], v[230:233], v[234:237], v[114:129]
	v_mfma_f32_32x32x16_f16 v[66:81], v[242:245], v[200:203], v[66:81]
	v_mfma_f32_32x32x16_f16 v[82:97], v[230:233], v[200:203], v[82:97]
	v_mfma_f32_32x32x16_f16 v[34:49], v[242:245], v[222:225], v[34:49]
	v_mfma_f32_32x32x16_f16 v[50:65], v[230:233], v[222:225], v[50:65]
	v_mfma_f32_32x32x16_f16 v[2:17], v[242:245], v[226:229], v[2:17]
	v_mfma_f32_32x32x16_f16 v[18:33], v[230:233], v[226:229], v[18:33]
	ds_read_b128 v[200:203], v162 offset:4640
	ds_read_b128 v[222:225], v162 offset:9248
	ds_read_b128 v[226:229], v162 offset:13856
	ds_read_b128 v[230:233], v163 offset:4640
	s_waitcnt lgkmcnt(4)
	v_mfma_f32_32x32x16_f16 v[98:113], v[246:249], v[238:241], v[98:113]
	s_waitcnt lgkmcnt(0)
	v_mfma_f32_32x32x16_f16 v[114:129], v[230:233], v[238:241], v[114:129]
	v_mfma_f32_32x32x16_f16 v[66:81], v[246:249], v[200:203], v[66:81]
	v_mfma_f32_32x32x16_f16 v[82:97], v[230:233], v[200:203], v[82:97]
	v_mfma_f32_32x32x16_f16 v[34:49], v[246:249], v[222:225], v[34:49]
	v_mfma_f32_32x32x16_f16 v[50:65], v[230:233], v[222:225], v[50:65]
	v_mfma_f32_32x32x16_f16 v[2:17], v[246:249], v[226:229], v[2:17]
	v_mfma_f32_32x32x16_f16 v[18:33], v[230:233], v[226:229], v[18:33]
	ds_read_b128 v[200:203], v162 offset:64
	ds_read_b128 v[222:225], v162 offset:4672
	ds_read_b128 v[226:229], v162 offset:9280
	ds_read_b128 v[230:233], v162 offset:13888
	ds_read_b128 v[234:237], v163 offset:64
	ds_read_b128 v[238:241], v163 offset:4672
	s_waitcnt lgkmcnt(1)
	v_mfma_f32_32x32x16_f16 v[98:113], v[234:237], v[200:203], v[98:113]
	s_waitcnt lgkmcnt(0)
	v_mfma_f32_32x32x16_f16 v[114:129], v[238:241], v[200:203], v[114:129]
	v_mfma_f32_32x32x16_f16 v[66:81], v[234:237], v[222:225], v[66:81]
	v_mfma_f32_32x32x16_f16 v[82:97], v[238:241], v[222:225], v[82:97]
	v_mfma_f32_32x32x16_f16 v[34:49], v[234:237], v[226:229], v[34:49]
	v_mfma_f32_32x32x16_f16 v[50:65], v[238:241], v[226:229], v[50:65]
	v_mfma_f32_32x32x16_f16 v[2:17], v[234:237], v[230:233], v[2:17]
	v_mfma_f32_32x32x16_f16 v[18:33], v[238:241], v[230:233], v[18:33]
	ds_read_b128 v[200:203], v162 offset:96
	ds_read_b128 v[222:225], v162 offset:4704
	ds_read_b128 v[226:229], v162 offset:9312
	ds_read_b128 v[230:233], v162 offset:13920
	ds_read_b128 v[234:237], v163 offset:96
	ds_read_b128 v[238:241], v163 offset:4704
	s_waitcnt lgkmcnt(0)
	s_barrier
	s_waitcnt vmcnt(0)
	ds_write_b128 v219, v[158:161]
	ds_write_b128 v220, v[150:153]
	ds_write_b128 v219, v[154:157] offset:16
	ds_write_b128 v220, v[142:145] offset:16
	ds_write_b128 v219, v[146:149] offset:32
	ds_write_b128 v220, v[134:137] offset:32
	ds_write_b128 v219, v[138:141] offset:48
	ds_write_b128 v220, v[130:133] offset:48
	global_load_dwordx4 v[130:133], v[176:177], off offset:1072
	global_load_dwordx4 v[134:137], v[176:177], off offset:1056
	global_load_dwordx4 v[142:145], v[176:177], off offset:1040
	global_load_dwordx4 v[150:153], v[176:177], off offset:1024
	global_load_dwordx4 v[138:141], v[174:175], off offset:1072
	global_load_dwordx4 v[146:149], v[174:175], off offset:1056
	global_load_dwordx4 v[154:157], v[174:175], off offset:1040
	global_load_dwordx4 v[158:161], v[174:175], off offset:1024
	v_mfma_f32_32x32x16_f16 v[98:113], v[234:237], v[200:203], v[98:113]
	v_mfma_f32_32x32x16_f16 v[114:129], v[238:241], v[200:203], v[114:129]
	v_mfma_f32_32x32x16_f16 v[66:81], v[234:237], v[222:225], v[66:81]
	v_mfma_f32_32x32x16_f16 v[82:97], v[238:241], v[222:225], v[82:97]
	v_mfma_f32_32x32x16_f16 v[34:49], v[234:237], v[226:229], v[34:49]
	v_mfma_f32_32x32x16_f16 v[50:65], v[238:241], v[226:229], v[50:65]
	v_mfma_f32_32x32x16_f16 v[2:17], v[234:237], v[230:233], v[2:17]
	v_mfma_f32_32x32x16_f16 v[18:33], v[238:241], v[230:233], v[18:33]
	ds_read_b128 v[200:203], v218 offset:4608
	ds_read_b128 v[222:225], v218 offset:9216
	ds_read_b128 v[226:229], v218 offset:13824
	ds_read_b128 v[230:233], v217 offset:41472
	ds_read_b128 v[234:237], v218
	ds_read_b128 v[238:241], v218 offset:32
	ds_read_b128 v[242:245], v217 offset:36864
	ds_read_b128 v[246:249], v217 offset:36896
	s_waitcnt lgkmcnt(1)
; DI f16v mfma32(h8v a, h8v b, f16v c) { return __builtin_amdgcn_mfma_f32_32x32x16_f16(a, b, c, 0, 0, 0); }
; template <bool GATHER>
; DI void gemm256_main(const h16* __restrict__ A, int lda, const int* __restrict__ idx, int m0,
;                      const h16* __restrict__ B, int ldb, int n0, int K, h16* lds, f16v (&acc)[4][2]) {
;     ...
;   for (int kt = 0; kt < nk; ++kt) {
;     const h16* As = lds + (kt & 1) * (512 * LDH);
;     const h16* Bs = As + 256 * LDH;
;     h16* Wn = lds + ((kt & 1) ^ 1) * (512 * LDH);
;     if (kt + 1 < nk) {
; #pragma unroll
;       for (int i = 0; i < 4; ++i) { *(u4v*)&Wn[lr * LDH + lc + 8 * i] = ra[i]; *(u4v*)&Wn[(256 + lr) * LDH + lc + 8 * i] = rb[i]; }
;     }
;     if (kt + 2 < nk) {
; #pragma unroll
;       for (int i = 0; i < 4; ++i) { ra[i] = *(const u4v*)(AP_ + 8 * i); rb[i] = *(const u4v*)(BP_ + 8 * i); }
;       ao += 64; bo += 64;
;     }
; #pragma unroll
;     for (int ks = 0; ks < 4; ++ks) {
;       h8v af[4], bf[2];
; #pragma unroll
;       for (int i = 0; i < 4; ++i) af[i] = *(const h8v*)&As[(wm * 128 + i * 32 + (lane & 31)) * LDH + ks * 16 + 8 * (lane >> 5)];
; #pragma unroll
;       for (int j = 0; j < 2; ++j) bf[j] = *(const h8v*)&Bs[(wn * 64 + j * 32 + (lane & 31)) * LDH + ks * 16 + 8 * (lane >> 5)];
; #pragma unroll
;       for (int i = 0; i < 4; ++i)
; #pragma unroll
;         for (int j = 0; j < 2; ++j) acc[i][j] = mfma32(bf[j], af[i], acc[i][j]);
;     }
;     __syncthreads();
;   }
	v_mfma_f32_32x32x16_f16 v[98:113], v[242:245], v[234:237], v[98:113]
	v_mfma_f32_32x32x16_f16 v[114:129], v[230:233], v[234:237], v[114:129]
	v_mfma_f32_32x32x16_f16 v[66:81], v[242:245], v[200:203], v[66:81]
	v_mfma_f32_32x32x16_f16 v[82:97], v[230:233], v[200:203], v[82:97]
	v_mfma_f32_32x32x16_f16 v[34:49], v[242:245], v[222:225], v[34:49]
	v_mfma_f32_32x32x16_f16 v[50:65], v[230:233], v[222:225], v[50:65]
	v_mfma_f32_32x32x16_f16 v[2:17], v[242:245], v[226:229], v[2:17]
	v_mfma_f32_32x32x16_f16 v[18:33], v[230:233], v[226:229], v[18:33]
	ds_read_b128 v[200:203], v218 offset:4640
	ds_read_b128 v[222:225], v218 offset:9248
	ds_read_b128 v[226:229], v218 offset:13856
	ds_read_b128 v[230:233], v217 offset:41504
	s_waitcnt lgkmcnt(4)
	v_mfma_f32_32x32x16_f16 v[98:113], v[246:249], v[238:241], v[98:113]
	s_waitcnt lgkmcnt(0)
	v_mfma_f32_32x32x16_f16 v[114:129], v[230:233], v[238:241], v[114:129]
	v_mfma_f32_32x32x16_f16 v[66:81], v[246:249], v[200:203], v[66:81]
	v_mfma_f32_32x32x16_f16 v[82:97], v[230:233], v[200:203], v[82:97]
	v_mfma_f32_32x32x16_f16 v[34:49], v[246:249], v[222:225], v[34:49]
	v_mfma_f32_32x32x16_f16 v[50:65], v[230:233], v[222:225], v[50:65]
	v_mfma_f32_32x32x16_f16 v[2:17], v[246:249], v[226:229], v[2:17]
	v_mfma_f32_32x32x16_f16 v[18:33], v[230:233], v[226:229], v[18:33]
	ds_read_b128 v[200:203], v218 offset:64
	ds_read_b128 v[222:225], v218 offset:4672
	ds_read_b128 v[226:229], v218 offset:9280
	ds_read_b128 v[230:233], v218 offset:13888
	ds_read_b128 v[234:237], v217 offset:36928
	ds_read_b128 v[238:241], v217 offset:41536
	s_waitcnt lgkmcnt(1)
	v_mfma_f32_32x32x16_f16 v[98:113], v[234:237], v[200:203], v[98:113]
	s_waitcnt lgkmcnt(0)
	v_mfma_f32_32x32x16_f16 v[114:129], v[238:241], v[200:203], v[114:129]
	v_mfma_f32_32x32x16_f16 v[66:81], v[234:237], v[222:225], v[66:81]
	v_mfma_f32_32x32x16_f16 v[82:97], v[238:241], v[222:225], v[82:97]
	v_mfma_f32_32x32x16_f16 v[34:49], v[234:237], v[226:229], v[34:49]
	v_mfma_f32_32x32x16_f16 v[50:65], v[238:241], v[226:229], v[50:65]
	v_mfma_f32_32x32x16_f16 v[2:17], v[234:237], v[230:233], v[2:17]
	v_mfma_f32_32x32x16_f16 v[18:33], v[238:241], v[230:233], v[18:33]
	ds_read_b128 v[200:203], v218 offset:96
	ds_read_b128 v[222:225], v218 offset:4704
	ds_read_b128 v[226:229], v218 offset:9312
	ds_read_b128 v[230:233], v218 offset:13920
	ds_read_b128 v[234:237], v217 offset:36960
	ds_read_b128 v[238:241], v217 offset:41568
	s_waitcnt lgkmcnt(0)
	s_barrier
	s_waitcnt vmcnt(0)
	ds_write_b128 v221, v[158:161]
	ds_write_b128 v221, v[150:153] offset:36864
	ds_write_b128 v221, v[154:157] offset:16
	ds_write_b128 v221, v[142:145] offset:36880
	ds_write_b128 v221, v[146:149] offset:32
	ds_write_b128 v221, v[134:137] offset:36896
	ds_write_b128 v221, v[138:141] offset:48
	ds_write_b128 v221, v[130:133] offset:36912
	global_load_dwordx4 v[130:133], v[176:177], off offset:1200
	global_load_dwordx4 v[134:137], v[176:177], off offset:1184
	global_load_dwordx4 v[142:145], v[176:177], off offset:1168
	global_load_dwordx4 v[150:153], v[176:177], off offset:1152
	global_load_dwordx4 v[138:141], v[174:175], off offset:1200
	global_load_dwordx4 v[146:149], v[174:175], off offset:1184
	global_load_dwordx4 v[154:157], v[174:175], off offset:1168
	global_load_dwordx4 v[158:161], v[174:175], off offset:1152
	v_mfma_f32_32x32x16_f16 v[98:113], v[234:237], v[200:203], v[98:113]
	v_mfma_f32_32x32x16_f16 v[114:129], v[238:241], v[200:203], v[114:129]
	v_mfma_f32_32x32x16_f16 v[66:81], v[234:237], v[222:225], v[66:81]
	v_mfma_f32_32x32x16_f16 v[82:97], v[238:241], v[222:225], v[82:97]
	v_mfma_f32_32x32x16_f16 v[34:49], v[234:237], v[226:229], v[34:49]
	v_mfma_f32_32x32x16_f16 v[50:65], v[238:241], v[226:229], v[50:65]
	v_mfma_f32_32x32x16_f16 v[2:17], v[234:237], v[230:233], v[2:17]
	v_mfma_f32_32x32x16_f16 v[18:33], v[238:241], v[230:233], v[18:33]
	ds_read_b128 v[200:203], v162 offset:4608
	ds_read_b128 v[222:225], v162 offset:9216
	ds_read_b128 v[226:229], v162 offset:13824
	ds_read_b128 v[230:233], v163 offset:4608
	ds_read_b128 v[234:237], v162
	ds_read_b128 v[238:241], v162 offset:32
	ds_read_b128 v[242:245], v163
	ds_read_b128 v[246:249], v163 offset:32
	s_waitcnt lgkmcnt(1)
	v_mfma_f32_32x32x16_f16 v[98:113], v[242:245], v[234:237], v[98:113]
	v_mfma_f32_32x32x16_f16 v[114:129], v[230:233], v[234:237], v[114:129]
	v_mfma_f32_32x32x16_f16 v[66:81], v[242:245], v[200:203], v[66:81]
	v_mfma_f32_32x32x16_f16 v[82:97], v[230:233], v[200:203], v[82:97]
	v_mfma_f32_32x32x16_f16 v[34:49], v[242:245], v[222:225], v[34:49]
	v_mfma_f32_32x32x16_f16 v[50:65], v[230:233], v[222:225], v[50:65]
	v_mfma_f32_32x32x16_f16 v[2:17], v[242:245], v[226:229], v[2:17]
	v_mfma_f32_32x32x16_f16 v[18:33], v[230:233], v[226:229], v[18:33]
	ds_read_b128 v[200:203], v162 offset:4640
	ds_read_b128 v[222:225], v162 offset:9248
	ds_read_b128 v[226:229], v162 offset:13856
	ds_read_b128 v[230:233], v163 offset:4640
	s_waitcnt lgkmcnt(4)
	v_mfma_f32_32x32x16_f16 v[98:113], v[246:249], v[238:241], v[98:113]
	s_waitcnt lgkmcnt(0)
	v_mfma_f32_32x32x16_f16 v[114:129], v[230:233], v[238:241], v[114:129]
	v_mfma_f32_32x32x16_f16 v[66:81], v[246:249], v[200:203], v[66:81]
	v_mfma_f32_32x32x16_f16 v[82:97], v[230:233], v[200:203], v[82:97]
	v_mfma_f32_32x32x16_f16 v[34:49], v[246:249], v[222:225], v[34:49]
	v_mfma_f32_32x32x16_f16 v[50:65], v[230:233], v[222:225], v[50:65]
	v_mfma_f32_32x32x16_f16 v[2:17], v[246:249], v[226:229], v[2:17]
	v_mfma_f32_32x32x16_f16 v[18:33], v[230:233], v[226:229], v[18:33]
	ds_read_b128 v[200:203], v162 offset:64
	ds_read_b128 v[222:225], v162 offset:4672
	ds_read_b128 v[226:229], v162 offset:9280
	ds_read_b128 v[230:233], v162 offset:13888
	ds_read_b128 v[234:237], v163 offset:64
	ds_read_b128 v[238:241], v163 offset:4672
	s_waitcnt lgkmcnt(1)
	v_mfma_f32_32x32x16_f16 v[98:113], v[234:237], v[200:203], v[98:113]
	s_waitcnt lgkmcnt(0)
	v_mfma_f32_32x32x16_f16 v[114:129], v[238:241], v[200:203], v[114:129]
	v_mfma_f32_32x32x16_f16 v[66:81], v[234:237], v[222:225], v[66:81]
	v_mfma_f32_32x32x16_f16 v[82:97], v[238:241], v[222:225], v[82:97]
	v_mfma_f32_32x32x16_f16 v[34:49], v[234:237], v[226:229], v[34:49]
	v_mfma_f32_32x32x16_f16 v[50:65], v[238:241], v[226:229], v[50:65]
	v_mfma_f32_32x32x16_f16 v[2:17], v[234:237], v[230:233], v[2:17]
	v_mfma_f32_32x32x16_f16 v[18:33], v[238:241], v[230:233], v[18:33]
	ds_read_b128 v[200:203], v162 offset:96
	ds_read_b128 v[222:225], v162 offset:4704
	ds_read_b128 v[226:229], v162 offset:9312
	ds_read_b128 v[230:233], v162 offset:13920
	ds_read_b128 v[234:237], v163 offset:96
	ds_read_b128 v[238:241], v163 offset:4704
	s_waitcnt lgkmcnt(0)
	s_barrier
; DI f16v mfma32(h8v a, h8v b, f16v c) { return __builtin_amdgcn_mfma_f32_32x32x16_f16(a, b, c, 0, 0, 0); }
; template <bool GATHER>
; DI void gemm256_main(const h16* __restrict__ A, int lda, const int* __restrict__ idx, int m0,
;                      const h16* __restrict__ B, int ldb, int n0, int K, h16* lds, f16v (&acc)[4][2]) {
;     ...
;   for (int kt = 0; kt < nk; ++kt) {
;     const h16* As = lds + (kt & 1) * (512 * LDH);
;     const h16* Bs = As + 256 * LDH;
;     h16* Wn = lds + ((kt & 1) ^ 1) * (512 * LDH);
;     if (kt + 1 < nk) {
; #pragma unroll
;       for (int i = 0; i < 4; ++i) { *(u4v*)&Wn[lr * LDH + lc + 8 * i] = ra[i]; *(u4v*)&Wn[(256 + lr) * LDH + lc + 8 * i] = rb[i]; }
;     }
;     if (kt + 2 < nk) {
; #pragma unroll
;       for (int i = 0; i < 4; ++i) { ra[i] = *(const u4v*)(AP_ + 8 * i); rb[i] = *(const u4v*)(BP_ + 8 * i); }
;       ao += 64; bo += 64;
;     }
; #pragma unroll
;     for (int ks = 0; ks < 4; ++ks) {
;       h8v af[4], bf[2];
; #pragma unroll
;       for (int i = 0; i < 4; ++i) af[i] = *(const h8v*)&As[(wm * 128 + i * 32 + (lane & 31)) * LDH + ks * 16 + 8 * (lane >> 5)];
; #pragma unroll
;       for (int j = 0; j < 2; ++j) bf[j] = *(const h8v*)&Bs[(wn * 64 + j * 32 + (lane & 31)) * LDH + ks * 16 + 8 * (lane >> 5)];
; #pragma unroll
;       for (int i = 0; i < 4; ++i)
; #pragma unroll
;         for (int j = 0; j < 2; ++j) acc[i][j] = mfma32(bf[j], af[i], acc[i][j]);
;     }
;     __syncthreads();
;   }
	s_waitcnt vmcnt(0)
	ds_write_b128 v219, v[158:161]
	ds_write_b128 v220, v[150:153]
	ds_write_b128 v219, v[154:157] offset:16
	ds_write_b128 v220, v[142:145] offset:16
	ds_write_b128 v219, v[146:149] offset:32
	ds_write_b128 v220, v[134:137] offset:32
	ds_write_b128 v219, v[138:141] offset:48
	ds_write_b128 v220, v[130:133] offset:48
	global_load_dwordx4 v[130:133], v[176:177], off offset:1328
	global_load_dwordx4 v[134:137], v[176:177], off offset:1312
	global_load_dwordx4 v[142:145], v[176:177], off offset:1296
	global_load_dwordx4 v[150:153], v[176:177], off offset:1280
	global_load_dwordx4 v[138:141], v[174:175], off offset:1328
	global_load_dwordx4 v[146:149], v[174:175], off offset:1312
	global_load_dwordx4 v[154:157], v[174:175], off offset:1296
	global_load_dwordx4 v[158:161], v[174:175], off offset:1280
	v_mfma_f32_32x32x16_f16 v[98:113], v[234:237], v[200:203], v[98:113]
	v_mfma_f32_32x32x16_f16 v[114:129], v[238:241], v[200:203], v[114:129]
	v_mfma_f32_32x32x16_f16 v[66:81], v[234:237], v[222:225], v[66:81]
	v_mfma_f32_32x32x16_f16 v[82:97], v[238:241], v[222:225], v[82:97]
	v_mfma_f32_32x32x16_f16 v[34:49], v[234:237], v[226:229], v[34:49]
	v_mfma_f32_32x32x16_f16 v[50:65], v[238:241], v[226:229], v[50:65]
	v_mfma_f32_32x32x16_f16 v[2:17], v[234:237], v[230:233], v[2:17]
	v_mfma_f32_32x32x16_f16 v[18:33], v[238:241], v[230:233], v[18:33]
	ds_read_b128 v[200:203], v218 offset:4608
	ds_read_b128 v[222:225], v218 offset:9216
	ds_read_b128 v[226:229], v218 offset:13824
	ds_read_b128 v[230:233], v217 offset:41472
	ds_read_b128 v[234:237], v218
	ds_read_b128 v[238:241], v218 offset:32
	ds_read_b128 v[242:245], v217 offset:36864
	ds_read_b128 v[246:249], v217 offset:36896
	s_waitcnt lgkmcnt(1)
	v_mfma_f32_32x32x16_f16 v[98:113], v[242:245], v[234:237], v[98:113]
	v_mfma_f32_32x32x16_f16 v[114:129], v[230:233], v[234:237], v[114:129]
	v_mfma_f32_32x32x16_f16 v[66:81], v[242:245], v[200:203], v[66:81]
	v_mfma_f32_32x32x16_f16 v[82:97], v[230:233], v[200:203], v[82:97]
	v_mfma_f32_32x32x16_f16 v[34:49], v[242:245], v[222:225], v[34:49]
	v_mfma_f32_32x32x16_f16 v[50:65], v[230:233], v[222:225], v[50:65]
	v_mfma_f32_32x32x16_f16 v[2:17], v[242:245], v[226:229], v[2:17]
	v_mfma_f32_32x32x16_f16 v[18:33], v[230:233], v[226:229], v[18:33]
	ds_read_b128 v[200:203], v218 offset:4640
	ds_read_b128 v[222:225], v218 offset:9248
	ds_read_b128 v[226:229], v218 offset:13856
	ds_read_b128 v[230:233], v217 offset:41504
	s_waitcnt lgkmcnt(4)
	v_mfma_f32_32x32x16_f16 v[98:113], v[246:249], v[238:241], v[98:113]
	s_waitcnt lgkmcnt(0)
	v_mfma_f32_32x32x16_f16 v[114:129], v[230:233], v[238:241], v[114:129]
	v_mfma_f32_32x32x16_f16 v[66:81], v[246:249], v[200:203], v[66:81]
	v_mfma_f32_32x32x16_f16 v[82:97], v[230:233], v[200:203], v[82:97]
	v_mfma_f32_32x32x16_f16 v[34:49], v[246:249], v[222:225], v[34:49]
	v_mfma_f32_32x32x16_f16 v[50:65], v[230:233], v[222:225], v[50:65]
	v_mfma_f32_32x32x16_f16 v[2:17], v[246:249], v[226:229], v[2:17]
	v_mfma_f32_32x32x16_f16 v[18:33], v[230:233], v[226:229], v[18:33]
	ds_read_b128 v[200:203], v218 offset:64
	ds_read_b128 v[222:225], v218 offset:4672
	ds_read_b128 v[226:229], v218 offset:9280
	ds_read_b128 v[230:233], v218 offset:13888
	ds_read_b128 v[234:237], v217 offset:36928
	ds_read_b128 v[238:241], v217 offset:41536
	s_waitcnt lgkmcnt(1)
	v_mfma_f32_32x32x16_f16 v[98:113], v[234:237], v[200:203], v[98:113]
	s_waitcnt lgkmcnt(0)
	v_mfma_f32_32x32x16_f16 v[114:129], v[238:241], v[200:203], v[114:129]
	v_mfma_f32_32x32x16_f16 v[66:81], v[234:237], v[222:225], v[66:81]
	v_mfma_f32_32x32x16_f16 v[82:97], v[238:241], v[222:225], v[82:97]
	v_mfma_f32_32x32x16_f16 v[34:49], v[234:237], v[226:229], v[34:49]
	v_mfma_f32_32x32x16_f16 v[50:65], v[238:241], v[226:229], v[50:65]
	v_mfma_f32_32x32x16_f16 v[2:17], v[234:237], v[230:233], v[2:17]
	v_mfma_f32_32x32x16_f16 v[18:33], v[238:241], v[230:233], v[18:33]
	ds_read_b128 v[200:203], v218 offset:96
	ds_read_b128 v[222:225], v218 offset:4704
	ds_read_b128 v[226:229], v218 offset:9312
	ds_read_b128 v[230:233], v218 offset:13920
	ds_read_b128 v[234:237], v217 offset:36960
	ds_read_b128 v[238:241], v217 offset:41568
	s_waitcnt lgkmcnt(0)
	s_barrier
	s_waitcnt vmcnt(0)
	ds_write_b128 v221, v[158:161]
	ds_write_b128 v221, v[150:153] offset:36864
	ds_write_b128 v221, v[154:157] offset:16
	ds_write_b128 v221, v[142:145] offset:36880
	ds_write_b128 v221, v[146:149] offset:32
	ds_write_b128 v221, v[134:137] offset:36896
	ds_write_b128 v221, v[138:141] offset:48
	ds_write_b128 v221, v[130:133] offset:36912
	global_load_dwordx4 v[130:133], v[176:177], off offset:1456
	global_load_dwordx4 v[134:137], v[176:177], off offset:1440
	global_load_dwordx4 v[142:145], v[176:177], off offset:1424
	global_load_dwordx4 v[150:153], v[176:177], off offset:1408
	global_load_dwordx4 v[138:141], v[174:175], off offset:1456
	global_load_dwordx4 v[146:149], v[174:175], off offset:1440
	global_load_dwordx4 v[154:157], v[174:175], off offset:1424
	global_load_dwordx4 v[158:161], v[174:175], off offset:1408
	v_mfma_f32_32x32x16_f16 v[98:113], v[234:237], v[200:203], v[98:113]
	v_mfma_f32_32x32x16_f16 v[114:129], v[238:241], v[200:203], v[114:129]
	v_mfma_f32_32x32x16_f16 v[66:81], v[234:237], v[222:225], v[66:81]
	v_mfma_f32_32x32x16_f16 v[82:97], v[238:241], v[222:225], v[82:97]
	v_mfma_f32_32x32x16_f16 v[34:49], v[234:237], v[226:229], v[34:49]
	v_mfma_f32_32x32x16_f16 v[50:65], v[238:241], v[226:229], v[50:65]
	v_mfma_f32_32x32x16_f16 v[2:17], v[234:237], v[230:233], v[2:17]
	v_mfma_f32_32x32x16_f16 v[18:33], v[238:241], v[230:233], v[18:33]
	ds_read_b128 v[200:203], v162 offset:4608
	ds_read_b128 v[222:225], v162 offset:9216
	ds_read_b128 v[226:229], v162 offset:13824
	ds_read_b128 v[230:233], v163 offset:4608
	ds_read_b128 v[234:237], v162
	ds_read_b128 v[238:241], v162 offset:32
	ds_read_b128 v[242:245], v163
	ds_read_b128 v[246:249], v163 offset:32
	s_waitcnt lgkmcnt(1)
; DI f16v mfma32(h8v a, h8v b, f16v c) { return __builtin_amdgcn_mfma_f32_32x32x16_f16(a, b, c, 0, 0, 0); }
; template <bool GATHER>
; DI void gemm256_main(const h16* __restrict__ A, int lda, const int* __restrict__ idx, int m0,
;                      const h16* __restrict__ B, int ldb, int n0, int K, h16* lds, f16v (&acc)[4][2]) {
;     ...
;   for (int kt = 0; kt < nk; ++kt) {
;     const h16* As = lds + (kt & 1) * (512 * LDH);
;     const h16* Bs = As + 256 * LDH;
;     h16* Wn = lds + ((kt & 1) ^ 1) * (512 * LDH);
;     if (kt + 1 < nk) {
; #pragma unroll
;       for (int i = 0; i < 4; ++i) { *(u4v*)&Wn[lr * LDH + lc + 8 * i] = ra[i]; *(u4v*)&Wn[(256 + lr) * LDH + lc + 8 * i] = rb[i]; }
;     }
;     if (kt + 2 < nk) {
; #pragma unroll
;       for (int i = 0; i < 4; ++i) { ra[i] = *(const u4v*)(AP_ + 8 * i); rb[i] = *(const u4v*)(BP_ + 8 * i); }
;       ao += 64; bo += 64;
;     }
; #pragma unroll
;     for (int ks = 0; ks < 4; ++ks) {
;       h8v af[4], bf[2];
; #pragma unroll
;       for (int i = 0; i < 4; ++i) af[i] = *(const h8v*)&As[(wm * 128 + i * 32 + (lane & 31)) * LDH + ks * 16 + 8 * (lane >> 5)];
; #pragma unroll
;       for (int j = 0; j < 2; ++j) bf[j] = *(const h8v*)&Bs[(wn * 64 + j * 32 + (lane & 31)) * LDH + ks * 16 + 8 * (lane >> 5)];
; #pragma unroll
;       for (int i = 0; i < 4; ++i)
; #pragma unroll
;         for (int j = 0; j < 2; ++j) acc[i][j] = mfma32(bf[j], af[i], acc[i][j]);
;     }
;     __syncthreads();
;   }
	v_mfma_f32_32x32x16_f16 v[98:113], v[242:245], v[234:237], v[98:113]
	v_mfma_f32_32x32x16_f16 v[114:129], v[230:233], v[234:237], v[114:129]
	v_mfma_f32_32x32x16_f16 v[66:81], v[242:245], v[200:203], v[66:81]
	v_mfma_f32_32x32x16_f16 v[82:97], v[230:233], v[200:203], v[82:97]
	v_mfma_f32_32x32x16_f16 v[34:49], v[242:245], v[222:225], v[34:49]
	v_mfma_f32_32x32x16_f16 v[50:65], v[230:233], v[222:225], v[50:65]
	v_mfma_f32_32x32x16_f16 v[2:17], v[242:245], v[226:229], v[2:17]
	v_mfma_f32_32x32x16_f16 v[18:33], v[230:233], v[226:229], v[18:33]
	ds_read_b128 v[200:203], v162 offset:4640
	ds_read_b128 v[222:225], v162 offset:9248
	ds_read_b128 v[226:229], v162 offset:13856
	ds_read_b128 v[230:233], v163 offset:4640
	s_waitcnt lgkmcnt(4)
	v_mfma_f32_32x32x16_f16 v[98:113], v[246:249], v[238:241], v[98:113]
	s_waitcnt lgkmcnt(0)
	v_mfma_f32_32x32x16_f16 v[114:129], v[230:233], v[238:241], v[114:129]
	v_mfma_f32_32x32x16_f16 v[66:81], v[246:249], v[200:203], v[66:81]
	v_mfma_f32_32x32x16_f16 v[82:97], v[230:233], v[200:203], v[82:97]
	v_mfma_f32_32x32x16_f16 v[34:49], v[246:249], v[222:225], v[34:49]
	v_mfma_f32_32x32x16_f16 v[50:65], v[230:233], v[222:225], v[50:65]
	v_mfma_f32_32x32x16_f16 v[2:17], v[246:249], v[226:229], v[2:17]
	v_mfma_f32_32x32x16_f16 v[18:33], v[230:233], v[226:229], v[18:33]
	ds_read_b128 v[200:203], v162 offset:64
	ds_read_b128 v[222:225], v162 offset:4672
	ds_read_b128 v[226:229], v162 offset:9280
	ds_read_b128 v[230:233], v162 offset:13888
	ds_read_b128 v[234:237], v163 offset:64
	ds_read_b128 v[238:241], v163 offset:4672
	s_waitcnt lgkmcnt(1)
	v_mfma_f32_32x32x16_f16 v[98:113], v[234:237], v[200:203], v[98:113]
	s_waitcnt lgkmcnt(0)
	v_mfma_f32_32x32x16_f16 v[114:129], v[238:241], v[200:203], v[114:129]
	v_mfma_f32_32x32x16_f16 v[66:81], v[234:237], v[222:225], v[66:81]
	v_mfma_f32_32x32x16_f16 v[82:97], v[238:241], v[222:225], v[82:97]
	v_mfma_f32_32x32x16_f16 v[34:49], v[234:237], v[226:229], v[34:49]
	v_mfma_f32_32x32x16_f16 v[50:65], v[238:241], v[226:229], v[50:65]
	v_mfma_f32_32x32x16_f16 v[2:17], v[234:237], v[230:233], v[2:17]
	v_mfma_f32_32x32x16_f16 v[18:33], v[238:241], v[230:233], v[18:33]
	ds_read_b128 v[200:203], v162 offset:96
	ds_read_b128 v[222:225], v162 offset:4704
	ds_read_b128 v[226:229], v162 offset:9312
	ds_read_b128 v[230:233], v162 offset:13920
	ds_read_b128 v[234:237], v163 offset:96
	ds_read_b128 v[238:241], v163 offset:4704
	s_waitcnt lgkmcnt(0)
	s_barrier
	s_waitcnt vmcnt(0)
	ds_write_b128 v219, v[158:161]
	ds_write_b128 v220, v[150:153]
	ds_write_b128 v219, v[154:157] offset:16
	ds_write_b128 v220, v[142:145] offset:16
	ds_write_b128 v219, v[146:149] offset:32
	ds_write_b128 v220, v[134:137] offset:32
	ds_write_b128 v219, v[138:141] offset:48
	ds_write_b128 v220, v[130:133] offset:48
	global_load_dwordx4 v[130:133], v[176:177], off offset:1584
	global_load_dwordx4 v[134:137], v[176:177], off offset:1568
	global_load_dwordx4 v[142:145], v[176:177], off offset:1552
	global_load_dwordx4 v[150:153], v[176:177], off offset:1536
	global_load_dwordx4 v[138:141], v[174:175], off offset:1584
	global_load_dwordx4 v[146:149], v[174:175], off offset:1568
	global_load_dwordx4 v[154:157], v[174:175], off offset:1552
	global_load_dwordx4 v[158:161], v[174:175], off offset:1536
	v_mfma_f32_32x32x16_f16 v[98:113], v[234:237], v[200:203], v[98:113]
	v_mfma_f32_32x32x16_f16 v[114:129], v[238:241], v[200:203], v[114:129]
	v_mfma_f32_32x32x16_f16 v[66:81], v[234:237], v[222:225], v[66:81]
	v_mfma_f32_32x32x16_f16 v[82:97], v[238:241], v[222:225], v[82:97]
	v_mfma_f32_32x32x16_f16 v[34:49], v[234:237], v[226:229], v[34:49]
	v_mfma_f32_32x32x16_f16 v[50:65], v[238:241], v[226:229], v[50:65]
	v_mfma_f32_32x32x16_f16 v[2:17], v[234:237], v[230:233], v[2:17]
	v_mfma_f32_32x32x16_f16 v[18:33], v[238:241], v[230:233], v[18:33]
	ds_read_b128 v[200:203], v218 offset:4608
	ds_read_b128 v[222:225], v218 offset:9216
	ds_read_b128 v[226:229], v218 offset:13824
	ds_read_b128 v[230:233], v217 offset:41472
	ds_read_b128 v[234:237], v218
	ds_read_b128 v[238:241], v218 offset:32
	ds_read_b128 v[242:245], v217 offset:36864
	ds_read_b128 v[246:249], v217 offset:36896
	s_waitcnt lgkmcnt(1)
	v_mfma_f32_32x32x16_f16 v[98:113], v[242:245], v[234:237], v[98:113]
	v_mfma_f32_32x32x16_f16 v[114:129], v[230:233], v[234:237], v[114:129]
	v_mfma_f32_32x32x16_f16 v[66:81], v[242:245], v[200:203], v[66:81]
	v_mfma_f32_32x32x16_f16 v[82:97], v[230:233], v[200:203], v[82:97]
	v_mfma_f32_32x32x16_f16 v[34:49], v[242:245], v[222:225], v[34:49]
	v_mfma_f32_32x32x16_f16 v[50:65], v[230:233], v[222:225], v[50:65]
	v_mfma_f32_32x32x16_f16 v[2:17], v[242:245], v[226:229], v[2:17]
	v_mfma_f32_32x32x16_f16 v[18:33], v[230:233], v[226:229], v[18:33]
	ds_read_b128 v[200:203], v218 offset:4640
	ds_read_b128 v[222:225], v218 offset:9248
	ds_read_b128 v[226:229], v218 offset:13856
	ds_read_b128 v[230:233], v217 offset:41504
	s_waitcnt lgkmcnt(4)
	v_mfma_f32_32x32x16_f16 v[98:113], v[246:249], v[238:241], v[98:113]
	s_waitcnt lgkmcnt(0)
	v_mfma_f32_32x32x16_f16 v[114:129], v[230:233], v[238:241], v[114:129]
	v_mfma_f32_32x32x16_f16 v[66:81], v[246:249], v[200:203], v[66:81]
	v_mfma_f32_32x32x16_f16 v[82:97], v[230:233], v[200:203], v[82:97]
	v_mfma_f32_32x32x16_f16 v[34:49], v[246:249], v[222:225], v[34:49]
	v_mfma_f32_32x32x16_f16 v[50:65], v[230:233], v[222:225], v[50:65]
	v_mfma_f32_32x32x16_f16 v[2:17], v[246:249], v[226:229], v[2:17]
	v_mfma_f32_32x32x16_f16 v[18:33], v[230:233], v[226:229], v[18:33]
	ds_read_b128 v[200:203], v218 offset:64
	ds_read_b128 v[222:225], v218 offset:4672
	ds_read_b128 v[226:229], v218 offset:9280
	ds_read_b128 v[230:233], v218 offset:13888
	ds_read_b128 v[234:237], v217 offset:36928
	ds_read_b128 v[238:241], v217 offset:41536
	s_waitcnt lgkmcnt(1)
	v_mfma_f32_32x32x16_f16 v[98:113], v[234:237], v[200:203], v[98:113]
	s_waitcnt lgkmcnt(0)
	v_mfma_f32_32x32x16_f16 v[114:129], v[238:241], v[200:203], v[114:129]
	v_mfma_f32_32x32x16_f16 v[66:81], v[234:237], v[222:225], v[66:81]
	v_mfma_f32_32x32x16_f16 v[82:97], v[238:241], v[222:225], v[82:97]
	v_mfma_f32_32x32x16_f16 v[34:49], v[234:237], v[226:229], v[34:49]
	v_mfma_f32_32x32x16_f16 v[50:65], v[238:241], v[226:229], v[50:65]
	v_mfma_f32_32x32x16_f16 v[2:17], v[234:237], v[230:233], v[2:17]
	v_mfma_f32_32x32x16_f16 v[18:33], v[238:241], v[230:233], v[18:33]
	ds_read_b128 v[200:203], v218 offset:96
	ds_read_b128 v[222:225], v218 offset:4704
	ds_read_b128 v[226:229], v218 offset:9312
	ds_read_b128 v[230:233], v218 offset:13920
	ds_read_b128 v[234:237], v217 offset:36960
	ds_read_b128 v[238:241], v217 offset:41568
	s_waitcnt lgkmcnt(0)
	s_barrier
; DI f16v mfma32(h8v a, h8v b, f16v c) { return __builtin_amdgcn_mfma_f32_32x32x16_f16(a, b, c, 0, 0, 0); }
; template <bool GATHER>
; DI void gemm256_main(const h16* __restrict__ A, int lda, const int* __restrict__ idx, int m0,
;                      const h16* __restrict__ B, int ldb, int n0, int K, h16* lds, f16v (&acc)[4][2]) {
;     ...
;   for (int kt = 0; kt < nk; ++kt) {
;     const h16* As = lds + (kt & 1) * (512 * LDH);
;     const h16* Bs = As + 256 * LDH;
;     h16* Wn = lds + ((kt & 1) ^ 1) * (512 * LDH);
;     if (kt + 1 < nk) {
; #pragma unroll
;       for (int i = 0; i < 4; ++i) { *(u4v*)&Wn[lr * LDH + lc + 8 * i] = ra[i]; *(u4v*)&Wn[(256 + lr) * LDH + lc + 8 * i] = rb[i]; }
;     }
;     if (kt + 2 < nk) {
; #pragma unroll
;       for (int i = 0; i < 4; ++i) { ra[i] = *(const u4v*)(AP_ + 8 * i); rb[i] = *(const u4v*)(BP_ + 8 * i); }
;       ao += 64; bo += 64;
;     }
; #pragma unroll
;     for (int ks = 0; ks < 4; ++ks) {
;       h8v af[4], bf[2];
; #pragma unroll
;       for (int i = 0; i < 4; ++i) af[i] = *(const h8v*)&As[(wm * 128 + i * 32 + (lane & 31)) * LDH + ks * 16 + 8 * (lane >> 5)];
; #pragma unroll
;       for (int j = 0; j < 2; ++j) bf[j] = *(const h8v*)&Bs[(wn * 64 + j * 32 + (lane & 31)) * LDH + ks * 16 + 8 * (lane >> 5)];
; #pragma unroll
;       for (int i = 0; i < 4; ++i)
; #pragma unroll
;         for (int j = 0; j < 2; ++j) acc[i][j] = mfma32(bf[j], af[i], acc[i][j]);
;     }
;     __syncthreads();
;   }
	s_waitcnt vmcnt(0)
	ds_write_b128 v221, v[158:161]
	ds_write_b128 v221, v[150:153] offset:36864
	ds_write_b128 v221, v[154:157] offset:16
	ds_write_b128 v221, v[142:145] offset:36880
	ds_write_b128 v221, v[146:149] offset:32
	ds_write_b128 v221, v[134:137] offset:36896
	ds_write_b128 v221, v[138:141] offset:48
	ds_write_b128 v221, v[130:133] offset:36912
	global_load_dwordx4 v[130:133], v[176:177], off offset:1712
	global_load_dwordx4 v[134:137], v[176:177], off offset:1696
	global_load_dwordx4 v[142:145], v[176:177], off offset:1680
	global_load_dwordx4 v[150:153], v[176:177], off offset:1664
	global_load_dwordx4 v[138:141], v[174:175], off offset:1712
	global_load_dwordx4 v[146:149], v[174:175], off offset:1696
	global_load_dwordx4 v[154:157], v[174:175], off offset:1680
	global_load_dwordx4 v[158:161], v[174:175], off offset:1664
	v_mfma_f32_32x32x16_f16 v[98:113], v[234:237], v[200:203], v[98:113]
	v_mfma_f32_32x32x16_f16 v[114:129], v[238:241], v[200:203], v[114:129]
	v_mfma_f32_32x32x16_f16 v[66:81], v[234:237], v[222:225], v[66:81]
	v_mfma_f32_32x32x16_f16 v[82:97], v[238:241], v[222:225], v[82:97]
	v_mfma_f32_32x32x16_f16 v[34:49], v[234:237], v[226:229], v[34:49]
	v_mfma_f32_32x32x16_f16 v[50:65], v[238:241], v[226:229], v[50:65]
	v_mfma_f32_32x32x16_f16 v[2:17], v[234:237], v[230:233], v[2:17]
	v_mfma_f32_32x32x16_f16 v[18:33], v[238:241], v[230:233], v[18:33]
	ds_read_b128 v[200:203], v162 offset:4608
	ds_read_b128 v[222:225], v162 offset:9216
	ds_read_b128 v[226:229], v162 offset:13824
	ds_read_b128 v[230:233], v163 offset:4608
	ds_read_b128 v[234:237], v162
	ds_read_b128 v[238:241], v162 offset:32
	ds_read_b128 v[242:245], v163
	ds_read_b128 v[246:249], v163 offset:32
	s_waitcnt lgkmcnt(1)
	v_mfma_f32_32x32x16_f16 v[98:113], v[242:245], v[234:237], v[98:113]
	v_mfma_f32_32x32x16_f16 v[114:129], v[230:233], v[234:237], v[114:129]
	v_mfma_f32_32x32x16_f16 v[66:81], v[242:245], v[200:203], v[66:81]
	v_mfma_f32_32x32x16_f16 v[82:97], v[230:233], v[200:203], v[82:97]
	v_mfma_f32_32x32x16_f16 v[34:49], v[242:245], v[222:225], v[34:49]
	v_mfma_f32_32x32x16_f16 v[50:65], v[230:233], v[222:225], v[50:65]
	v_mfma_f32_32x32x16_f16 v[2:17], v[242:245], v[226:229], v[2:17]
	v_mfma_f32_32x32x16_f16 v[18:33], v[230:233], v[226:229], v[18:33]
	ds_read_b128 v[200:203], v162 offset:4640
	ds_read_b128 v[222:225], v162 offset:9248
	ds_read_b128 v[226:229], v162 offset:13856
	ds_read_b128 v[230:233], v163 offset:4640
	s_waitcnt lgkmcnt(4)
	v_mfma_f32_32x32x16_f16 v[98:113], v[246:249], v[238:241], v[98:113]
	s_waitcnt lgkmcnt(0)
	v_mfma_f32_32x32x16_f16 v[114:129], v[230:233], v[238:241], v[114:129]
	v_mfma_f32_32x32x16_f16 v[66:81], v[246:249], v[200:203], v[66:81]
	v_mfma_f32_32x32x16_f16 v[82:97], v[230:233], v[200:203], v[82:97]
	v_mfma_f32_32x32x16_f16 v[34:49], v[246:249], v[222:225], v[34:49]
	v_mfma_f32_32x32x16_f16 v[50:65], v[230:233], v[222:225], v[50:65]
	v_mfma_f32_32x32x16_f16 v[2:17], v[246:249], v[226:229], v[2:17]
	v_mfma_f32_32x32x16_f16 v[18:33], v[230:233], v[226:229], v[18:33]
	ds_read_b128 v[200:203], v162 offset:64
	ds_read_b128 v[222:225], v162 offset:4672
	ds_read_b128 v[226:229], v162 offset:9280
	ds_read_b128 v[230:233], v162 offset:13888
	ds_read_b128 v[234:237], v163 offset:64
	ds_read_b128 v[238:241], v163 offset:4672
	s_waitcnt lgkmcnt(1)
	v_mfma_f32_32x32x16_f16 v[98:113], v[234:237], v[200:203], v[98:113]
	s_waitcnt lgkmcnt(0)
	v_mfma_f32_32x32x16_f16 v[114:129], v[238:241], v[200:203], v[114:129]
	v_mfma_f32_32x32x16_f16 v[66:81], v[234:237], v[222:225], v[66:81]
	v_mfma_f32_32x32x16_f16 v[82:97], v[238:241], v[222:225], v[82:97]
	v_mfma_f32_32x32x16_f16 v[34:49], v[234:237], v[226:229], v[34:49]
	v_mfma_f32_32x32x16_f16 v[50:65], v[238:241], v[226:229], v[50:65]
	v_mfma_f32_32x32x16_f16 v[2:17], v[234:237], v[230:233], v[2:17]
	v_mfma_f32_32x32x16_f16 v[18:33], v[238:241], v[230:233], v[18:33]
	ds_read_b128 v[200:203], v162 offset:96
	ds_read_b128 v[222:225], v162 offset:4704
	ds_read_b128 v[226:229], v162 offset:9312
	ds_read_b128 v[230:233], v162 offset:13920
	ds_read_b128 v[234:237], v163 offset:96
	ds_read_b128 v[238:241], v163 offset:4704
	s_waitcnt lgkmcnt(0)
	s_barrier
	s_waitcnt vmcnt(0)
	ds_write_b128 v219, v[158:161]
	ds_write_b128 v220, v[150:153]
	ds_write_b128 v219, v[154:157] offset:16
	ds_write_b128 v220, v[142:145] offset:16
	ds_write_b128 v219, v[146:149] offset:32
	ds_write_b128 v220, v[134:137] offset:32
	ds_write_b128 v219, v[138:141] offset:48
	ds_write_b128 v220, v[130:133] offset:48
	global_load_dwordx4 v[130:133], v[176:177], off offset:1840
	global_load_dwordx4 v[134:137], v[176:177], off offset:1824
	global_load_dwordx4 v[142:145], v[176:177], off offset:1808
	global_load_dwordx4 v[150:153], v[176:177], off offset:1792
	global_load_dwordx4 v[138:141], v[174:175], off offset:1840
	global_load_dwordx4 v[146:149], v[174:175], off offset:1824
	global_load_dwordx4 v[154:157], v[174:175], off offset:1808
	global_load_dwordx4 v[158:161], v[174:175], off offset:1792
	v_mfma_f32_32x32x16_f16 v[98:113], v[234:237], v[200:203], v[98:113]
	v_mfma_f32_32x32x16_f16 v[114:129], v[238:241], v[200:203], v[114:129]
	v_mfma_f32_32x32x16_f16 v[66:81], v[234:237], v[222:225], v[66:81]
	v_mfma_f32_32x32x16_f16 v[82:97], v[238:241], v[222:225], v[82:97]
	v_mfma_f32_32x32x16_f16 v[34:49], v[234:237], v[226:229], v[34:49]
	v_mfma_f32_32x32x16_f16 v[50:65], v[238:241], v[226:229], v[50:65]
	v_mfma_f32_32x32x16_f16 v[2:17], v[234:237], v[230:233], v[2:17]
	v_mfma_f32_32x32x16_f16 v[18:33], v[238:241], v[230:233], v[18:33]
	ds_read_b128 v[200:203], v218 offset:4608
	ds_read_b128 v[222:225], v218 offset:9216
	ds_read_b128 v[226:229], v218 offset:13824
	ds_read_b128 v[230:233], v217 offset:41472
	ds_read_b128 v[234:237], v218
	ds_read_b128 v[238:241], v218 offset:32
	ds_read_b128 v[242:245], v217 offset:36864
	ds_read_b128 v[246:249], v217 offset:36896
	s_waitcnt lgkmcnt(1)
; DI f16v mfma32(h8v a, h8v b, f16v c) { return __builtin_amdgcn_mfma_f32_32x32x16_f16(a, b, c, 0, 0, 0); }
; template <bool GATHER>
; DI void gemm256_main(const h16* __restrict__ A, int lda, const int* __restrict__ idx, int m0,
;                      const h16* __restrict__ B, int ldb, int n0, int K, h16* lds, f16v (&acc)[4][2]) {
;     ...
;   for (int kt = 0; kt < nk; ++kt) {
;     const h16* As = lds + (kt & 1) * (512 * LDH);
;     const h16* Bs = As + 256 * LDH;
;     h16* Wn = lds + ((kt & 1) ^ 1) * (512 * LDH);
;     if (kt + 1 < nk) {
; #pragma unroll
;       for (int i = 0; i < 4; ++i) { *(u4v*)&Wn[lr * LDH + lc + 8 * i] = ra[i]; *(u4v*)&Wn[(256 + lr) * LDH + lc + 8 * i] = rb[i]; }
;     }
;     if (kt + 2 < nk) {
; #pragma unroll
;       for (int i = 0; i < 4; ++i) { ra[i] = *(const u4v*)(AP_ + 8 * i); rb[i] = *(const u4v*)(BP_ + 8 * i); }
;       ao += 64; bo += 64;
;     }
; #pragma unroll
;     for (int ks = 0; ks < 4; ++ks) {
;       h8v af[4], bf[2];
; #pragma unroll
;       for (int i = 0; i < 4; ++i) af[i] = *(const h8v*)&As[(wm * 128 + i * 32 + (lane & 31)) * LDH + ks * 16 + 8 * (lane >> 5)];
; #pragma unroll
;       for (int j = 0; j < 2; ++j) bf[j] = *(const h8v*)&Bs[(wn * 64 + j * 32 + (lane & 31)) * LDH + ks * 16 + 8 * (lane >> 5)];
; #pragma unroll
;       for (int i = 0; i < 4; ++i)
; #pragma unroll
;         for (int j = 0; j < 2; ++j) acc[i][j] = mfma32(bf[j], af[i], acc[i][j]);
;     }
;     __syncthreads();
;   }
	v_mfma_f32_32x32x16_f16 v[98:113], v[242:245], v[234:237], v[98:113]
	v_mfma_f32_32x32x16_f16 v[114:129], v[230:233], v[234:237], v[114:129]
	v_mfma_f32_32x32x16_f16 v[66:81], v[242:245], v[200:203], v[66:81]
	v_mfma_f32_32x32x16_f16 v[82:97], v[230:233], v[200:203], v[82:97]
	v_mfma_f32_32x32x16_f16 v[34:49], v[242:245], v[222:225], v[34:49]
	v_mfma_f32_32x32x16_f16 v[50:65], v[230:233], v[222:225], v[50:65]
	v_mfma_f32_32x32x16_f16 v[2:17], v[242:245], v[226:229], v[2:17]
	v_mfma_f32_32x32x16_f16 v[18:33], v[230:233], v[226:229], v[18:33]
	ds_read_b128 v[200:203], v218 offset:4640
	ds_read_b128 v[222:225], v218 offset:9248
	ds_read_b128 v[226:229], v218 offset:13856
	ds_read_b128 v[230:233], v217 offset:41504
	s_waitcnt lgkmcnt(4)
	v_mfma_f32_32x32x16_f16 v[98:113], v[246:249], v[238:241], v[98:113]
	s_waitcnt lgkmcnt(0)
	v_mfma_f32_32x32x16_f16 v[114:129], v[230:233], v[238:241], v[114:129]
	v_mfma_f32_32x32x16_f16 v[66:81], v[246:249], v[200:203], v[66:81]
	v_mfma_f32_32x32x16_f16 v[82:97], v[230:233], v[200:203], v[82:97]
	v_mfma_f32_32x32x16_f16 v[34:49], v[246:249], v[222:225], v[34:49]
	v_mfma_f32_32x32x16_f16 v[50:65], v[230:233], v[222:225], v[50:65]
	v_mfma_f32_32x32x16_f16 v[2:17], v[246:249], v[226:229], v[2:17]
	v_mfma_f32_32x32x16_f16 v[18:33], v[230:233], v[226:229], v[18:33]
	ds_read_b128 v[200:203], v218 offset:64
	ds_read_b128 v[222:225], v218 offset:4672
	ds_read_b128 v[226:229], v218 offset:9280
	ds_read_b128 v[230:233], v218 offset:13888
	ds_read_b128 v[234:237], v217 offset:36928
	ds_read_b128 v[238:241], v217 offset:41536
	s_waitcnt lgkmcnt(1)
	v_mfma_f32_32x32x16_f16 v[98:113], v[234:237], v[200:203], v[98:113]
	s_waitcnt lgkmcnt(0)
	v_mfma_f32_32x32x16_f16 v[114:129], v[238:241], v[200:203], v[114:129]
	v_mfma_f32_32x32x16_f16 v[66:81], v[234:237], v[222:225], v[66:81]
	v_mfma_f32_32x32x16_f16 v[82:97], v[238:241], v[222:225], v[82:97]
	v_mfma_f32_32x32x16_f16 v[34:49], v[234:237], v[226:229], v[34:49]
	v_mfma_f32_32x32x16_f16 v[50:65], v[238:241], v[226:229], v[50:65]
	v_mfma_f32_32x32x16_f16 v[2:17], v[234:237], v[230:233], v[2:17]
	v_mfma_f32_32x32x16_f16 v[18:33], v[238:241], v[230:233], v[18:33]
	ds_read_b128 v[200:203], v218 offset:96
	ds_read_b128 v[222:225], v218 offset:4704
	ds_read_b128 v[226:229], v218 offset:9312
	ds_read_b128 v[230:233], v218 offset:13920
	ds_read_b128 v[234:237], v217 offset:36960
	ds_read_b128 v[238:241], v217 offset:41568
	s_waitcnt lgkmcnt(0)
	s_barrier
	s_waitcnt vmcnt(0)
	ds_write_b128 v221, v[158:161]
	ds_write_b128 v221, v[150:153] offset:36864
	ds_write_b128 v221, v[154:157] offset:16
	ds_write_b128 v221, v[142:145] offset:36880
	ds_write_b128 v221, v[146:149] offset:32
	ds_write_b128 v221, v[134:137] offset:36896
	ds_write_b128 v221, v[138:141] offset:48
	ds_write_b128 v221, v[130:133] offset:36912
	global_load_dwordx4 v[130:133], v[176:177], off offset:1968
	global_load_dwordx4 v[134:137], v[176:177], off offset:1952
	global_load_dwordx4 v[142:145], v[176:177], off offset:1936
	global_load_dwordx4 v[150:153], v[176:177], off offset:1920
	global_load_dwordx4 v[138:141], v[174:175], off offset:1968
	global_load_dwordx4 v[146:149], v[174:175], off offset:1952
	global_load_dwordx4 v[154:157], v[174:175], off offset:1936
	global_load_dwordx4 v[158:161], v[174:175], off offset:1920
	v_mfma_f32_32x32x16_f16 v[98:113], v[234:237], v[200:203], v[98:113]
	v_mfma_f32_32x32x16_f16 v[114:129], v[238:241], v[200:203], v[114:129]
	v_mfma_f32_32x32x16_f16 v[66:81], v[234:237], v[222:225], v[66:81]
	v_mfma_f32_32x32x16_f16 v[82:97], v[238:241], v[222:225], v[82:97]
	v_mfma_f32_32x32x16_f16 v[34:49], v[234:237], v[226:229], v[34:49]
	v_mfma_f32_32x32x16_f16 v[50:65], v[238:241], v[226:229], v[50:65]
	v_mfma_f32_32x32x16_f16 v[2:17], v[234:237], v[230:233], v[2:17]
	v_mfma_f32_32x32x16_f16 v[18:33], v[238:241], v[230:233], v[18:33]
	ds_read_b128 v[174:177], v162 offset:4608
	ds_read_b128 v[200:203], v162 offset:9216
	ds_read_b128 v[222:225], v162 offset:13824
	ds_read_b128 v[226:229], v163 offset:4608
	ds_read_b128 v[230:233], v162
	ds_read_b128 v[234:237], v162 offset:32
	ds_read_b128 v[238:241], v163
	ds_read_b128 v[242:245], v163 offset:32
	s_waitcnt lgkmcnt(1)
	v_mfma_f32_32x32x16_f16 v[98:113], v[238:241], v[230:233], v[98:113]
	v_mfma_f32_32x32x16_f16 v[114:129], v[226:229], v[230:233], v[114:129]
	v_mfma_f32_32x32x16_f16 v[66:81], v[238:241], v[174:177], v[66:81]
	v_mfma_f32_32x32x16_f16 v[82:97], v[226:229], v[174:177], v[82:97]
	v_mfma_f32_32x32x16_f16 v[34:49], v[238:241], v[200:203], v[34:49]
	v_mfma_f32_32x32x16_f16 v[50:65], v[226:229], v[200:203], v[50:65]
	v_mfma_f32_32x32x16_f16 v[2:17], v[238:241], v[222:225], v[2:17]
	v_mfma_f32_32x32x16_f16 v[18:33], v[226:229], v[222:225], v[18:33]
	ds_read_b128 v[174:177], v162 offset:4640
	ds_read_b128 v[200:203], v162 offset:9248
	ds_read_b128 v[222:225], v162 offset:13856
	ds_read_b128 v[226:229], v163 offset:4640
	s_waitcnt lgkmcnt(4)
	v_mfma_f32_32x32x16_f16 v[98:113], v[242:245], v[234:237], v[98:113]
	s_waitcnt lgkmcnt(0)
	v_mfma_f32_32x32x16_f16 v[114:129], v[226:229], v[234:237], v[114:129]
	v_mfma_f32_32x32x16_f16 v[66:81], v[242:245], v[174:177], v[66:81]
	v_mfma_f32_32x32x16_f16 v[82:97], v[226:229], v[174:177], v[82:97]
	v_mfma_f32_32x32x16_f16 v[34:49], v[242:245], v[200:203], v[34:49]
	v_mfma_f32_32x32x16_f16 v[50:65], v[226:229], v[200:203], v[50:65]
	v_mfma_f32_32x32x16_f16 v[2:17], v[242:245], v[222:225], v[2:17]
	v_mfma_f32_32x32x16_f16 v[18:33], v[226:229], v[222:225], v[18:33]
	ds_read_b128 v[174:177], v162 offset:64
	ds_read_b128 v[200:203], v162 offset:4672
	ds_read_b128 v[222:225], v162 offset:9280
	ds_read_b128 v[226:229], v162 offset:13888
	ds_read_b128 v[230:233], v163 offset:64
	ds_read_b128 v[234:237], v163 offset:4672
	s_waitcnt lgkmcnt(1)
	v_mfma_f32_32x32x16_f16 v[98:113], v[230:233], v[174:177], v[98:113]
	s_waitcnt lgkmcnt(0)
	v_mfma_f32_32x32x16_f16 v[114:129], v[234:237], v[174:177], v[114:129]
	v_mfma_f32_32x32x16_f16 v[66:81], v[230:233], v[200:203], v[66:81]
	v_mfma_f32_32x32x16_f16 v[82:97], v[234:237], v[200:203], v[82:97]
	v_mfma_f32_32x32x16_f16 v[34:49], v[230:233], v[222:225], v[34:49]
	v_mfma_f32_32x32x16_f16 v[50:65], v[234:237], v[222:225], v[50:65]
	v_mfma_f32_32x32x16_f16 v[2:17], v[230:233], v[226:229], v[2:17]
	v_mfma_f32_32x32x16_f16 v[18:33], v[234:237], v[226:229], v[18:33]
	ds_read_b128 v[174:177], v162 offset:96
	ds_read_b128 v[200:203], v162 offset:4704
	ds_read_b128 v[222:225], v162 offset:9312
	ds_read_b128 v[226:229], v162 offset:13920
	ds_read_b128 v[230:233], v163 offset:96
	ds_read_b128 v[234:237], v163 offset:4704
	s_waitcnt lgkmcnt(0)
	s_barrier
; DI f16v mfma32(h8v a, h8v b, f16v c) { return __builtin_amdgcn_mfma_f32_32x32x16_f16(a, b, c, 0, 0, 0); }
; template <bool GATHER>
; DI void gemm256_main(const h16* __restrict__ A, int lda, const int* __restrict__ idx, int m0,
;                      const h16* __restrict__ B, int ldb, int n0, int K, h16* lds, f16v (&acc)[4][2]) {
;     ...
;   for (int kt = 0; kt < nk; ++kt) {
;     const h16* As = lds + (kt & 1) * (512 * LDH);
;     const h16* Bs = As + 256 * LDH;
;     h16* Wn = lds + ((kt & 1) ^ 1) * (512 * LDH);
;     if (kt + 1 < nk) {
; #pragma unroll
;       for (int i = 0; i < 4; ++i) { *(u4v*)&Wn[lr * LDH + lc + 8 * i] = ra[i]; *(u4v*)&Wn[(256 + lr) * LDH + lc + 8 * i] = rb[i]; }
;     }
;     if (kt + 2 < nk) {
; #pragma unroll
;       for (int i = 0; i < 4; ++i) { ra[i] = *(const u4v*)(AP_ + 8 * i); rb[i] = *(const u4v*)(BP_ + 8 * i); }
;       ao += 64; bo += 64;
;     }
; #pragma unroll
;     for (int ks = 0; ks < 4; ++ks) {
;       h8v af[4], bf[2];
; #pragma unroll
;       for (int i = 0; i < 4; ++i) af[i] = *(const h8v*)&As[(wm * 128 + i * 32 + (lane & 31)) * LDH + ks * 16 + 8 * (lane >> 5)];
; #pragma unroll
;       for (int j = 0; j < 2; ++j) bf[j] = *(const h8v*)&Bs[(wn * 64 + j * 32 + (lane & 31)) * LDH + ks * 16 + 8 * (lane >> 5)];
; #pragma unroll
;       for (int i = 0; i < 4; ++i)
; #pragma unroll
;         for (int j = 0; j < 2; ++j) acc[i][j] = mfma32(bf[j], af[i], acc[i][j]);
;     }
;     __syncthreads();
;   }
	s_waitcnt vmcnt(0)
	ds_write_b128 v219, v[158:161]
	ds_write_b128 v220, v[150:153]
	ds_write_b128 v219, v[154:157] offset:16
	ds_write_b128 v220, v[142:145] offset:16
	ds_write_b128 v219, v[146:149] offset:32
	ds_write_b128 v220, v[134:137] offset:32
	ds_write_b128 v219, v[138:141] offset:48
	ds_write_b128 v220, v[130:133] offset:48
	ds_read_b128 v[130:133], v218 offset:4608
	ds_read_b128 v[134:137], v218 offset:9216
	ds_read_b128 v[138:141], v218 offset:13824
	ds_read_b128 v[142:145], v217 offset:41472
	ds_read_b128 v[146:149], v218
	ds_read_b128 v[150:153], v218 offset:32
	ds_read_b128 v[154:157], v217 offset:36864
	ds_read_b128 v[158:161], v217 offset:36896
	v_mfma_f32_32x32x16_f16 v[98:113], v[230:233], v[174:177], v[98:113]
	v_mfma_f32_32x32x16_f16 v[114:129], v[234:237], v[174:177], v[114:129]
	v_mfma_f32_32x32x16_f16 v[66:81], v[230:233], v[200:203], v[66:81]
	v_mfma_f32_32x32x16_f16 v[82:97], v[234:237], v[200:203], v[82:97]
	v_mfma_f32_32x32x16_f16 v[34:49], v[230:233], v[222:225], v[34:49]
	v_mfma_f32_32x32x16_f16 v[50:65], v[234:237], v[222:225], v[50:65]
	v_mfma_f32_32x32x16_f16 v[2:17], v[230:233], v[226:229], v[2:17]
	v_mfma_f32_32x32x16_f16 v[18:33], v[234:237], v[226:229], v[18:33]
	s_waitcnt lgkmcnt(1)
	v_mfma_f32_32x32x16_f16 v[98:113], v[154:157], v[146:149], v[98:113]
	v_mfma_f32_32x32x16_f16 v[114:129], v[142:145], v[146:149], v[114:129]
	v_mfma_f32_32x32x16_f16 v[66:81], v[154:157], v[130:133], v[66:81]
	v_mfma_f32_32x32x16_f16 v[82:97], v[142:145], v[130:133], v[82:97]
	v_mfma_f32_32x32x16_f16 v[34:49], v[154:157], v[134:137], v[34:49]
	v_mfma_f32_32x32x16_f16 v[50:65], v[142:145], v[134:137], v[50:65]
	v_mfma_f32_32x32x16_f16 v[2:17], v[154:157], v[138:141], v[2:17]
	v_mfma_f32_32x32x16_f16 v[18:33], v[142:145], v[138:141], v[18:33]
	ds_read_b128 v[130:133], v218 offset:4640
	ds_read_b128 v[134:137], v218 offset:9248
	ds_read_b128 v[138:141], v218 offset:13856
	ds_read_b128 v[142:145], v217 offset:41504
	s_waitcnt lgkmcnt(4)
	v_mfma_f32_32x32x16_f16 v[98:113], v[158:161], v[150:153], v[98:113]
	s_waitcnt lgkmcnt(0)
	v_mfma_f32_32x32x16_f16 v[114:129], v[142:145], v[150:153], v[114:129]
	v_mfma_f32_32x32x16_f16 v[66:81], v[158:161], v[130:133], v[66:81]
	v_mfma_f32_32x32x16_f16 v[82:97], v[142:145], v[130:133], v[82:97]
	v_mfma_f32_32x32x16_f16 v[34:49], v[158:161], v[134:137], v[34:49]
	v_mfma_f32_32x32x16_f16 v[50:65], v[142:145], v[134:137], v[50:65]
	v_mfma_f32_32x32x16_f16 v[2:17], v[158:161], v[138:141], v[2:17]
	v_mfma_f32_32x32x16_f16 v[18:33], v[142:145], v[138:141], v[18:33]
	ds_read_b128 v[130:133], v218 offset:64
	ds_read_b128 v[134:137], v218 offset:4672
	ds_read_b128 v[138:141], v218 offset:9280
	ds_read_b128 v[142:145], v218 offset:13888
	ds_read_b128 v[146:149], v217 offset:36928
	ds_read_b128 v[150:153], v217 offset:41536
	s_waitcnt lgkmcnt(1)
	v_mfma_f32_32x32x16_f16 v[98:113], v[146:149], v[130:133], v[98:113]
	s_waitcnt lgkmcnt(0)
	v_mfma_f32_32x32x16_f16 v[114:129], v[150:153], v[130:133], v[114:129]
	v_mfma_f32_32x32x16_f16 v[66:81], v[146:149], v[134:137], v[66:81]
	v_mfma_f32_32x32x16_f16 v[82:97], v[150:153], v[134:137], v[82:97]
	v_mfma_f32_32x32x16_f16 v[34:49], v[146:149], v[138:141], v[34:49]
	v_mfma_f32_32x32x16_f16 v[50:65], v[150:153], v[138:141], v[50:65]
	v_mfma_f32_32x32x16_f16 v[2:17], v[146:149], v[142:145], v[2:17]
	v_mfma_f32_32x32x16_f16 v[18:33], v[150:153], v[142:145], v[18:33]
	ds_read_b128 v[130:133], v218 offset:96
	ds_read_b128 v[134:137], v218 offset:4704
	ds_read_b128 v[138:141], v218 offset:9312
	ds_read_b128 v[142:145], v218 offset:13920
	ds_read_b128 v[146:149], v217 offset:36960
	ds_read_b128 v[150:153], v217 offset:41568
	s_waitcnt lgkmcnt(0)
	s_barrier
	v_mfma_f32_32x32x16_f16 v[98:113], v[146:149], v[130:133], v[98:113]
	v_mfma_f32_32x32x16_f16 v[114:129], v[150:153], v[130:133], v[114:129]
	v_mfma_f32_32x32x16_f16 v[66:81], v[146:149], v[134:137], v[66:81]
	v_mfma_f32_32x32x16_f16 v[82:97], v[150:153], v[134:137], v[82:97]
	v_mfma_f32_32x32x16_f16 v[34:49], v[146:149], v[138:141], v[34:49]
	v_mfma_f32_32x32x16_f16 v[50:65], v[150:153], v[138:141], v[50:65]
	v_mfma_f32_32x32x16_f16 v[2:17], v[146:149], v[142:145], v[2:17]
	v_mfma_f32_32x32x16_f16 v[18:33], v[150:153], v[142:145], v[18:33]
	ds_read_b128 v[130:133], v162 offset:4608
	ds_read_b128 v[134:137], v162 offset:9216
	ds_read_b128 v[138:141], v162 offset:13824
	ds_read_b128 v[142:145], v163 offset:4608
	ds_read_b128 v[146:149], v162
	ds_read_b128 v[150:153], v162 offset:32
	ds_read_b128 v[154:157], v163
	ds_read_b128 v[158:161], v163 offset:32
	s_waitcnt lgkmcnt(1)
	v_mfma_f32_32x32x16_f16 v[98:113], v[154:157], v[146:149], v[98:113]
	v_mfma_f32_32x32x16_f16 v[114:129], v[142:145], v[146:149], v[114:129]
	v_mfma_f32_32x32x16_f16 v[66:81], v[154:157], v[130:133], v[66:81]
	v_mfma_f32_32x32x16_f16 v[82:97], v[142:145], v[130:133], v[82:97]
	v_mfma_f32_32x32x16_f16 v[34:49], v[154:157], v[134:137], v[34:49]
	v_mfma_f32_32x32x16_f16 v[50:65], v[142:145], v[134:137], v[50:65]
	v_mfma_f32_32x32x16_f16 v[2:17], v[154:157], v[138:141], v[2:17]
	v_mfma_f32_32x32x16_f16 v[18:33], v[142:145], v[138:141], v[18:33]
	ds_read_b128 v[130:133], v162 offset:4640
	ds_read_b128 v[134:137], v162 offset:9248
	ds_read_b128 v[138:141], v162 offset:13856
	ds_read_b128 v[142:145], v163 offset:4640
	s_waitcnt lgkmcnt(4)
	v_mfma_f32_32x32x16_f16 v[98:113], v[158:161], v[150:153], v[98:113]
	s_waitcnt lgkmcnt(0)
	v_mfma_f32_32x32x16_f16 v[114:129], v[142:145], v[150:153], v[114:129]
	v_mfma_f32_32x32x16_f16 v[66:81], v[158:161], v[130:133], v[66:81]
	v_mfma_f32_32x32x16_f16 v[82:97], v[142:145], v[130:133], v[82:97]
	v_mfma_f32_32x32x16_f16 v[34:49], v[158:161], v[134:137], v[34:49]
	v_mfma_f32_32x32x16_f16 v[50:65], v[142:145], v[134:137], v[50:65]
	v_mfma_f32_32x32x16_f16 v[2:17], v[158:161], v[138:141], v[2:17]
	v_mfma_f32_32x32x16_f16 v[18:33], v[142:145], v[138:141], v[18:33]
	ds_read_b128 v[130:133], v162 offset:64
	ds_read_b128 v[134:137], v162 offset:4672
	ds_read_b128 v[138:141], v162 offset:9280
	ds_read_b128 v[142:145], v162 offset:13888
	ds_read_b128 v[146:149], v163 offset:64
	ds_read_b128 v[150:153], v163 offset:4672
	s_waitcnt lgkmcnt(1)
	v_mfma_f32_32x32x16_f16 v[98:113], v[146:149], v[130:133], v[98:113]
	s_waitcnt lgkmcnt(0)
	v_mfma_f32_32x32x16_f16 v[114:129], v[150:153], v[130:133], v[114:129]
	v_mfma_f32_32x32x16_f16 v[66:81], v[146:149], v[134:137], v[66:81]
	v_mfma_f32_32x32x16_f16 v[82:97], v[150:153], v[134:137], v[82:97]
	v_mfma_f32_32x32x16_f16 v[34:49], v[146:149], v[138:141], v[34:49]
	v_mfma_f32_32x32x16_f16 v[50:65], v[150:153], v[138:141], v[50:65]
	v_mfma_f32_32x32x16_f16 v[2:17], v[146:149], v[142:145], v[2:17]
	v_mfma_f32_32x32x16_f16 v[18:33], v[150:153], v[142:145], v[18:33]
	ds_read_b128 v[130:133], v162 offset:96
	ds_read_b128 v[134:137], v162 offset:4704
	ds_read_b128 v[138:141], v162 offset:9312
	ds_read_b128 v[142:145], v162 offset:13920
	ds_read_b128 v[146:149], v163 offset:96
	ds_read_b128 v[150:153], v163 offset:4704
	s_waitcnt lgkmcnt(0)
	s_barrier
; DI int otid512() { int t = threadIdx.x; asm volatile("" : "+v"(t)); return t; }
; DI float silu_(float x) { return x / (1.f + __expf(-x)); }
; template <class Epi>
; DI void gemm256_epilogue(f16v (&acc)[4][2], int m0, int n0, Epi epi) {
;   const int tid = otid512(), lane = tid & 63, wv = tid >> 6, wm = wv >> 2, wn = wv & 3, h = lane >> 5;
; #pragma unroll
;   for (int i = 0; i < 4; ++i) {
;     const int m = m0 + wm * 128 + i * 32 + (lane & 31);
; #pragma unroll
;     for (int g = 0; g < 4; ++g) {
;       const int n = n0 + wn * 64 + 8 * g + 4 * h;
;       f4v v0 = {acc[i][0][4 * g], acc[i][0][4 * g + 1], acc[i][0][4 * g + 2], acc[i][0][4 * g + 3]};
;       f4v v1 = {acc[i][1][4 * g], acc[i][1][4 * g + 1], acc[i][1][4 * g + 2], acc[i][1][4 * g + 3]};
;       epi(m, n, v0, v1);
;     }
;   }
; }
; DI void phase_ffn1_moe(const Params& p, int bid, int nb, h16* lds) {
;     ...
;     gemm256_epilogue(acc, m0, n0, [&](int m, int n, f4v v0, f4v v1) {
;       f4v hq;
; #pragma unroll
;       for (int i = 0; i < 4; ++i) hq[i] = silu_(v0[i]) * v1[i];
;       st_h4(&H[(size_t)m * 1408 + (n >> 6) * 32 + (n & 31)], hq);
;     });
	v_mfma_f32_32x32x16_f16 v[98:113], v[146:149], v[130:133], v[98:113]
	v_mfma_f32_32x32x16_f16 v[66:81], v[146:149], v[134:137], v[66:81]
	v_mfma_f32_32x32x16_f16 v[82:97], v[150:153], v[134:137], v[82:97]
	v_mfma_f32_32x32x16_f16 v[114:129], v[150:153], v[130:133], v[114:129]
	v_mfma_f32_32x32x16_f16 v[34:49], v[146:149], v[138:141], v[34:49]
	v_mfma_f32_32x32x16_f16 v[50:65], v[150:153], v[138:141], v[50:65]
	v_mfma_f32_32x32x16_f16 v[2:17], v[146:149], v[142:145], v[2:17]
	v_mfma_f32_32x32x16_f16 v[18:33], v[150:153], v[142:145], v[18:33]
	s_nop 15
	s_barrier
	v_readfirstlane_b32 s66, v180
	s_sub_i32 s69, s4, s7
	s_mov_b32 s65, s6
	s_lshr_b32 s66, s66, 6
	s_and_b32 s67, s66, 3
	s_lshr_b32 s68, s66, 2
	s_lshr_b32 s70, s69, 1
	s_lshl_b32 s67, s67, 5
	s_add_i32 s70, s70, s67
	s_lshl_b32 s71, s68, 7
	s_add_i32 s71, s71, s65
	s_mul_i32 s72, s66, 0x2800
	s_add_i32 s72, s72, 16
	s_mov_b32 s73, 0xb00
	v_and_b32_e32 v146, 63, v180
	v_and_b32_e32 v148, 31, v146
	v_lshrrev_b32_e32 v147, 5, v146
	v_mul_u32_u24_e32 v130, 0x50, v148
	v_lshl_add_u32 v130, v147, 3, v130
	v_add_u32_e32 v130, s72, v130
	v_lshrrev_b32_e32 v149, 2, v146
	v_and_b32_e32 v138, 3, v146
	v_mul_u32_u24_e32 v131, 0x50, v149
	v_lshl_add_u32 v131, v138, 4, v131
	v_add_u32_e32 v131, s72, v131
	v_add_u32_e32 v140, s71, v149
	v_lshl_add_u32 v138, v138, 3, s70
	v_mov_b64_e32 v[132:133], s[0:1]
	v_mad_u64_u32 v[132:133], s[74:75], v140, s73, v[132:133]
	v_lshlrev_b32_e32 v138, 1, v138
	v_mov_b32_e32 v139, v0
	v_lshl_add_u64 v[132:133], v[132:133], 0, v[138:139]
	s_mov_b32 s76, 0xb000
	s_mov_b32 s77, 0
	v_mul_f32_e32 v234, 0xbfb8aa3b, v98
	v_mul_f32_e32 v235, 0xbfb8aa3b, v99
	v_mul_f32_e32 v236, 0xbfb8aa3b, v100
	v_mul_f32_e32 v237, 0xbfb8aa3b, v101
	v_exp_f32_e32 v234, v234
	v_exp_f32_e32 v235, v235
	v_exp_f32_e32 v236, v236
	v_exp_f32_e32 v237, v237
	v_add_f32_e32 v234, 1.0, v234
	v_add_f32_e32 v235, 1.0, v235
	v_add_f32_e32 v236, 1.0, v236
	v_add_f32_e32 v237, 1.0, v237
	v_rcp_f32_e32 v234, v234
	v_rcp_f32_e32 v235, v235
	v_rcp_f32_e32 v236, v236
	v_rcp_f32_e32 v237, v237
	v_mul_f32_e32 v98, v98, v234
	v_mul_f32_e32 v99, v99, v235
	v_mul_f32_e32 v100, v100, v236
	v_mul_f32_e32 v101, v101, v237
	v_mul_f32_e32 v98, v98, v114
	v_mul_f32_e32 v99, v99, v115
	v_mul_f32_e32 v100, v100, v116
	v_mul_f32_e32 v101, v101, v117
	v_cvt_pk_f16_f32 v138, v98, v99
	v_cvt_pk_f16_f32 v139, v100, v101
	ds_write_b64 v130, v[138:139] offset:0
	v_mul_f32_e32 v234, 0xbfb8aa3b, v102
	v_mul_f32_e32 v235, 0xbfb8aa3b, v103
	v_mul_f32_e32 v236, 0xbfb8aa3b, v104
	v_mul_f32_e32 v237, 0xbfb8aa3b, v105
	v_exp_f32_e32 v234, v234
	v_exp_f32_e32 v235, v235
	v_exp_f32_e32 v236, v236
	v_exp_f32_e32 v237, v237
	v_add_f32_e32 v234, 1.0, v234
	v_add_f32_e32 v235, 1.0, v235
	v_add_f32_e32 v236, 1.0, v236
	v_add_f32_e32 v237, 1.0, v237
	v_rcp_f32_e32 v234, v234
	v_rcp_f32_e32 v235, v235
	v_rcp_f32_e32 v236, v236
	v_rcp_f32_e32 v237, v237
	v_mul_f32_e32 v102, v102, v234
	v_mul_f32_e32 v103, v103, v235
	v_mul_f32_e32 v104, v104, v236
	v_mul_f32_e32 v105, v105, v237
	v_mul_f32_e32 v102, v102, v118
	v_mul_f32_e32 v103, v103, v119
	v_mul_f32_e32 v104, v104, v120
	v_mul_f32_e32 v105, v105, v121
	v_cvt_pk_f16_f32 v140, v102, v103
	v_cvt_pk_f16_f32 v141, v104, v105
	ds_write_b64 v130, v[140:141] offset:16
	v_mul_f32_e32 v234, 0xbfb8aa3b, v106
	v_mul_f32_e32 v235, 0xbfb8aa3b, v107
	v_mul_f32_e32 v236, 0xbfb8aa3b, v108
	v_mul_f32_e32 v237, 0xbfb8aa3b, v109
	v_exp_f32_e32 v234, v234
	v_exp_f32_e32 v235, v235
	v_exp_f32_e32 v236, v236
	v_exp_f32_e32 v237, v237
	v_add_f32_e32 v234, 1.0, v234
	v_add_f32_e32 v235, 1.0, v235
	v_add_f32_e32 v236, 1.0, v236
	v_add_f32_e32 v237, 1.0, v237
	v_rcp_f32_e32 v234, v234
	v_rcp_f32_e32 v235, v235
	v_rcp_f32_e32 v236, v236
	v_rcp_f32_e32 v237, v237
	v_mul_f32_e32 v106, v106, v234
	v_mul_f32_e32 v107, v107, v235
	v_mul_f32_e32 v108, v108, v236
	v_mul_f32_e32 v109, v109, v237
	v_mul_f32_e32 v106, v106, v122
	v_mul_f32_e32 v107, v107, v123
	v_mul_f32_e32 v108, v108, v124
	v_mul_f32_e32 v109, v109, v125
	v_cvt_pk_f16_f32 v142, v106, v107
	v_cvt_pk_f16_f32 v143, v108, v109
	ds_write_b64 v130, v[142:143] offset:32
	v_mul_f32_e32 v234, 0xbfb8aa3b, v110
	v_mul_f32_e32 v235, 0xbfb8aa3b, v111
	v_mul_f32_e32 v236, 0xbfb8aa3b, v112
	v_mul_f32_e32 v237, 0xbfb8aa3b, v113
	v_exp_f32_e32 v234, v234
	v_exp_f32_e32 v235, v235
	v_exp_f32_e32 v236, v236
	v_exp_f32_e32 v237, v237
	v_add_f32_e32 v234, 1.0, v234
	v_add_f32_e32 v235, 1.0, v235
	v_add_f32_e32 v236, 1.0, v236
	v_add_f32_e32 v237, 1.0, v237
	v_rcp_f32_e32 v234, v234
	v_rcp_f32_e32 v235, v235
	v_rcp_f32_e32 v236, v236
	v_rcp_f32_e32 v237, v237
	v_mul_f32_e32 v110, v110, v234
	v_mul_f32_e32 v111, v111, v235
	v_mul_f32_e32 v112, v112, v236
	v_mul_f32_e32 v113, v113, v237
	v_mul_f32_e32 v110, v110, v126
	v_mul_f32_e32 v111, v111, v127
	v_mul_f32_e32 v112, v112, v128
	v_mul_f32_e32 v113, v113, v129
	v_cvt_pk_f16_f32 v144, v110, v111
	v_cvt_pk_f16_f32 v145, v112, v113
	ds_write_b64 v130, v[144:145] offset:48
	v_mul_f32_e32 v234, 0xbfb8aa3b, v66
	v_mul_f32_e32 v235, 0xbfb8aa3b, v67
	v_mul_f32_e32 v236, 0xbfb8aa3b, v68
	v_mul_f32_e32 v237, 0xbfb8aa3b, v69
	v_exp_f32_e32 v234, v234
	v_exp_f32_e32 v235, v235
	v_exp_f32_e32 v236, v236
	v_exp_f32_e32 v237, v237
	v_add_f32_e32 v234, 1.0, v234
	v_add_f32_e32 v235, 1.0, v235
	v_add_f32_e32 v236, 1.0, v236
	v_add_f32_e32 v237, 1.0, v237
	v_rcp_f32_e32 v234, v234
	v_rcp_f32_e32 v235, v235
	v_rcp_f32_e32 v236, v236
	v_rcp_f32_e32 v237, v237
	v_mul_f32_e32 v66, v66, v234
	v_mul_f32_e32 v67, v67, v235
	v_mul_f32_e32 v68, v68, v236
	v_mul_f32_e32 v69, v69, v237
	v_mul_f32_e32 v66, v66, v82
	v_mul_f32_e32 v67, v67, v83
; DI float silu_(float x) { return x / (1.f + __expf(-x)); }
; DI void phase_ffn1_moe(const Params& p, int bid, int nb, h16* lds) {
;     ...
;     gemm256_epilogue(acc, m0, n0, [&](int m, int n, f4v v0, f4v v1) {
;       f4v hq;
; #pragma unroll
;       for (int i = 0; i < 4; ++i) hq[i] = silu_(v0[i]) * v1[i];
;       st_h4(&H[(size_t)m * 1408 + (n >> 6) * 32 + (n & 31)], hq);
;     });
	v_mul_f32_e32 v68, v68, v84
	v_mul_f32_e32 v69, v69, v85
	v_cvt_pk_f16_f32 v138, v66, v67
	v_cvt_pk_f16_f32 v139, v68, v69
	ds_write_b64 v130, v[138:139] offset:2560
	v_mul_f32_e32 v234, 0xbfb8aa3b, v70
	v_mul_f32_e32 v235, 0xbfb8aa3b, v71
	v_mul_f32_e32 v236, 0xbfb8aa3b, v72
	v_mul_f32_e32 v237, 0xbfb8aa3b, v73
	v_exp_f32_e32 v234, v234
	v_exp_f32_e32 v235, v235
	v_exp_f32_e32 v236, v236
	v_exp_f32_e32 v237, v237
	v_add_f32_e32 v234, 1.0, v234
	v_add_f32_e32 v235, 1.0, v235
	v_add_f32_e32 v236, 1.0, v236
	v_add_f32_e32 v237, 1.0, v237
	v_rcp_f32_e32 v234, v234
	v_rcp_f32_e32 v235, v235
	v_rcp_f32_e32 v236, v236
	v_rcp_f32_e32 v237, v237
	v_mul_f32_e32 v70, v70, v234
	v_mul_f32_e32 v71, v71, v235
	v_mul_f32_e32 v72, v72, v236
	v_mul_f32_e32 v73, v73, v237
	v_mul_f32_e32 v70, v70, v86
	v_mul_f32_e32 v71, v71, v87
	v_mul_f32_e32 v72, v72, v88
	v_mul_f32_e32 v73, v73, v89
	v_cvt_pk_f16_f32 v140, v70, v71
	v_cvt_pk_f16_f32 v141, v72, v73
	ds_write_b64 v130, v[140:141] offset:2576
	v_mul_f32_e32 v234, 0xbfb8aa3b, v74
	v_mul_f32_e32 v235, 0xbfb8aa3b, v75
	v_mul_f32_e32 v236, 0xbfb8aa3b, v76
	v_mul_f32_e32 v237, 0xbfb8aa3b, v77
	v_exp_f32_e32 v234, v234
	v_exp_f32_e32 v235, v235
	v_exp_f32_e32 v236, v236
	v_exp_f32_e32 v237, v237
	v_add_f32_e32 v234, 1.0, v234
	v_add_f32_e32 v235, 1.0, v235
	v_add_f32_e32 v236, 1.0, v236
	v_add_f32_e32 v237, 1.0, v237
	v_rcp_f32_e32 v234, v234
	v_rcp_f32_e32 v235, v235
	v_rcp_f32_e32 v236, v236
	v_rcp_f32_e32 v237, v237
	v_mul_f32_e32 v74, v74, v234
	v_mul_f32_e32 v75, v75, v235
	v_mul_f32_e32 v76, v76, v236
	v_mul_f32_e32 v77, v77, v237
	v_mul_f32_e32 v74, v74, v90
	v_mul_f32_e32 v75, v75, v91
	v_mul_f32_e32 v76, v76, v92
	v_mul_f32_e32 v77, v77, v93
	v_cvt_pk_f16_f32 v142, v74, v75
	v_cvt_pk_f16_f32 v143, v76, v77
	ds_write_b64 v130, v[142:143] offset:2592
	v_mul_f32_e32 v234, 0xbfb8aa3b, v78
	v_mul_f32_e32 v235, 0xbfb8aa3b, v79
	v_mul_f32_e32 v236, 0xbfb8aa3b, v80
	v_mul_f32_e32 v237, 0xbfb8aa3b, v81
	v_exp_f32_e32 v234, v234
	v_exp_f32_e32 v235, v235
	v_exp_f32_e32 v236, v236
	v_exp_f32_e32 v237, v237
	v_add_f32_e32 v234, 1.0, v234
	v_add_f32_e32 v235, 1.0, v235
	v_add_f32_e32 v236, 1.0, v236
	v_add_f32_e32 v237, 1.0, v237
	v_rcp_f32_e32 v234, v234
	v_rcp_f32_e32 v235, v235
	v_rcp_f32_e32 v236, v236
	v_rcp_f32_e32 v237, v237
	v_mul_f32_e32 v78, v78, v234
	v_mul_f32_e32 v79, v79, v235
	v_mul_f32_e32 v80, v80, v236
	v_mul_f32_e32 v81, v81, v237
	v_mul_f32_e32 v78, v78, v94
	v_mul_f32_e32 v79, v79, v95
	v_mul_f32_e32 v80, v80, v96
	v_mul_f32_e32 v81, v81, v97
	v_cvt_pk_f16_f32 v144, v78, v79
	v_cvt_pk_f16_f32 v145, v80, v81
	ds_write_b64 v130, v[144:145] offset:2608
	v_mul_f32_e32 v234, 0xbfb8aa3b, v34
	v_mul_f32_e32 v235, 0xbfb8aa3b, v35
	v_mul_f32_e32 v236, 0xbfb8aa3b, v36
	v_mul_f32_e32 v237, 0xbfb8aa3b, v37
	v_exp_f32_e32 v234, v234
	v_exp_f32_e32 v235, v235
	v_exp_f32_e32 v236, v236
	v_exp_f32_e32 v237, v237
	v_add_f32_e32 v234, 1.0, v234
	v_add_f32_e32 v235, 1.0, v235
	v_add_f32_e32 v236, 1.0, v236
	v_add_f32_e32 v237, 1.0, v237
	v_rcp_f32_e32 v234, v234
	v_rcp_f32_e32 v235, v235
	v_rcp_f32_e32 v236, v236
	v_rcp_f32_e32 v237, v237
	v_mul_f32_e32 v34, v34, v234
	v_mul_f32_e32 v35, v35, v235
	v_mul_f32_e32 v36, v36, v236
	v_mul_f32_e32 v37, v37, v237
	v_mul_f32_e32 v34, v34, v50
	v_mul_f32_e32 v35, v35, v51
	v_mul_f32_e32 v36, v36, v52
	v_mul_f32_e32 v37, v37, v53
	v_cvt_pk_f16_f32 v138, v34, v35
	v_cvt_pk_f16_f32 v139, v36, v37
	ds_write_b64 v130, v[138:139] offset:5120
	v_mul_f32_e32 v234, 0xbfb8aa3b, v38
	v_mul_f32_e32 v235, 0xbfb8aa3b, v39
	v_mul_f32_e32 v236, 0xbfb8aa3b, v40
	v_mul_f32_e32 v237, 0xbfb8aa3b, v41
	v_exp_f32_e32 v234, v234
	v_exp_f32_e32 v235, v235
	v_exp_f32_e32 v236, v236
	v_exp_f32_e32 v237, v237
	v_add_f32_e32 v234, 1.0, v234
	v_add_f32_e32 v235, 1.0, v235
	v_add_f32_e32 v236, 1.0, v236
	v_add_f32_e32 v237, 1.0, v237
	v_rcp_f32_e32 v234, v234
	v_rcp_f32_e32 v235, v235
	v_rcp_f32_e32 v236, v236
	v_rcp_f32_e32 v237, v237
	v_mul_f32_e32 v38, v38, v234
	v_mul_f32_e32 v39, v39, v235
	v_mul_f32_e32 v40, v40, v236
	v_mul_f32_e32 v41, v41, v237
	v_mul_f32_e32 v38, v38, v54
	v_mul_f32_e32 v39, v39, v55
	v_mul_f32_e32 v40, v40, v56
	v_mul_f32_e32 v41, v41, v57
	v_cvt_pk_f16_f32 v140, v38, v39
	v_cvt_pk_f16_f32 v141, v40, v41
	ds_write_b64 v130, v[140:141] offset:5136
	v_mul_f32_e32 v234, 0xbfb8aa3b, v42
	v_mul_f32_e32 v235, 0xbfb8aa3b, v43
	v_mul_f32_e32 v236, 0xbfb8aa3b, v44
	v_mul_f32_e32 v237, 0xbfb8aa3b, v45
	v_exp_f32_e32 v234, v234
	v_exp_f32_e32 v235, v235
	v_exp_f32_e32 v236, v236
	v_exp_f32_e32 v237, v237
	v_add_f32_e32 v234, 1.0, v234
	v_add_f32_e32 v235, 1.0, v235
	v_add_f32_e32 v236, 1.0, v236
	v_add_f32_e32 v237, 1.0, v237
	v_rcp_f32_e32 v234, v234
	v_rcp_f32_e32 v235, v235
	v_rcp_f32_e32 v236, v236
	v_rcp_f32_e32 v237, v237
	v_mul_f32_e32 v42, v42, v234
	v_mul_f32_e32 v43, v43, v235
	v_mul_f32_e32 v44, v44, v236
	v_mul_f32_e32 v45, v45, v237
	v_mul_f32_e32 v42, v42, v58
	v_mul_f32_e32 v43, v43, v59
	v_mul_f32_e32 v44, v44, v60
	v_mul_f32_e32 v45, v45, v61
	v_cvt_pk_f16_f32 v142, v42, v43
	v_cvt_pk_f16_f32 v143, v44, v45
	ds_write_b64 v130, v[142:143] offset:5152
	v_mul_f32_e32 v234, 0xbfb8aa3b, v46
	v_mul_f32_e32 v235, 0xbfb8aa3b, v47
	v_mul_f32_e32 v236, 0xbfb8aa3b, v48
	v_mul_f32_e32 v237, 0xbfb8aa3b, v49
	v_exp_f32_e32 v234, v234
	v_exp_f32_e32 v235, v235
; DI float silu_(float x) { return x / (1.f + __expf(-x)); }
; DI void phase_ffn1_moe(const Params& p, int bid, int nb, h16* lds) {
;     ...
;     gemm256_epilogue(acc, m0, n0, [&](int m, int n, f4v v0, f4v v1) {
;       f4v hq;
; #pragma unroll
;       for (int i = 0; i < 4; ++i) hq[i] = silu_(v0[i]) * v1[i];
;       st_h4(&H[(size_t)m * 1408 + (n >> 6) * 32 + (n & 31)], hq);
;     });
	v_exp_f32_e32 v236, v236
	v_exp_f32_e32 v237, v237
	v_add_f32_e32 v234, 1.0, v234
	v_add_f32_e32 v235, 1.0, v235
	v_add_f32_e32 v236, 1.0, v236
	v_add_f32_e32 v237, 1.0, v237
	v_rcp_f32_e32 v234, v234
	v_rcp_f32_e32 v235, v235
	v_rcp_f32_e32 v236, v236
	v_rcp_f32_e32 v237, v237
	v_mul_f32_e32 v46, v46, v234
	v_mul_f32_e32 v47, v47, v235
	v_mul_f32_e32 v48, v48, v236
	v_mul_f32_e32 v49, v49, v237
	v_mul_f32_e32 v46, v46, v62
	v_mul_f32_e32 v47, v47, v63
	v_mul_f32_e32 v48, v48, v64
	v_mul_f32_e32 v49, v49, v65
	v_cvt_pk_f16_f32 v144, v46, v47
	v_cvt_pk_f16_f32 v145, v48, v49
	ds_write_b64 v130, v[144:145] offset:5168
	v_mul_f32_e32 v234, 0xbfb8aa3b, v2
	v_mul_f32_e32 v235, 0xbfb8aa3b, v3
	v_mul_f32_e32 v236, 0xbfb8aa3b, v4
	v_mul_f32_e32 v237, 0xbfb8aa3b, v5
	v_exp_f32_e32 v234, v234
	v_exp_f32_e32 v235, v235
	v_exp_f32_e32 v236, v236
	v_exp_f32_e32 v237, v237
	v_add_f32_e32 v234, 1.0, v234
	v_add_f32_e32 v235, 1.0, v235
	v_add_f32_e32 v236, 1.0, v236
	v_add_f32_e32 v237, 1.0, v237
	v_rcp_f32_e32 v234, v234
	v_rcp_f32_e32 v235, v235
	v_rcp_f32_e32 v236, v236
	v_rcp_f32_e32 v237, v237
	v_mul_f32_e32 v2, v2, v234
	v_mul_f32_e32 v3, v3, v235
	v_mul_f32_e32 v4, v4, v236
	v_mul_f32_e32 v5, v5, v237
	v_mul_f32_e32 v2, v2, v18
	v_mul_f32_e32 v3, v3, v19
	v_mul_f32_e32 v4, v4, v20
	v_mul_f32_e32 v5, v5, v21
	v_cvt_pk_f16_f32 v138, v2, v3
	v_cvt_pk_f16_f32 v139, v4, v5
	ds_write_b64 v130, v[138:139] offset:7680
	v_mul_f32_e32 v234, 0xbfb8aa3b, v6
	v_mul_f32_e32 v235, 0xbfb8aa3b, v7
	v_mul_f32_e32 v236, 0xbfb8aa3b, v8
	v_mul_f32_e32 v237, 0xbfb8aa3b, v9
	v_exp_f32_e32 v234, v234
	v_exp_f32_e32 v235, v235
	v_exp_f32_e32 v236, v236
	v_exp_f32_e32 v237, v237
	v_add_f32_e32 v234, 1.0, v234
	v_add_f32_e32 v235, 1.0, v235
	v_add_f32_e32 v236, 1.0, v236
	v_add_f32_e32 v237, 1.0, v237
	v_rcp_f32_e32 v234, v234
	v_rcp_f32_e32 v235, v235
	v_rcp_f32_e32 v236, v236
	v_rcp_f32_e32 v237, v237
	v_mul_f32_e32 v6, v6, v234
	v_mul_f32_e32 v7, v7, v235
	v_mul_f32_e32 v8, v8, v236
	v_mul_f32_e32 v9, v9, v237
	v_mul_f32_e32 v6, v6, v22
	v_mul_f32_e32 v7, v7, v23
	v_mul_f32_e32 v8, v8, v24
	v_mul_f32_e32 v9, v9, v25
	v_cvt_pk_f16_f32 v140, v6, v7
	v_cvt_pk_f16_f32 v141, v8, v9
	ds_write_b64 v130, v[140:141] offset:7696
	v_mul_f32_e32 v234, 0xbfb8aa3b, v10
	v_mul_f32_e32 v235, 0xbfb8aa3b, v11
	v_mul_f32_e32 v236, 0xbfb8aa3b, v12
	v_mul_f32_e32 v237, 0xbfb8aa3b, v13
	v_exp_f32_e32 v234, v234
	v_exp_f32_e32 v235, v235
	v_exp_f32_e32 v236, v236
	v_exp_f32_e32 v237, v237
	v_add_f32_e32 v234, 1.0, v234
	v_add_f32_e32 v235, 1.0, v235
	v_add_f32_e32 v236, 1.0, v236
	v_add_f32_e32 v237, 1.0, v237
	v_rcp_f32_e32 v234, v234
	v_rcp_f32_e32 v235, v235
	v_rcp_f32_e32 v236, v236
	v_rcp_f32_e32 v237, v237
	v_mul_f32_e32 v10, v10, v234
	v_mul_f32_e32 v11, v11, v235
	v_mul_f32_e32 v12, v12, v236
	v_mul_f32_e32 v13, v13, v237
	v_mul_f32_e32 v10, v10, v26
	v_mul_f32_e32 v11, v11, v27
	v_mul_f32_e32 v12, v12, v28
	v_mul_f32_e32 v13, v13, v29
	v_cvt_pk_f16_f32 v142, v10, v11
	v_cvt_pk_f16_f32 v143, v12, v13
	ds_write_b64 v130, v[142:143] offset:7712
	v_mul_f32_e32 v234, 0xbfb8aa3b, v14
	v_mul_f32_e32 v235, 0xbfb8aa3b, v15
	v_mul_f32_e32 v236, 0xbfb8aa3b, v16
	v_mul_f32_e32 v237, 0xbfb8aa3b, v17
	v_exp_f32_e32 v234, v234
	v_exp_f32_e32 v235, v235
	v_exp_f32_e32 v236, v236
	v_exp_f32_e32 v237, v237
	v_add_f32_e32 v234, 1.0, v234
	v_add_f32_e32 v235, 1.0, v235
	v_add_f32_e32 v236, 1.0, v236
	v_add_f32_e32 v237, 1.0, v237
	v_rcp_f32_e32 v234, v234
	v_rcp_f32_e32 v235, v235
	v_rcp_f32_e32 v236, v236
	v_rcp_f32_e32 v237, v237
	v_mul_f32_e32 v14, v14, v234
	v_mul_f32_e32 v15, v15, v235
	v_mul_f32_e32 v16, v16, v236
	v_mul_f32_e32 v17, v17, v237
	v_mul_f32_e32 v14, v14, v30
	v_mul_f32_e32 v15, v15, v31
	v_mul_f32_e32 v16, v16, v32
	v_mul_f32_e32 v17, v17, v33
	v_cvt_pk_f16_f32 v144, v14, v15
	v_cvt_pk_f16_f32 v145, v16, v17
	ds_write_b64 v130, v[144:145] offset:7728
	ds_read_b128 v[150:153], v131 offset:0
	ds_read_b128 v[154:157], v131 offset:1280
	ds_read_b128 v[158:161], v131 offset:2560
	ds_read_b128 v[162:165], v131 offset:3840
	ds_read_b128 v[218:221], v131 offset:5120
	ds_read_b128 v[222:225], v131 offset:6400
	ds_read_b128 v[226:229], v131 offset:7680
	ds_read_b128 v[230:233], v131 offset:8960
	s_waitcnt lgkmcnt(7)
	global_store_dwordx4 v[132:133], v[150:153], off
	v_lshl_add_u64 v[132:133], v[132:133], 0, s[76:77]
	s_waitcnt lgkmcnt(6)
	global_store_dwordx4 v[132:133], v[154:157], off
	v_lshl_add_u64 v[132:133], v[132:133], 0, s[76:77]
	s_waitcnt lgkmcnt(5)
	global_store_dwordx4 v[132:133], v[158:161], off
	v_lshl_add_u64 v[132:133], v[132:133], 0, s[76:77]
	s_waitcnt lgkmcnt(4)
	global_store_dwordx4 v[132:133], v[162:165], off
	v_lshl_add_u64 v[132:133], v[132:133], 0, s[76:77]
	s_waitcnt lgkmcnt(3)
	global_store_dwordx4 v[132:133], v[218:221], off
	v_lshl_add_u64 v[132:133], v[132:133], 0, s[76:77]
	s_waitcnt lgkmcnt(2)
	global_store_dwordx4 v[132:133], v[222:225], off
	v_lshl_add_u64 v[132:133], v[132:133], 0, s[76:77]
	s_waitcnt lgkmcnt(1)
	global_store_dwordx4 v[132:133], v[226:229], off
	v_lshl_add_u64 v[132:133], v[132:133], 0, s[76:77]
	s_waitcnt lgkmcnt(0)
	global_store_dwordx4 v[132:133], v[230:233], off
	v_lshl_add_u64 v[132:133], v[132:133], 0, s[76:77]
	s_add_i32 s4, s4, s23
	v_cmp_lt_i32_e32 vcc, s5, v216
	s_nop 4
	s_cbranch_vccnz .LBB0_1520
	s_mov_b32 s56, 0xfffff80

; template <bool GATHER>
; DI void gemm256_main(const h16* __restrict__ A, int lda, const int* __restrict__ idx, int m0,
;                      const h16* __restrict__ B, int ldb, int n0, int K, h16* lds, f16v (&acc)[4][2]) {
;   const int tid = otid512(), lane = tid & 63, wv = tid >> 6, wm = wv >> 2, wn = wv & 3;
;   const int lr = tid >> 1, lc = (tid & 1) * 32;
;   unsigned ao = (unsigned)(GATHER ? idx[m0 + lr] : (m0 + lr)) * (unsigned)lda + lc;
;   unsigned bo = (unsigned)(n0 + lr) * (unsigned)ldb + lc;
;   const h16* ap = A; const h16* bp = B;
;     ...
;   u4v ra[4], rb[4];
;   const int nk = K >> 6;
;   __syncthreads();
; #pragma unroll
;   for (int i = 0; i < 4; ++i) { ra[i] = *(const u4v*)(AP_ + 8 * i); rb[i] = *(const u4v*)(BP_ + 8 * i); }
;   ao += 64; bo += 64;
; #pragma unroll
;   for (int i = 0; i < 4; ++i) { *(u4v*)&lds[lr * LDH + lc + 8 * i] = ra[i]; *(u4v*)&lds[(256 + lr) * LDH + lc + 8 * i] = rb[i]; }
; #pragma unroll
;   for (int i = 0; i < 4; ++i) { ra[i] = *(const u4v*)(AP_ + 8 * i); rb[i] = *(const u4v*)(BP_ + 8 * i); }
;   ao += 64; bo += 64;
;   __syncthreads();
;   for (int kt = 0; kt < nk; ++kt) {
;     const h16* As = lds + (kt & 1) * (512 * LDH);
;     const h16* Bs = As + 256 * LDH;
;     h16* Wn = lds + ((kt & 1) ^ 1) * (512 * LDH);
;     if (kt + 1 < nk) {
; #pragma unroll
;       for (int i = 0; i < 4; ++i) { *(u4v*)&Wn[lr * LDH + lc + 8 * i] = ra[i]; *(u4v*)&Wn[(256 + lr) * LDH + lc + 8 * i] = rb[i]; }
;     }
;     if (kt + 2 < nk) {
; #pragma unroll
;       for (int i = 0; i < 4; ++i) { ra[i] = *(const u4v*)(AP_ + 8 * i); rb[i] = *(const u4v*)(BP_ + 8 * i); }
;       ao += 64; bo += 64;
;     }
; #pragma unroll
;     for (int ks = 0; ks < 4; ++ks) {
;       h8v af[4], bf[2];
; #pragma unroll
;       for (int i = 0; i < 4; ++i) af[i] = *(const h8v*)&As[(wm * 128 + i * 32 + (lane & 31)) * LDH + ks * 16 + 8 * (lane >> 5)];
; #pragma unroll
;       for (int j = 0; j < 2; ++j) bf[j] = *(const h8v*)&Bs[(wn * 64 + j * 32 + (lane & 31)) * LDH + ks * 16 + 8 * (lane >> 5)];
; #pragma unroll
;       for (int i = 0; i < 4; ++i)
; #pragma unroll
; DI void phase_ffn1_dense(const Params& p, int bid, int nb, h16* lds) {
;     ...
;   for (int u = bid; u < 64 * 22; u += nb) {
;     const int m0 = (u / 22) * 256, n0 = (u % 22) * 256;
;     f16v acc[4][2]; acc256_zero(acc);
;     gemm256_main<false>(x16, DM, nullptr, m0, w13, 1024, n0, 1024, lds, acc);
.LBB0_1626:
	s_mul_hi_i32 s4, s3, 0x2e8ba2e9
	s_lshr_b32 s5, s4, 31
	s_ashr_i32 s4, s4, 2
	s_add_i32 s5, s4, s5
	v_mov_b32_e32 v1, v180
	s_lshl_b32 s4, s5, 8
	s_mulk_i32 s5, 0x1600
	v_ashrrev_i32_e32 v34, 1, v1
	v_lshlrev_b32_e32 v2, 5, v1
	v_subrev_u32_e32 v3, s5, v34
	v_and_b32_e32 v35, 32, v2
	v_add_u32_e32 v2, s4, v34
	v_add_u32_e32 v3, s2, v3
	v_lshl_or_b32 v2, v2, 10, v35
	v_lshl_or_b32 v176, v3, 10, v35
	v_mov_b32_e32 v3, v0
	v_mov_b32_e32 v177, v0
	v_lshl_add_u64 v[174:175], v[2:3], 1, s[20:21]
	v_lshl_add_u64 v[30:31], v[176:177], 1, s[8:9]
	s_barrier
	global_load_dwordx4 v[2:5], v[174:175], off offset:48
	global_load_dwordx4 v[6:9], v[174:175], off offset:32
	global_load_dwordx4 v[10:13], v[174:175], off offset:16
	global_load_dwordx4 v[14:17], v[174:175], off
	global_load_dwordx4 v[18:21], v[30:31], off offset:48
	global_load_dwordx4 v[22:25], v[30:31], off offset:32
	global_load_dwordx4 v[26:29], v[30:31], off offset:16
	s_nop 0
	global_load_dwordx4 v[30:33], v[30:31], off
	v_mul_lo_u32 v36, v34, s33
	v_lshlrev_b32_e32 v35, 1, v35
	v_add3_u32 v216, 16, v36, v35
	v_add_u32_e32 v177, 0x12000, v216
	v_add_u32_e32 v215, 0x1b000, v216
	v_and_b32_e32 v35, 31, v1
	v_and_or_b32 v34, v34, s17, v35
	v_and_b32_e32 v35, 0xdf, v1
	v_lshrrev_b32_e32 v1, 1, v1
	v_and_b32_e32 v219, 16, v1
	v_mul_lo_u32 v218, v34, s33
	v_add_u32_e32 v1, 16, v219
	v_add_u32_e32 v171, v1, v218
	v_mad_u32_u24 v1, v35, s33, v1
	v_mul_u32_u24_e32 v217, 0x90, v35
	v_or_b32_e32 v178, 0xc0, v176
	v_mov_b32_e32 v179, v0
	s_add_i32 s6, 16, 0x12000
	s_add_i32 s7, 16, 0x1b000
	s_add_i32 s3, s3, s22
	s_waitcnt vmcnt(4)
	ds_write_b128 v216, v[14:17]
	s_waitcnt vmcnt(0)
	ds_write_b128 v216, v[30:33] offset:36864
	ds_write_b128 v216, v[10:13] offset:16
	ds_write_b128 v216, v[26:29] offset:36880
	ds_write_b128 v216, v[6:9] offset:32
	ds_write_b128 v216, v[22:25] offset:36896
	ds_write_b128 v216, v[2:5] offset:48
	ds_write_b128 v216, v[18:21] offset:36912
	v_or_b32_e32 v2, 64, v176
	v_mov_b32_e32 v3, v0
	v_lshl_add_u64 v[30:31], v[2:3], 1, s[8:9]
	global_load_dwordx4 v[2:5], v[174:175], off offset:176
	global_load_dwordx4 v[6:9], v[174:175], off offset:160
	global_load_dwordx4 v[10:13], v[174:175], off offset:144
	global_load_dwordx4 v[14:17], v[174:175], off offset:128
	global_load_dwordx4 v[18:21], v[30:31], off offset:48
	global_load_dwordx4 v[22:25], v[30:31], off offset:32
	global_load_dwordx4 v[26:29], v[30:31], off offset:16
	s_nop 0
	global_load_dwordx4 v[30:33], v[30:31], off
	s_waitcnt lgkmcnt(0)
	s_barrier
	s_waitcnt vmcnt(4)
	ds_write_b128 v177, v[14:17]
	s_waitcnt vmcnt(0)
	ds_write_b128 v215, v[30:33]
	ds_write_b128 v177, v[10:13] offset:16
	ds_write_b128 v215, v[26:29] offset:16
	ds_write_b128 v177, v[6:9] offset:32
	ds_write_b128 v215, v[22:25] offset:32
	ds_write_b128 v177, v[2:5] offset:48
	ds_write_b128 v215, v[18:21] offset:48
	v_or_b32_e32 v2, 0x80, v176
	v_mov_b32_e32 v3, v0
	v_lshl_add_u64 v[2:3], v[2:3], 1, s[8:9]
	global_load_dwordx4 v[130:133], v[2:3], off offset:48
	global_load_dwordx4 v[134:137], v[2:3], off offset:32
	global_load_dwordx4 v[142:145], v[2:3], off offset:16
	global_load_dwordx4 v[150:153], v[2:3], off
	global_load_dwordx4 v[138:141], v[174:175], off offset:304
	global_load_dwordx4 v[146:149], v[174:175], off offset:288
	global_load_dwordx4 v[154:157], v[174:175], off offset:272
	global_load_dwordx4 v[158:161], v[174:175], off offset:256
	ds_read_b128 v[2:5], v171 offset:4608
	ds_read_b128 v[6:9], v171 offset:9216
	ds_read_b128 v[18:21], v171 offset:13824
	ds_read_b128 v[22:25], v1 offset:41472
	ds_read_b128 v[10:13], v171
	ds_read_b128 v[162:165], v171 offset:32
	ds_read_b128 v[14:17], v1 offset:36864
	ds_read_b128 v[200:203], v1 offset:36896
	s_waitcnt lgkmcnt(1)
	v_mfma_f32_32x32x16_f16 v[98:113], v[14:17], v[10:13], 0
	ds_read_b128 v[220:223], v171 offset:4640
	ds_read_b128 v[224:227], v171 offset:9248
	ds_read_b128 v[228:231], v171 offset:13856
	ds_read_b128 v[232:235], v1 offset:41504
	v_mfma_f32_32x32x16_f16 v[114:129], v[22:25], v[10:13], 0
	v_mfma_f32_32x32x16_f16 v[66:81], v[14:17], v[2:5], 0
	v_mfma_f32_32x32x16_f16 v[82:97], v[22:25], v[2:5], 0
	v_mfma_f32_32x32x16_f16 v[34:49], v[14:17], v[6:9], 0
	v_mfma_f32_32x32x16_f16 v[50:65], v[22:25], v[6:9], 0
	v_mfma_f32_32x32x16_f16 v[2:17], v[14:17], v[18:21], 0
	v_mfma_f32_32x32x16_f16 v[18:33], v[22:25], v[18:21], 0
	s_waitcnt lgkmcnt(4)
	v_mfma_f32_32x32x16_f16 v[98:113], v[200:203], v[162:165], v[98:113]
	s_waitcnt lgkmcnt(0)
	v_mfma_f32_32x32x16_f16 v[114:129], v[232:235], v[162:165], v[114:129]
	v_mfma_f32_32x32x16_f16 v[66:81], v[200:203], v[220:223], v[66:81]
	v_mfma_f32_32x32x16_f16 v[82:97], v[232:235], v[220:223], v[82:97]
	v_mfma_f32_32x32x16_f16 v[34:49], v[200:203], v[224:227], v[34:49]
	v_mfma_f32_32x32x16_f16 v[50:65], v[232:235], v[224:227], v[50:65]
	v_mfma_f32_32x32x16_f16 v[2:17], v[200:203], v[228:231], v[2:17]
	v_mfma_f32_32x32x16_f16 v[18:33], v[232:235], v[228:231], v[18:33]
	ds_read_b128 v[162:165], v171 offset:64
	ds_read_b128 v[200:203], v171 offset:4672
	ds_read_b128 v[220:223], v171 offset:9280
	ds_read_b128 v[224:227], v171 offset:13888
	ds_read_b128 v[228:231], v1 offset:36928
	ds_read_b128 v[232:235], v1 offset:41536
	s_waitcnt lgkmcnt(1)
	v_mfma_f32_32x32x16_f16 v[98:113], v[228:231], v[162:165], v[98:113]
	s_waitcnt lgkmcnt(0)
	v_mfma_f32_32x32x16_f16 v[114:129], v[232:235], v[162:165], v[114:129]
	v_mfma_f32_32x32x16_f16 v[66:81], v[228:231], v[200:203], v[66:81]
	v_mfma_f32_32x32x16_f16 v[82:97], v[232:235], v[200:203], v[82:97]
	v_mfma_f32_32x32x16_f16 v[34:49], v[228:231], v[220:223], v[34:49]
	v_mfma_f32_32x32x16_f16 v[50:65], v[232:235], v[220:223], v[50:65]
	v_mfma_f32_32x32x16_f16 v[2:17], v[228:231], v[224:227], v[2:17]
	v_mfma_f32_32x32x16_f16 v[18:33], v[232:235], v[224:227], v[18:33]
	ds_read_b128 v[162:165], v171 offset:96
	ds_read_b128 v[200:203], v171 offset:4704
	ds_read_b128 v[220:223], v171 offset:9312
	ds_read_b128 v[224:227], v171 offset:13920
	ds_read_b128 v[228:231], v1 offset:36960
	ds_read_b128 v[232:235], v1 offset:41568
	s_waitcnt lgkmcnt(0)
	s_barrier
; DI f16v mfma32(h8v a, h8v b, f16v c) { return __builtin_amdgcn_mfma_f32_32x32x16_f16(a, b, c, 0, 0, 0); }
; template <bool GATHER>
; DI void gemm256_main(const h16* __restrict__ A, int lda, const int* __restrict__ idx, int m0,
;                      const h16* __restrict__ B, int ldb, int n0, int K, h16* lds, f16v (&acc)[4][2]) {
;     ...
;   for (int kt = 0; kt < nk; ++kt) {
;     const h16* As = lds + (kt & 1) * (512 * LDH);
;     const h16* Bs = As + 256 * LDH;
;     h16* Wn = lds + ((kt & 1) ^ 1) * (512 * LDH);
;     if (kt + 1 < nk) {
; #pragma unroll
;       for (int i = 0; i < 4; ++i) { *(u4v*)&Wn[lr * LDH + lc + 8 * i] = ra[i]; *(u4v*)&Wn[(256 + lr) * LDH + lc + 8 * i] = rb[i]; }
;     }
;     if (kt + 2 < nk) {
; #pragma unroll
;       for (int i = 0; i < 4; ++i) { ra[i] = *(const u4v*)(AP_ + 8 * i); rb[i] = *(const u4v*)(BP_ + 8 * i); }
;       ao += 64; bo += 64;
;     }
; #pragma unroll
;     for (int ks = 0; ks < 4; ++ks) {
;       h8v af[4], bf[2];
; #pragma unroll
;       for (int i = 0; i < 4; ++i) af[i] = *(const h8v*)&As[(wm * 128 + i * 32 + (lane & 31)) * LDH + ks * 16 + 8 * (lane >> 5)];
; #pragma unroll
;       for (int j = 0; j < 2; ++j) bf[j] = *(const h8v*)&Bs[(wn * 64 + j * 32 + (lane & 31)) * LDH + ks * 16 + 8 * (lane >> 5)];
; #pragma unroll
;       for (int i = 0; i < 4; ++i)
; #pragma unroll
;         for (int j = 0; j < 2; ++j) acc[i][j] = mfma32(bf[j], af[i], acc[i][j]);
;     }
;     __syncthreads();
;   }
	s_waitcnt vmcnt(0)
	ds_write_b128 v216, v[158:161]
	ds_write_b128 v216, v[150:153] offset:36864
	ds_write_b128 v216, v[154:157] offset:16
	ds_write_b128 v216, v[142:145] offset:36880
	ds_write_b128 v216, v[146:149] offset:32
	ds_write_b128 v216, v[134:137] offset:36896
	ds_write_b128 v216, v[138:141] offset:48
	ds_write_b128 v216, v[130:133] offset:36912
	v_lshl_add_u64 v[138:139], v[178:179], 1, s[8:9]
	global_load_dwordx4 v[130:133], v[138:139], off offset:48
	global_load_dwordx4 v[134:137], v[138:139], off offset:32
	global_load_dwordx4 v[142:145], v[138:139], off offset:16
	global_load_dwordx4 v[150:153], v[138:139], off
	s_nop 0
	global_load_dwordx4 v[138:141], v[174:175], off offset:432
	global_load_dwordx4 v[146:149], v[174:175], off offset:416
	global_load_dwordx4 v[154:157], v[174:175], off offset:400
	global_load_dwordx4 v[158:161], v[174:175], off offset:384
	v_mfma_f32_32x32x16_f16 v[98:113], v[228:231], v[162:165], v[98:113]
	v_add3_u32 v178, s6, v219, v218
	v_add3_u32 v179, s7, v219, v217
	v_mfma_f32_32x32x16_f16 v[114:129], v[232:235], v[162:165], v[114:129]
	v_or_b32_e32 v162, 0x100, v176
	v_mov_b32_e32 v163, v0
	v_or_b32_e32 v164, 0x140, v176
	v_mov_b32_e32 v165, v0
	v_mfma_f32_32x32x16_f16 v[66:81], v[228:231], v[200:203], v[66:81]
	v_mfma_f32_32x32x16_f16 v[82:97], v[232:235], v[200:203], v[82:97]
	v_mfma_f32_32x32x16_f16 v[34:49], v[228:231], v[220:223], v[34:49]
	v_mfma_f32_32x32x16_f16 v[50:65], v[232:235], v[220:223], v[50:65]
	v_mfma_f32_32x32x16_f16 v[2:17], v[228:231], v[224:227], v[2:17]
	v_mfma_f32_32x32x16_f16 v[18:33], v[232:235], v[224:227], v[18:33]
	ds_read_b128 v[200:203], v178 offset:4608
	ds_read_b128 v[220:223], v178 offset:9216
	ds_read_b128 v[224:227], v178 offset:13824
	ds_read_b128 v[228:231], v179 offset:4608
	ds_read_b128 v[232:235], v178
	ds_read_b128 v[236:239], v178 offset:32
	ds_read_b128 v[240:243], v179
	ds_read_b128 v[244:247], v179 offset:32
	s_waitcnt lgkmcnt(1)
	v_mfma_f32_32x32x16_f16 v[98:113], v[240:243], v[232:235], v[98:113]
	v_mfma_f32_32x32x16_f16 v[114:129], v[228:231], v[232:235], v[114:129]
	v_mfma_f32_32x32x16_f16 v[66:81], v[240:243], v[200:203], v[66:81]
	v_mfma_f32_32x32x16_f16 v[82:97], v[228:231], v[200:203], v[82:97]
	v_mfma_f32_32x32x16_f16 v[34:49], v[240:243], v[220:223], v[34:49]
	v_mfma_f32_32x32x16_f16 v[50:65], v[228:231], v[220:223], v[50:65]
	v_mfma_f32_32x32x16_f16 v[2:17], v[240:243], v[224:227], v[2:17]
	v_mfma_f32_32x32x16_f16 v[18:33], v[228:231], v[224:227], v[18:33]
	ds_read_b128 v[200:203], v178 offset:4640
	ds_read_b128 v[218:221], v178 offset:9248
	ds_read_b128 v[222:225], v178 offset:13856
	ds_read_b128 v[226:229], v179 offset:4640
	s_waitcnt lgkmcnt(4)
	v_mfma_f32_32x32x16_f16 v[98:113], v[244:247], v[236:239], v[98:113]
	s_waitcnt lgkmcnt(0)
	v_mfma_f32_32x32x16_f16 v[114:129], v[226:229], v[236:239], v[114:129]
	v_mfma_f32_32x32x16_f16 v[66:81], v[244:247], v[200:203], v[66:81]
	v_mfma_f32_32x32x16_f16 v[82:97], v[226:229], v[200:203], v[82:97]
	v_mfma_f32_32x32x16_f16 v[34:49], v[244:247], v[218:221], v[34:49]
	v_mfma_f32_32x32x16_f16 v[50:65], v[226:229], v[218:221], v[50:65]
	v_mfma_f32_32x32x16_f16 v[2:17], v[244:247], v[222:225], v[2:17]
	v_mfma_f32_32x32x16_f16 v[18:33], v[226:229], v[222:225], v[18:33]
	ds_read_b128 v[200:203], v178 offset:64
	ds_read_b128 v[218:221], v178 offset:4672
	ds_read_b128 v[222:225], v178 offset:9280
	ds_read_b128 v[226:229], v178 offset:13888
	ds_read_b128 v[230:233], v179 offset:64
	ds_read_b128 v[234:237], v179 offset:4672
	s_waitcnt lgkmcnt(1)
	v_mfma_f32_32x32x16_f16 v[98:113], v[230:233], v[200:203], v[98:113]
	s_waitcnt lgkmcnt(0)
	v_mfma_f32_32x32x16_f16 v[114:129], v[234:237], v[200:203], v[114:129]
	v_mfma_f32_32x32x16_f16 v[66:81], v[230:233], v[218:221], v[66:81]
	v_mfma_f32_32x32x16_f16 v[82:97], v[234:237], v[218:221], v[82:97]
	v_mfma_f32_32x32x16_f16 v[34:49], v[230:233], v[222:225], v[34:49]
	v_mfma_f32_32x32x16_f16 v[50:65], v[234:237], v[222:225], v[50:65]
	v_mfma_f32_32x32x16_f16 v[2:17], v[230:233], v[226:229], v[2:17]
	v_mfma_f32_32x32x16_f16 v[18:33], v[234:237], v[226:229], v[18:33]
	ds_read_b128 v[200:203], v178 offset:96
	ds_read_b128 v[218:221], v178 offset:4704
	ds_read_b128 v[222:225], v178 offset:9312
	ds_read_b128 v[226:229], v178 offset:13920
	ds_read_b128 v[230:233], v179 offset:96
	ds_read_b128 v[234:237], v179 offset:4704
	s_waitcnt lgkmcnt(0)
	s_barrier
; DI f16v mfma32(h8v a, h8v b, f16v c) { return __builtin_amdgcn_mfma_f32_32x32x16_f16(a, b, c, 0, 0, 0); }
; template <bool GATHER>
; DI void gemm256_main(const h16* __restrict__ A, int lda, const int* __restrict__ idx, int m0,
;                      const h16* __restrict__ B, int ldb, int n0, int K, h16* lds, f16v (&acc)[4][2]) {
;     ...
;   for (int kt = 0; kt < nk; ++kt) {
;     const h16* As = lds + (kt & 1) * (512 * LDH);
;     const h16* Bs = As + 256 * LDH;
;     h16* Wn = lds + ((kt & 1) ^ 1) * (512 * LDH);
;     if (kt + 1 < nk) {
; #pragma unroll
;       for (int i = 0; i < 4; ++i) { *(u4v*)&Wn[lr * LDH + lc + 8 * i] = ra[i]; *(u4v*)&Wn[(256 + lr) * LDH + lc + 8 * i] = rb[i]; }
;     }
;     if (kt + 2 < nk) {
; #pragma unroll
;       for (int i = 0; i < 4; ++i) { ra[i] = *(const u4v*)(AP_ + 8 * i); rb[i] = *(const u4v*)(BP_ + 8 * i); }
;       ao += 64; bo += 64;
;     }
; #pragma unroll
;     for (int ks = 0; ks < 4; ++ks) {
;       h8v af[4], bf[2];
; #pragma unroll
;       for (int i = 0; i < 4; ++i) af[i] = *(const h8v*)&As[(wm * 128 + i * 32 + (lane & 31)) * LDH + ks * 16 + 8 * (lane >> 5)];
; #pragma unroll
;       for (int j = 0; j < 2; ++j) bf[j] = *(const h8v*)&Bs[(wn * 64 + j * 32 + (lane & 31)) * LDH + ks * 16 + 8 * (lane >> 5)];
; #pragma unroll
;       for (int i = 0; i < 4; ++i)
; #pragma unroll
;         for (int j = 0; j < 2; ++j) acc[i][j] = mfma32(bf[j], af[i], acc[i][j]);
;     }
;     __syncthreads();
;   }
	s_waitcnt vmcnt(0)
	ds_write_b128 v177, v[158:161]
	ds_write_b128 v215, v[150:153]
	ds_write_b128 v177, v[154:157] offset:16
	ds_write_b128 v215, v[142:145] offset:16
	ds_write_b128 v177, v[146:149] offset:32
	ds_write_b128 v215, v[134:137] offset:32
	ds_write_b128 v177, v[138:141] offset:48
	ds_write_b128 v215, v[130:133] offset:48
	v_lshl_add_u64 v[138:139], v[162:163], 1, s[8:9]
	global_load_dwordx4 v[130:133], v[138:139], off offset:48
	global_load_dwordx4 v[134:137], v[138:139], off offset:32
	global_load_dwordx4 v[142:145], v[138:139], off offset:16
	global_load_dwordx4 v[150:153], v[138:139], off
	s_nop 0
	global_load_dwordx4 v[138:141], v[174:175], off offset:560
	global_load_dwordx4 v[146:149], v[174:175], off offset:544
	global_load_dwordx4 v[154:157], v[174:175], off offset:528
	global_load_dwordx4 v[158:161], v[174:175], off offset:512
	v_mfma_f32_32x32x16_f16 v[98:113], v[230:233], v[200:203], v[98:113]
	v_or_b32_e32 v162, 0x180, v176
	v_mfma_f32_32x32x16_f16 v[114:129], v[234:237], v[200:203], v[114:129]
	v_mfma_f32_32x32x16_f16 v[66:81], v[230:233], v[218:221], v[66:81]
	v_mfma_f32_32x32x16_f16 v[82:97], v[234:237], v[218:221], v[82:97]
	v_mfma_f32_32x32x16_f16 v[34:49], v[230:233], v[222:225], v[34:49]
	v_mfma_f32_32x32x16_f16 v[50:65], v[234:237], v[222:225], v[50:65]
	v_mfma_f32_32x32x16_f16 v[2:17], v[230:233], v[226:229], v[2:17]
	v_mfma_f32_32x32x16_f16 v[18:33], v[234:237], v[226:229], v[18:33]
	ds_read_b128 v[200:203], v171 offset:4608
	ds_read_b128 v[218:221], v171 offset:9216
	ds_read_b128 v[222:225], v171 offset:13824
	ds_read_b128 v[226:229], v1 offset:41472
	ds_read_b128 v[230:233], v171
	ds_read_b128 v[234:237], v171 offset:32
	ds_read_b128 v[238:241], v1 offset:36864
	ds_read_b128 v[242:245], v1 offset:36896
	s_waitcnt lgkmcnt(1)
	v_mfma_f32_32x32x16_f16 v[98:113], v[238:241], v[230:233], v[98:113]
	v_mfma_f32_32x32x16_f16 v[114:129], v[226:229], v[230:233], v[114:129]
	v_mfma_f32_32x32x16_f16 v[66:81], v[238:241], v[200:203], v[66:81]
	v_mfma_f32_32x32x16_f16 v[82:97], v[226:229], v[200:203], v[82:97]
	v_mfma_f32_32x32x16_f16 v[34:49], v[238:241], v[218:221], v[34:49]
	v_mfma_f32_32x32x16_f16 v[50:65], v[226:229], v[218:221], v[50:65]
	v_mfma_f32_32x32x16_f16 v[2:17], v[238:241], v[222:225], v[2:17]
	v_mfma_f32_32x32x16_f16 v[18:33], v[226:229], v[222:225], v[18:33]
	ds_read_b128 v[200:203], v171 offset:4640
	ds_read_b128 v[218:221], v171 offset:9248
	ds_read_b128 v[222:225], v171 offset:13856
	ds_read_b128 v[226:229], v1 offset:41504
	s_waitcnt lgkmcnt(4)
	v_mfma_f32_32x32x16_f16 v[98:113], v[242:245], v[234:237], v[98:113]
	s_waitcnt lgkmcnt(0)
	v_mfma_f32_32x32x16_f16 v[114:129], v[226:229], v[234:237], v[114:129]
	v_mfma_f32_32x32x16_f16 v[66:81], v[242:245], v[200:203], v[66:81]
	v_mfma_f32_32x32x16_f16 v[82:97], v[226:229], v[200:203], v[82:97]
	v_mfma_f32_32x32x16_f16 v[34:49], v[242:245], v[218:221], v[34:49]
	v_mfma_f32_32x32x16_f16 v[50:65], v[226:229], v[218:221], v[50:65]
	v_mfma_f32_32x32x16_f16 v[2:17], v[242:245], v[222:225], v[2:17]
	v_mfma_f32_32x32x16_f16 v[18:33], v[226:229], v[222:225], v[18:33]
	ds_read_b128 v[200:203], v171 offset:64
	ds_read_b128 v[218:221], v171 offset:4672
	ds_read_b128 v[222:225], v171 offset:9280
	ds_read_b128 v[226:229], v171 offset:13888
	ds_read_b128 v[230:233], v1 offset:36928
	ds_read_b128 v[234:237], v1 offset:41536
	s_waitcnt lgkmcnt(1)
	v_mfma_f32_32x32x16_f16 v[98:113], v[230:233], v[200:203], v[98:113]
	s_waitcnt lgkmcnt(0)
	v_mfma_f32_32x32x16_f16 v[114:129], v[234:237], v[200:203], v[114:129]
	v_mfma_f32_32x32x16_f16 v[66:81], v[230:233], v[218:221], v[66:81]
	v_mfma_f32_32x32x16_f16 v[82:97], v[234:237], v[218:221], v[82:97]
	v_mfma_f32_32x32x16_f16 v[34:49], v[230:233], v[222:225], v[34:49]
	v_mfma_f32_32x32x16_f16 v[50:65], v[234:237], v[222:225], v[50:65]
	v_mfma_f32_32x32x16_f16 v[2:17], v[230:233], v[226:229], v[2:17]
	v_mfma_f32_32x32x16_f16 v[18:33], v[234:237], v[226:229], v[18:33]
	ds_read_b128 v[200:203], v171 offset:96
	ds_read_b128 v[218:221], v171 offset:4704
	ds_read_b128 v[222:225], v171 offset:9312
	ds_read_b128 v[226:229], v171 offset:13920
	ds_read_b128 v[230:233], v1 offset:36960
	ds_read_b128 v[234:237], v1 offset:41568
	s_waitcnt lgkmcnt(0)
	s_barrier
; DI f16v mfma32(h8v a, h8v b, f16v c) { return __builtin_amdgcn_mfma_f32_32x32x16_f16(a, b, c, 0, 0, 0); }
; template <bool GATHER>
; DI void gemm256_main(const h16* __restrict__ A, int lda, const int* __restrict__ idx, int m0,
;                      const h16* __restrict__ B, int ldb, int n0, int K, h16* lds, f16v (&acc)[4][2]) {
;     ...
;   for (int kt = 0; kt < nk; ++kt) {
;     const h16* As = lds + (kt & 1) * (512 * LDH);
;     const h16* Bs = As + 256 * LDH;
;     h16* Wn = lds + ((kt & 1) ^ 1) * (512 * LDH);
;     if (kt + 1 < nk) {
; #pragma unroll
;       for (int i = 0; i < 4; ++i) { *(u4v*)&Wn[lr * LDH + lc + 8 * i] = ra[i]; *(u4v*)&Wn[(256 + lr) * LDH + lc + 8 * i] = rb[i]; }
;     }
;     if (kt + 2 < nk) {
; #pragma unroll
;       for (int i = 0; i < 4; ++i) { ra[i] = *(const u4v*)(AP_ + 8 * i); rb[i] = *(const u4v*)(BP_ + 8 * i); }
;       ao += 64; bo += 64;
;     }
; #pragma unroll
;     for (int ks = 0; ks < 4; ++ks) {
;       h8v af[4], bf[2];
; #pragma unroll
;       for (int i = 0; i < 4; ++i) af[i] = *(const h8v*)&As[(wm * 128 + i * 32 + (lane & 31)) * LDH + ks * 16 + 8 * (lane >> 5)];
; #pragma unroll
;       for (int j = 0; j < 2; ++j) bf[j] = *(const h8v*)&Bs[(wn * 64 + j * 32 + (lane & 31)) * LDH + ks * 16 + 8 * (lane >> 5)];
; #pragma unroll
;       for (int i = 0; i < 4; ++i)
; #pragma unroll
;         for (int j = 0; j < 2; ++j) acc[i][j] = mfma32(bf[j], af[i], acc[i][j]);
;     }
;     __syncthreads();
;   }
	s_waitcnt vmcnt(0)
	ds_write_b128 v216, v[158:161]
	ds_write_b128 v216, v[150:153] offset:36864
	ds_write_b128 v216, v[154:157] offset:16
	ds_write_b128 v216, v[142:145] offset:36880
	ds_write_b128 v216, v[146:149] offset:32
	ds_write_b128 v216, v[134:137] offset:36896
	ds_write_b128 v216, v[138:141] offset:48
	ds_write_b128 v216, v[130:133] offset:36912
	v_lshl_add_u64 v[138:139], v[164:165], 1, s[8:9]
	global_load_dwordx4 v[130:133], v[138:139], off offset:48
	global_load_dwordx4 v[134:137], v[138:139], off offset:32
	global_load_dwordx4 v[142:145], v[138:139], off offset:16
	global_load_dwordx4 v[150:153], v[138:139], off
	s_nop 0
	global_load_dwordx4 v[138:141], v[174:175], off offset:688
	global_load_dwordx4 v[146:149], v[174:175], off offset:672
	global_load_dwordx4 v[154:157], v[174:175], off offset:656
	global_load_dwordx4 v[158:161], v[174:175], off offset:640
	v_mfma_f32_32x32x16_f16 v[98:113], v[230:233], v[200:203], v[98:113]
	v_or_b32_e32 v164, 0x1c0, v176
	v_mfma_f32_32x32x16_f16 v[114:129], v[234:237], v[200:203], v[114:129]
	v_mfma_f32_32x32x16_f16 v[66:81], v[230:233], v[218:221], v[66:81]
	v_mfma_f32_32x32x16_f16 v[82:97], v[234:237], v[218:221], v[82:97]
	v_mfma_f32_32x32x16_f16 v[34:49], v[230:233], v[222:225], v[34:49]
	v_mfma_f32_32x32x16_f16 v[50:65], v[234:237], v[222:225], v[50:65]
	v_mfma_f32_32x32x16_f16 v[2:17], v[230:233], v[226:229], v[2:17]
	v_mfma_f32_32x32x16_f16 v[18:33], v[234:237], v[226:229], v[18:33]
	ds_read_b128 v[200:203], v178 offset:4608
	ds_read_b128 v[218:221], v178 offset:9216
	ds_read_b128 v[222:225], v178 offset:13824
	ds_read_b128 v[226:229], v179 offset:4608
	ds_read_b128 v[230:233], v178
	ds_read_b128 v[234:237], v178 offset:32
	ds_read_b128 v[238:241], v179
	ds_read_b128 v[242:245], v179 offset:32
	s_waitcnt lgkmcnt(1)
	v_mfma_f32_32x32x16_f16 v[98:113], v[238:241], v[230:233], v[98:113]
	v_mfma_f32_32x32x16_f16 v[114:129], v[226:229], v[230:233], v[114:129]
	v_mfma_f32_32x32x16_f16 v[66:81], v[238:241], v[200:203], v[66:81]
	v_mfma_f32_32x32x16_f16 v[82:97], v[226:229], v[200:203], v[82:97]
	v_mfma_f32_32x32x16_f16 v[34:49], v[238:241], v[218:221], v[34:49]
	v_mfma_f32_32x32x16_f16 v[50:65], v[226:229], v[218:221], v[50:65]
	v_mfma_f32_32x32x16_f16 v[2:17], v[238:241], v[222:225], v[2:17]
	v_mfma_f32_32x32x16_f16 v[18:33], v[226:229], v[222:225], v[18:33]
	ds_read_b128 v[200:203], v178 offset:4640
	ds_read_b128 v[218:221], v178 offset:9248
	ds_read_b128 v[222:225], v178 offset:13856
	ds_read_b128 v[226:229], v179 offset:4640
	s_waitcnt lgkmcnt(4)
	v_mfma_f32_32x32x16_f16 v[98:113], v[242:245], v[234:237], v[98:113]
	s_waitcnt lgkmcnt(0)
	v_mfma_f32_32x32x16_f16 v[114:129], v[226:229], v[234:237], v[114:129]
	v_mfma_f32_32x32x16_f16 v[66:81], v[242:245], v[200:203], v[66:81]
	v_mfma_f32_32x32x16_f16 v[82:97], v[226:229], v[200:203], v[82:97]
	v_mfma_f32_32x32x16_f16 v[34:49], v[242:245], v[218:221], v[34:49]
	v_mfma_f32_32x32x16_f16 v[50:65], v[226:229], v[218:221], v[50:65]
	v_mfma_f32_32x32x16_f16 v[2:17], v[242:245], v[222:225], v[2:17]
	v_mfma_f32_32x32x16_f16 v[18:33], v[226:229], v[222:225], v[18:33]
	ds_read_b128 v[200:203], v178 offset:64
	ds_read_b128 v[218:221], v178 offset:4672
	ds_read_b128 v[222:225], v178 offset:9280
	ds_read_b128 v[226:229], v178 offset:13888
	ds_read_b128 v[230:233], v179 offset:64
	ds_read_b128 v[234:237], v179 offset:4672
	s_waitcnt lgkmcnt(1)
	v_mfma_f32_32x32x16_f16 v[98:113], v[230:233], v[200:203], v[98:113]
	s_waitcnt lgkmcnt(0)
	v_mfma_f32_32x32x16_f16 v[114:129], v[234:237], v[200:203], v[114:129]
	v_mfma_f32_32x32x16_f16 v[66:81], v[230:233], v[218:221], v[66:81]
	v_mfma_f32_32x32x16_f16 v[82:97], v[234:237], v[218:221], v[82:97]
	v_mfma_f32_32x32x16_f16 v[34:49], v[230:233], v[222:225], v[34:49]
	v_mfma_f32_32x32x16_f16 v[50:65], v[234:237], v[222:225], v[50:65]
	v_mfma_f32_32x32x16_f16 v[2:17], v[230:233], v[226:229], v[2:17]
	v_mfma_f32_32x32x16_f16 v[18:33], v[234:237], v[226:229], v[18:33]
	ds_read_b128 v[200:203], v178 offset:96
	ds_read_b128 v[218:221], v178 offset:4704
	ds_read_b128 v[222:225], v178 offset:9312
	ds_read_b128 v[226:229], v178 offset:13920
	ds_read_b128 v[230:233], v179 offset:96
	ds_read_b128 v[234:237], v179 offset:4704
	s_waitcnt lgkmcnt(0)
	s_barrier
; DI f16v mfma32(h8v a, h8v b, f16v c) { return __builtin_amdgcn_mfma_f32_32x32x16_f16(a, b, c, 0, 0, 0); }
; template <bool GATHER>
; DI void gemm256_main(const h16* __restrict__ A, int lda, const int* __restrict__ idx, int m0,
;                      const h16* __restrict__ B, int ldb, int n0, int K, h16* lds, f16v (&acc)[4][2]) {
;     ...
;   for (int kt = 0; kt < nk; ++kt) {
;     const h16* As = lds + (kt & 1) * (512 * LDH);
;     const h16* Bs = As + 256 * LDH;
;     h16* Wn = lds + ((kt & 1) ^ 1) * (512 * LDH);
;     if (kt + 1 < nk) {
; #pragma unroll
;       for (int i = 0; i < 4; ++i) { *(u4v*)&Wn[lr * LDH + lc + 8 * i] = ra[i]; *(u4v*)&Wn[(256 + lr) * LDH + lc + 8 * i] = rb[i]; }
;     }
;     if (kt + 2 < nk) {
; #pragma unroll
;       for (int i = 0; i < 4; ++i) { ra[i] = *(const u4v*)(AP_ + 8 * i); rb[i] = *(const u4v*)(BP_ + 8 * i); }
;       ao += 64; bo += 64;
;     }
; #pragma unroll
;     for (int ks = 0; ks < 4; ++ks) {
;       h8v af[4], bf[2];
; #pragma unroll
;       for (int i = 0; i < 4; ++i) af[i] = *(const h8v*)&As[(wm * 128 + i * 32 + (lane & 31)) * LDH + ks * 16 + 8 * (lane >> 5)];
; #pragma unroll
;       for (int j = 0; j < 2; ++j) bf[j] = *(const h8v*)&Bs[(wn * 64 + j * 32 + (lane & 31)) * LDH + ks * 16 + 8 * (lane >> 5)];
; #pragma unroll
;       for (int i = 0; i < 4; ++i)
; #pragma unroll
;         for (int j = 0; j < 2; ++j) acc[i][j] = mfma32(bf[j], af[i], acc[i][j]);
;     }
;     __syncthreads();
;   }
	s_waitcnt vmcnt(0)
	ds_write_b128 v177, v[158:161]
	ds_write_b128 v215, v[150:153]
	ds_write_b128 v177, v[154:157] offset:16
	ds_write_b128 v215, v[142:145] offset:16
	ds_write_b128 v177, v[146:149] offset:32
	ds_write_b128 v215, v[134:137] offset:32
	ds_write_b128 v177, v[138:141] offset:48
	ds_write_b128 v215, v[130:133] offset:48
	v_lshl_add_u64 v[138:139], v[162:163], 1, s[8:9]
	global_load_dwordx4 v[130:133], v[138:139], off offset:48
	global_load_dwordx4 v[134:137], v[138:139], off offset:32
	global_load_dwordx4 v[142:145], v[138:139], off offset:16
	global_load_dwordx4 v[150:153], v[138:139], off
	s_nop 0
	global_load_dwordx4 v[138:141], v[174:175], off offset:816
	global_load_dwordx4 v[146:149], v[174:175], off offset:800
	global_load_dwordx4 v[154:157], v[174:175], off offset:784
	global_load_dwordx4 v[158:161], v[174:175], off offset:768
	v_mfma_f32_32x32x16_f16 v[98:113], v[230:233], v[200:203], v[98:113]
	v_or_b32_e32 v162, 0x200, v176
	v_mfma_f32_32x32x16_f16 v[114:129], v[234:237], v[200:203], v[114:129]
	v_mfma_f32_32x32x16_f16 v[66:81], v[230:233], v[218:221], v[66:81]
	v_mfma_f32_32x32x16_f16 v[82:97], v[234:237], v[218:221], v[82:97]
	v_mfma_f32_32x32x16_f16 v[34:49], v[230:233], v[222:225], v[34:49]
	v_mfma_f32_32x32x16_f16 v[50:65], v[234:237], v[222:225], v[50:65]
	v_mfma_f32_32x32x16_f16 v[2:17], v[230:233], v[226:229], v[2:17]
	v_mfma_f32_32x32x16_f16 v[18:33], v[234:237], v[226:229], v[18:33]
	ds_read_b128 v[200:203], v171 offset:4608
	ds_read_b128 v[218:221], v171 offset:9216
	ds_read_b128 v[222:225], v171 offset:13824
	ds_read_b128 v[226:229], v1 offset:41472
	ds_read_b128 v[230:233], v171
	ds_read_b128 v[234:237], v171 offset:32
	ds_read_b128 v[238:241], v1 offset:36864
	ds_read_b128 v[242:245], v1 offset:36896
	s_waitcnt lgkmcnt(1)
	v_mfma_f32_32x32x16_f16 v[98:113], v[238:241], v[230:233], v[98:113]
	v_mfma_f32_32x32x16_f16 v[114:129], v[226:229], v[230:233], v[114:129]
	v_mfma_f32_32x32x16_f16 v[66:81], v[238:241], v[200:203], v[66:81]
	v_mfma_f32_32x32x16_f16 v[82:97], v[226:229], v[200:203], v[82:97]
	v_mfma_f32_32x32x16_f16 v[34:49], v[238:241], v[218:221], v[34:49]
	v_mfma_f32_32x32x16_f16 v[50:65], v[226:229], v[218:221], v[50:65]
	v_mfma_f32_32x32x16_f16 v[2:17], v[238:241], v[222:225], v[2:17]
	v_mfma_f32_32x32x16_f16 v[18:33], v[226:229], v[222:225], v[18:33]
	ds_read_b128 v[200:203], v171 offset:4640
	ds_read_b128 v[218:221], v171 offset:9248
	ds_read_b128 v[222:225], v171 offset:13856
	ds_read_b128 v[226:229], v1 offset:41504
	s_waitcnt lgkmcnt(4)
	v_mfma_f32_32x32x16_f16 v[98:113], v[242:245], v[234:237], v[98:113]
	s_waitcnt lgkmcnt(0)
	v_mfma_f32_32x32x16_f16 v[114:129], v[226:229], v[234:237], v[114:129]
	v_mfma_f32_32x32x16_f16 v[66:81], v[242:245], v[200:203], v[66:81]
	v_mfma_f32_32x32x16_f16 v[82:97], v[226:229], v[200:203], v[82:97]
	v_mfma_f32_32x32x16_f16 v[34:49], v[242:245], v[218:221], v[34:49]
	v_mfma_f32_32x32x16_f16 v[50:65], v[226:229], v[218:221], v[50:65]
	v_mfma_f32_32x32x16_f16 v[2:17], v[242:245], v[222:225], v[2:17]
	v_mfma_f32_32x32x16_f16 v[18:33], v[226:229], v[222:225], v[18:33]
	ds_read_b128 v[200:203], v171 offset:64
	ds_read_b128 v[218:221], v171 offset:4672
	ds_read_b128 v[222:225], v171 offset:9280
	ds_read_b128 v[226:229], v171 offset:13888
	ds_read_b128 v[230:233], v1 offset:36928
	ds_read_b128 v[234:237], v1 offset:41536
	s_waitcnt lgkmcnt(1)
	v_mfma_f32_32x32x16_f16 v[98:113], v[230:233], v[200:203], v[98:113]
	s_waitcnt lgkmcnt(0)
	v_mfma_f32_32x32x16_f16 v[114:129], v[234:237], v[200:203], v[114:129]
	v_mfma_f32_32x32x16_f16 v[66:81], v[230:233], v[218:221], v[66:81]
	v_mfma_f32_32x32x16_f16 v[82:97], v[234:237], v[218:221], v[82:97]
	v_mfma_f32_32x32x16_f16 v[34:49], v[230:233], v[222:225], v[34:49]
	v_mfma_f32_32x32x16_f16 v[50:65], v[234:237], v[222:225], v[50:65]
	v_mfma_f32_32x32x16_f16 v[2:17], v[230:233], v[226:229], v[2:17]
	v_mfma_f32_32x32x16_f16 v[18:33], v[234:237], v[226:229], v[18:33]
	ds_read_b128 v[200:203], v171 offset:96
	ds_read_b128 v[218:221], v171 offset:4704
	ds_read_b128 v[222:225], v171 offset:9312
	ds_read_b128 v[226:229], v171 offset:13920
	ds_read_b128 v[230:233], v1 offset:36960
	ds_read_b128 v[234:237], v1 offset:41568
	s_waitcnt lgkmcnt(0)
	s_barrier
; DI f16v mfma32(h8v a, h8v b, f16v c) { return __builtin_amdgcn_mfma_f32_32x32x16_f16(a, b, c, 0, 0, 0); }
; template <bool GATHER>
; DI void gemm256_main(const h16* __restrict__ A, int lda, const int* __restrict__ idx, int m0,
;                      const h16* __restrict__ B, int ldb, int n0, int K, h16* lds, f16v (&acc)[4][2]) {
;     ...
;   for (int kt = 0; kt < nk; ++kt) {
;     const h16* As = lds + (kt & 1) * (512 * LDH);
;     const h16* Bs = As + 256 * LDH;
;     h16* Wn = lds + ((kt & 1) ^ 1) * (512 * LDH);
;     if (kt + 1 < nk) {
; #pragma unroll
;       for (int i = 0; i < 4; ++i) { *(u4v*)&Wn[lr * LDH + lc + 8 * i] = ra[i]; *(u4v*)&Wn[(256 + lr) * LDH + lc + 8 * i] = rb[i]; }
;     }
;     if (kt + 2 < nk) {
; #pragma unroll
;       for (int i = 0; i < 4; ++i) { ra[i] = *(const u4v*)(AP_ + 8 * i); rb[i] = *(const u4v*)(BP_ + 8 * i); }
;       ao += 64; bo += 64;
;     }
; #pragma unroll
;     for (int ks = 0; ks < 4; ++ks) {
;       h8v af[4], bf[2];
; #pragma unroll
;       for (int i = 0; i < 4; ++i) af[i] = *(const h8v*)&As[(wm * 128 + i * 32 + (lane & 31)) * LDH + ks * 16 + 8 * (lane >> 5)];
; #pragma unroll
;       for (int j = 0; j < 2; ++j) bf[j] = *(const h8v*)&Bs[(wn * 64 + j * 32 + (lane & 31)) * LDH + ks * 16 + 8 * (lane >> 5)];
; #pragma unroll
;       for (int i = 0; i < 4; ++i)
; #pragma unroll
;         for (int j = 0; j < 2; ++j) acc[i][j] = mfma32(bf[j], af[i], acc[i][j]);
;     }
;     __syncthreads();
;   }
	s_waitcnt vmcnt(0)
	ds_write_b128 v216, v[158:161]
	ds_write_b128 v216, v[150:153] offset:36864
	ds_write_b128 v216, v[154:157] offset:16
	ds_write_b128 v216, v[142:145] offset:36880
	ds_write_b128 v216, v[146:149] offset:32
	ds_write_b128 v216, v[134:137] offset:36896
	ds_write_b128 v216, v[138:141] offset:48
	ds_write_b128 v216, v[130:133] offset:36912
	v_lshl_add_u64 v[138:139], v[164:165], 1, s[8:9]
	global_load_dwordx4 v[130:133], v[138:139], off offset:48
	global_load_dwordx4 v[134:137], v[138:139], off offset:32
	global_load_dwordx4 v[142:145], v[138:139], off offset:16
	global_load_dwordx4 v[150:153], v[138:139], off
	s_nop 0
	global_load_dwordx4 v[138:141], v[174:175], off offset:944
	global_load_dwordx4 v[146:149], v[174:175], off offset:928
	global_load_dwordx4 v[154:157], v[174:175], off offset:912
	global_load_dwordx4 v[158:161], v[174:175], off offset:896
	v_mfma_f32_32x32x16_f16 v[98:113], v[230:233], v[200:203], v[98:113]
	v_or_b32_e32 v164, 0x240, v176
	v_mfma_f32_32x32x16_f16 v[114:129], v[234:237], v[200:203], v[114:129]
	v_mfma_f32_32x32x16_f16 v[66:81], v[230:233], v[218:221], v[66:81]
	v_mfma_f32_32x32x16_f16 v[82:97], v[234:237], v[218:221], v[82:97]
	v_mfma_f32_32x32x16_f16 v[34:49], v[230:233], v[222:225], v[34:49]
	v_mfma_f32_32x32x16_f16 v[50:65], v[234:237], v[222:225], v[50:65]
	v_mfma_f32_32x32x16_f16 v[2:17], v[230:233], v[226:229], v[2:17]
	v_mfma_f32_32x32x16_f16 v[18:33], v[234:237], v[226:229], v[18:33]
	ds_read_b128 v[200:203], v178 offset:4608
	ds_read_b128 v[218:221], v178 offset:9216
	ds_read_b128 v[222:225], v178 offset:13824
	ds_read_b128 v[226:229], v179 offset:4608
	ds_read_b128 v[230:233], v178
	ds_read_b128 v[234:237], v178 offset:32
	ds_read_b128 v[238:241], v179
	ds_read_b128 v[242:245], v179 offset:32
	s_waitcnt lgkmcnt(1)
	v_mfma_f32_32x32x16_f16 v[98:113], v[238:241], v[230:233], v[98:113]
	v_mfma_f32_32x32x16_f16 v[114:129], v[226:229], v[230:233], v[114:129]
	v_mfma_f32_32x32x16_f16 v[66:81], v[238:241], v[200:203], v[66:81]
	v_mfma_f32_32x32x16_f16 v[82:97], v[226:229], v[200:203], v[82:97]
	v_mfma_f32_32x32x16_f16 v[34:49], v[238:241], v[218:221], v[34:49]
	v_mfma_f32_32x32x16_f16 v[50:65], v[226:229], v[218:221], v[50:65]
	v_mfma_f32_32x32x16_f16 v[2:17], v[238:241], v[222:225], v[2:17]
	v_mfma_f32_32x32x16_f16 v[18:33], v[226:229], v[222:225], v[18:33]
	ds_read_b128 v[200:203], v178 offset:4640
	ds_read_b128 v[218:221], v178 offset:9248
	ds_read_b128 v[222:225], v178 offset:13856
	ds_read_b128 v[226:229], v179 offset:4640
	s_waitcnt lgkmcnt(4)
	v_mfma_f32_32x32x16_f16 v[98:113], v[242:245], v[234:237], v[98:113]
	s_waitcnt lgkmcnt(0)
	v_mfma_f32_32x32x16_f16 v[114:129], v[226:229], v[234:237], v[114:129]
	v_mfma_f32_32x32x16_f16 v[66:81], v[242:245], v[200:203], v[66:81]
	v_mfma_f32_32x32x16_f16 v[82:97], v[226:229], v[200:203], v[82:97]
	v_mfma_f32_32x32x16_f16 v[34:49], v[242:245], v[218:221], v[34:49]
	v_mfma_f32_32x32x16_f16 v[50:65], v[226:229], v[218:221], v[50:65]
	v_mfma_f32_32x32x16_f16 v[2:17], v[242:245], v[222:225], v[2:17]
	v_mfma_f32_32x32x16_f16 v[18:33], v[226:229], v[222:225], v[18:33]
	ds_read_b128 v[200:203], v178 offset:64
	ds_read_b128 v[218:221], v178 offset:4672
	ds_read_b128 v[222:225], v178 offset:9280
	ds_read_b128 v[226:229], v178 offset:13888
	ds_read_b128 v[230:233], v179 offset:64
	ds_read_b128 v[234:237], v179 offset:4672
	s_waitcnt lgkmcnt(1)
	v_mfma_f32_32x32x16_f16 v[98:113], v[230:233], v[200:203], v[98:113]
	s_waitcnt lgkmcnt(0)
	v_mfma_f32_32x32x16_f16 v[114:129], v[234:237], v[200:203], v[114:129]
	v_mfma_f32_32x32x16_f16 v[66:81], v[230:233], v[218:221], v[66:81]
	v_mfma_f32_32x32x16_f16 v[82:97], v[234:237], v[218:221], v[82:97]
	v_mfma_f32_32x32x16_f16 v[34:49], v[230:233], v[222:225], v[34:49]
	v_mfma_f32_32x32x16_f16 v[50:65], v[234:237], v[222:225], v[50:65]
	v_mfma_f32_32x32x16_f16 v[2:17], v[230:233], v[226:229], v[2:17]
	v_mfma_f32_32x32x16_f16 v[18:33], v[234:237], v[226:229], v[18:33]
	ds_read_b128 v[200:203], v178 offset:96
	ds_read_b128 v[218:221], v178 offset:4704
	ds_read_b128 v[222:225], v178 offset:9312
	ds_read_b128 v[226:229], v178 offset:13920
	ds_read_b128 v[230:233], v179 offset:96
	ds_read_b128 v[234:237], v179 offset:4704
	s_waitcnt lgkmcnt(0)
	s_barrier
; DI f16v mfma32(h8v a, h8v b, f16v c) { return __builtin_amdgcn_mfma_f32_32x32x16_f16(a, b, c, 0, 0, 0); }
; template <bool GATHER>
; DI void gemm256_main(const h16* __restrict__ A, int lda, const int* __restrict__ idx, int m0,
;                      const h16* __restrict__ B, int ldb, int n0, int K, h16* lds, f16v (&acc)[4][2]) {
;     ...
;   for (int kt = 0; kt < nk; ++kt) {
;     const h16* As = lds + (kt & 1) * (512 * LDH);
;     const h16* Bs = As + 256 * LDH;
;     h16* Wn = lds + ((kt & 1) ^ 1) * (512 * LDH);
;     if (kt + 1 < nk) {
; #pragma unroll
;       for (int i = 0; i < 4; ++i) { *(u4v*)&Wn[lr * LDH + lc + 8 * i] = ra[i]; *(u4v*)&Wn[(256 + lr) * LDH + lc + 8 * i] = rb[i]; }
;     }
;     if (kt + 2 < nk) {
; #pragma unroll
;       for (int i = 0; i < 4; ++i) { ra[i] = *(const u4v*)(AP_ + 8 * i); rb[i] = *(const u4v*)(BP_ + 8 * i); }
;       ao += 64; bo += 64;
;     }
; #pragma unroll
;     for (int ks = 0; ks < 4; ++ks) {
;       h8v af[4], bf[2];
; #pragma unroll
;       for (int i = 0; i < 4; ++i) af[i] = *(const h8v*)&As[(wm * 128 + i * 32 + (lane & 31)) * LDH + ks * 16 + 8 * (lane >> 5)];
; #pragma unroll
;       for (int j = 0; j < 2; ++j) bf[j] = *(const h8v*)&Bs[(wn * 64 + j * 32 + (lane & 31)) * LDH + ks * 16 + 8 * (lane >> 5)];
; #pragma unroll
;       for (int i = 0; i < 4; ++i)
; #pragma unroll
;         for (int j = 0; j < 2; ++j) acc[i][j] = mfma32(bf[j], af[i], acc[i][j]);
;     }
;     __syncthreads();
;   }
	s_waitcnt vmcnt(0)
	ds_write_b128 v177, v[158:161]
	ds_write_b128 v215, v[150:153]
	ds_write_b128 v177, v[154:157] offset:16
	ds_write_b128 v215, v[142:145] offset:16
	ds_write_b128 v177, v[146:149] offset:32
	ds_write_b128 v215, v[134:137] offset:32
	ds_write_b128 v177, v[138:141] offset:48
	ds_write_b128 v215, v[130:133] offset:48
	v_lshl_add_u64 v[138:139], v[162:163], 1, s[8:9]
	global_load_dwordx4 v[130:133], v[138:139], off offset:48
	global_load_dwordx4 v[134:137], v[138:139], off offset:32
	global_load_dwordx4 v[142:145], v[138:139], off offset:16
	global_load_dwordx4 v[150:153], v[138:139], off
	s_nop 0
	global_load_dwordx4 v[138:141], v[174:175], off offset:1072
	global_load_dwordx4 v[146:149], v[174:175], off offset:1056
	global_load_dwordx4 v[154:157], v[174:175], off offset:1040
	global_load_dwordx4 v[158:161], v[174:175], off offset:1024
	v_mfma_f32_32x32x16_f16 v[98:113], v[230:233], v[200:203], v[98:113]
	v_or_b32_e32 v162, 0x280, v176
	v_mfma_f32_32x32x16_f16 v[114:129], v[234:237], v[200:203], v[114:129]
	v_mfma_f32_32x32x16_f16 v[66:81], v[230:233], v[218:221], v[66:81]
	v_mfma_f32_32x32x16_f16 v[82:97], v[234:237], v[218:221], v[82:97]
	v_mfma_f32_32x32x16_f16 v[34:49], v[230:233], v[222:225], v[34:49]
	v_mfma_f32_32x32x16_f16 v[50:65], v[234:237], v[222:225], v[50:65]
	v_mfma_f32_32x32x16_f16 v[2:17], v[230:233], v[226:229], v[2:17]
	v_mfma_f32_32x32x16_f16 v[18:33], v[234:237], v[226:229], v[18:33]
	ds_read_b128 v[200:203], v171 offset:4608
	ds_read_b128 v[218:221], v171 offset:9216
	ds_read_b128 v[222:225], v171 offset:13824
	ds_read_b128 v[226:229], v1 offset:41472
	ds_read_b128 v[230:233], v171
	ds_read_b128 v[234:237], v171 offset:32
	ds_read_b128 v[238:241], v1 offset:36864
	ds_read_b128 v[242:245], v1 offset:36896
	s_waitcnt lgkmcnt(1)
	v_mfma_f32_32x32x16_f16 v[98:113], v[238:241], v[230:233], v[98:113]
	v_mfma_f32_32x32x16_f16 v[114:129], v[226:229], v[230:233], v[114:129]
	v_mfma_f32_32x32x16_f16 v[66:81], v[238:241], v[200:203], v[66:81]
	v_mfma_f32_32x32x16_f16 v[82:97], v[226:229], v[200:203], v[82:97]
	v_mfma_f32_32x32x16_f16 v[34:49], v[238:241], v[218:221], v[34:49]
	v_mfma_f32_32x32x16_f16 v[50:65], v[226:229], v[218:221], v[50:65]
	v_mfma_f32_32x32x16_f16 v[2:17], v[238:241], v[222:225], v[2:17]
	v_mfma_f32_32x32x16_f16 v[18:33], v[226:229], v[222:225], v[18:33]
	ds_read_b128 v[200:203], v171 offset:4640
	ds_read_b128 v[218:221], v171 offset:9248
	ds_read_b128 v[222:225], v171 offset:13856
	ds_read_b128 v[226:229], v1 offset:41504
	s_waitcnt lgkmcnt(4)
	v_mfma_f32_32x32x16_f16 v[98:113], v[242:245], v[234:237], v[98:113]
	s_waitcnt lgkmcnt(0)
	v_mfma_f32_32x32x16_f16 v[114:129], v[226:229], v[234:237], v[114:129]
	v_mfma_f32_32x32x16_f16 v[66:81], v[242:245], v[200:203], v[66:81]
	v_mfma_f32_32x32x16_f16 v[82:97], v[226:229], v[200:203], v[82:97]
	v_mfma_f32_32x32x16_f16 v[34:49], v[242:245], v[218:221], v[34:49]
	v_mfma_f32_32x32x16_f16 v[50:65], v[226:229], v[218:221], v[50:65]
	v_mfma_f32_32x32x16_f16 v[2:17], v[242:245], v[222:225], v[2:17]
	v_mfma_f32_32x32x16_f16 v[18:33], v[226:229], v[222:225], v[18:33]
	ds_read_b128 v[200:203], v171 offset:64
	ds_read_b128 v[218:221], v171 offset:4672
	ds_read_b128 v[222:225], v171 offset:9280
	ds_read_b128 v[226:229], v171 offset:13888
	ds_read_b128 v[230:233], v1 offset:36928
	ds_read_b128 v[234:237], v1 offset:41536
	s_waitcnt lgkmcnt(1)
	v_mfma_f32_32x32x16_f16 v[98:113], v[230:233], v[200:203], v[98:113]
	s_waitcnt lgkmcnt(0)
	v_mfma_f32_32x32x16_f16 v[114:129], v[234:237], v[200:203], v[114:129]
	v_mfma_f32_32x32x16_f16 v[66:81], v[230:233], v[218:221], v[66:81]
	v_mfma_f32_32x32x16_f16 v[82:97], v[234:237], v[218:221], v[82:97]
	v_mfma_f32_32x32x16_f16 v[34:49], v[230:233], v[222:225], v[34:49]
	v_mfma_f32_32x32x16_f16 v[50:65], v[234:237], v[222:225], v[50:65]
	v_mfma_f32_32x32x16_f16 v[2:17], v[230:233], v[226:229], v[2:17]
	v_mfma_f32_32x32x16_f16 v[18:33], v[234:237], v[226:229], v[18:33]
	ds_read_b128 v[200:203], v171 offset:96
	ds_read_b128 v[218:221], v171 offset:4704
	ds_read_b128 v[222:225], v171 offset:9312
	ds_read_b128 v[226:229], v171 offset:13920
	ds_read_b128 v[230:233], v1 offset:36960
	ds_read_b128 v[234:237], v1 offset:41568
	s_waitcnt lgkmcnt(0)
	s_barrier
; DI f16v mfma32(h8v a, h8v b, f16v c) { return __builtin_amdgcn_mfma_f32_32x32x16_f16(a, b, c, 0, 0, 0); }
; template <bool GATHER>
; DI void gemm256_main(const h16* __restrict__ A, int lda, const int* __restrict__ idx, int m0,
;                      const h16* __restrict__ B, int ldb, int n0, int K, h16* lds, f16v (&acc)[4][2]) {
;     ...
;   for (int kt = 0; kt < nk; ++kt) {
;     const h16* As = lds + (kt & 1) * (512 * LDH);
;     const h16* Bs = As + 256 * LDH;
;     h16* Wn = lds + ((kt & 1) ^ 1) * (512 * LDH);
;     if (kt + 1 < nk) {
; #pragma unroll
;       for (int i = 0; i < 4; ++i) { *(u4v*)&Wn[lr * LDH + lc + 8 * i] = ra[i]; *(u4v*)&Wn[(256 + lr) * LDH + lc + 8 * i] = rb[i]; }
;     }
;     if (kt + 2 < nk) {
; #pragma unroll
;       for (int i = 0; i < 4; ++i) { ra[i] = *(const u4v*)(AP_ + 8 * i); rb[i] = *(const u4v*)(BP_ + 8 * i); }
;       ao += 64; bo += 64;
;     }
; #pragma unroll
;     for (int ks = 0; ks < 4; ++ks) {
;       h8v af[4], bf[2];
; #pragma unroll
;       for (int i = 0; i < 4; ++i) af[i] = *(const h8v*)&As[(wm * 128 + i * 32 + (lane & 31)) * LDH + ks * 16 + 8 * (lane >> 5)];
; #pragma unroll
;       for (int j = 0; j < 2; ++j) bf[j] = *(const h8v*)&Bs[(wn * 64 + j * 32 + (lane & 31)) * LDH + ks * 16 + 8 * (lane >> 5)];
; #pragma unroll
;       for (int i = 0; i < 4; ++i)
; #pragma unroll
;         for (int j = 0; j < 2; ++j) acc[i][j] = mfma32(bf[j], af[i], acc[i][j]);
;     }
;     __syncthreads();
;   }
	s_waitcnt vmcnt(0)
	ds_write_b128 v216, v[158:161]
	ds_write_b128 v216, v[150:153] offset:36864
	ds_write_b128 v216, v[154:157] offset:16
	ds_write_b128 v216, v[142:145] offset:36880
	ds_write_b128 v216, v[146:149] offset:32
	ds_write_b128 v216, v[134:137] offset:36896
	ds_write_b128 v216, v[138:141] offset:48
	ds_write_b128 v216, v[130:133] offset:36912
	v_lshl_add_u64 v[138:139], v[164:165], 1, s[8:9]
	global_load_dwordx4 v[130:133], v[138:139], off offset:48
	global_load_dwordx4 v[134:137], v[138:139], off offset:32
	global_load_dwordx4 v[142:145], v[138:139], off offset:16
	global_load_dwordx4 v[150:153], v[138:139], off
	s_nop 0
	global_load_dwordx4 v[138:141], v[174:175], off offset:1200
	global_load_dwordx4 v[146:149], v[174:175], off offset:1184
	global_load_dwordx4 v[154:157], v[174:175], off offset:1168
	global_load_dwordx4 v[158:161], v[174:175], off offset:1152
	v_mfma_f32_32x32x16_f16 v[98:113], v[230:233], v[200:203], v[98:113]
	v_or_b32_e32 v164, 0x2c0, v176
	v_mfma_f32_32x32x16_f16 v[114:129], v[234:237], v[200:203], v[114:129]
	v_mfma_f32_32x32x16_f16 v[66:81], v[230:233], v[218:221], v[66:81]
	v_mfma_f32_32x32x16_f16 v[82:97], v[234:237], v[218:221], v[82:97]
	v_mfma_f32_32x32x16_f16 v[34:49], v[230:233], v[222:225], v[34:49]
	v_mfma_f32_32x32x16_f16 v[50:65], v[234:237], v[222:225], v[50:65]
	v_mfma_f32_32x32x16_f16 v[2:17], v[230:233], v[226:229], v[2:17]
	v_mfma_f32_32x32x16_f16 v[18:33], v[234:237], v[226:229], v[18:33]
	ds_read_b128 v[200:203], v178 offset:4608
	ds_read_b128 v[218:221], v178 offset:9216
	ds_read_b128 v[222:225], v178 offset:13824
	ds_read_b128 v[226:229], v179 offset:4608
	ds_read_b128 v[230:233], v178
	ds_read_b128 v[234:237], v178 offset:32
	ds_read_b128 v[238:241], v179
	ds_read_b128 v[242:245], v179 offset:32
	s_waitcnt lgkmcnt(1)
	v_mfma_f32_32x32x16_f16 v[98:113], v[238:241], v[230:233], v[98:113]
	v_mfma_f32_32x32x16_f16 v[114:129], v[226:229], v[230:233], v[114:129]
	v_mfma_f32_32x32x16_f16 v[66:81], v[238:241], v[200:203], v[66:81]
	v_mfma_f32_32x32x16_f16 v[82:97], v[226:229], v[200:203], v[82:97]
	v_mfma_f32_32x32x16_f16 v[34:49], v[238:241], v[218:221], v[34:49]
	v_mfma_f32_32x32x16_f16 v[50:65], v[226:229], v[218:221], v[50:65]
	v_mfma_f32_32x32x16_f16 v[2:17], v[238:241], v[222:225], v[2:17]
	v_mfma_f32_32x32x16_f16 v[18:33], v[226:229], v[222:225], v[18:33]
	ds_read_b128 v[200:203], v178 offset:4640
	ds_read_b128 v[218:221], v178 offset:9248
	ds_read_b128 v[222:225], v178 offset:13856
	ds_read_b128 v[226:229], v179 offset:4640
	s_waitcnt lgkmcnt(4)
	v_mfma_f32_32x32x16_f16 v[98:113], v[242:245], v[234:237], v[98:113]
	s_waitcnt lgkmcnt(0)
	v_mfma_f32_32x32x16_f16 v[114:129], v[226:229], v[234:237], v[114:129]
	v_mfma_f32_32x32x16_f16 v[66:81], v[242:245], v[200:203], v[66:81]
	v_mfma_f32_32x32x16_f16 v[82:97], v[226:229], v[200:203], v[82:97]
	v_mfma_f32_32x32x16_f16 v[34:49], v[242:245], v[218:221], v[34:49]
	v_mfma_f32_32x32x16_f16 v[50:65], v[226:229], v[218:221], v[50:65]
	v_mfma_f32_32x32x16_f16 v[2:17], v[242:245], v[222:225], v[2:17]
	v_mfma_f32_32x32x16_f16 v[18:33], v[226:229], v[222:225], v[18:33]
	ds_read_b128 v[200:203], v178 offset:64
	ds_read_b128 v[218:221], v178 offset:4672
	ds_read_b128 v[222:225], v178 offset:9280
	ds_read_b128 v[226:229], v178 offset:13888
	ds_read_b128 v[230:233], v179 offset:64
	ds_read_b128 v[234:237], v179 offset:4672
	s_waitcnt lgkmcnt(1)
	v_mfma_f32_32x32x16_f16 v[98:113], v[230:233], v[200:203], v[98:113]
	s_waitcnt lgkmcnt(0)
	v_mfma_f32_32x32x16_f16 v[114:129], v[234:237], v[200:203], v[114:129]
	v_mfma_f32_32x32x16_f16 v[66:81], v[230:233], v[218:221], v[66:81]
	v_mfma_f32_32x32x16_f16 v[82:97], v[234:237], v[218:221], v[82:97]
	v_mfma_f32_32x32x16_f16 v[34:49], v[230:233], v[222:225], v[34:49]
	v_mfma_f32_32x32x16_f16 v[50:65], v[234:237], v[222:225], v[50:65]
	v_mfma_f32_32x32x16_f16 v[2:17], v[230:233], v[226:229], v[2:17]
	v_mfma_f32_32x32x16_f16 v[18:33], v[234:237], v[226:229], v[18:33]
	ds_read_b128 v[200:203], v178 offset:96
	ds_read_b128 v[218:221], v178 offset:4704
	ds_read_b128 v[222:225], v178 offset:9312
	ds_read_b128 v[226:229], v178 offset:13920
	ds_read_b128 v[230:233], v179 offset:96
	ds_read_b128 v[234:237], v179 offset:4704
	s_waitcnt lgkmcnt(0)
	s_barrier
; DI f16v mfma32(h8v a, h8v b, f16v c) { return __builtin_amdgcn_mfma_f32_32x32x16_f16(a, b, c, 0, 0, 0); }
; template <bool GATHER>
; DI void gemm256_main(const h16* __restrict__ A, int lda, const int* __restrict__ idx, int m0,
;                      const h16* __restrict__ B, int ldb, int n0, int K, h16* lds, f16v (&acc)[4][2]) {
;     ...
;   for (int kt = 0; kt < nk; ++kt) {
;     const h16* As = lds + (kt & 1) * (512 * LDH);
;     const h16* Bs = As + 256 * LDH;
;     h16* Wn = lds + ((kt & 1) ^ 1) * (512 * LDH);
;     if (kt + 1 < nk) {
; #pragma unroll
;       for (int i = 0; i < 4; ++i) { *(u4v*)&Wn[lr * LDH + lc + 8 * i] = ra[i]; *(u4v*)&Wn[(256 + lr) * LDH + lc + 8 * i] = rb[i]; }
;     }
;     if (kt + 2 < nk) {
; #pragma unroll
;       for (int i = 0; i < 4; ++i) { ra[i] = *(const u4v*)(AP_ + 8 * i); rb[i] = *(const u4v*)(BP_ + 8 * i); }
;       ao += 64; bo += 64;
;     }
; #pragma unroll
;     for (int ks = 0; ks < 4; ++ks) {
;       h8v af[4], bf[2];
; #pragma unroll
;       for (int i = 0; i < 4; ++i) af[i] = *(const h8v*)&As[(wm * 128 + i * 32 + (lane & 31)) * LDH + ks * 16 + 8 * (lane >> 5)];
; #pragma unroll
;       for (int j = 0; j < 2; ++j) bf[j] = *(const h8v*)&Bs[(wn * 64 + j * 32 + (lane & 31)) * LDH + ks * 16 + 8 * (lane >> 5)];
; #pragma unroll
;       for (int i = 0; i < 4; ++i)
; #pragma unroll
;         for (int j = 0; j < 2; ++j) acc[i][j] = mfma32(bf[j], af[i], acc[i][j]);
;     }
;     __syncthreads();
;   }
	s_waitcnt vmcnt(0)
	ds_write_b128 v177, v[158:161]
	ds_write_b128 v215, v[150:153]
	ds_write_b128 v177, v[154:157] offset:16
	ds_write_b128 v215, v[142:145] offset:16
	ds_write_b128 v177, v[146:149] offset:32
	ds_write_b128 v215, v[134:137] offset:32
	ds_write_b128 v177, v[138:141] offset:48
	ds_write_b128 v215, v[130:133] offset:48
	v_lshl_add_u64 v[138:139], v[162:163], 1, s[8:9]
	global_load_dwordx4 v[130:133], v[138:139], off offset:48
	global_load_dwordx4 v[134:137], v[138:139], off offset:32
	global_load_dwordx4 v[142:145], v[138:139], off offset:16
	global_load_dwordx4 v[150:153], v[138:139], off
	s_nop 0
	global_load_dwordx4 v[138:141], v[174:175], off offset:1328
	global_load_dwordx4 v[146:149], v[174:175], off offset:1312
	global_load_dwordx4 v[154:157], v[174:175], off offset:1296
	global_load_dwordx4 v[158:161], v[174:175], off offset:1280
	v_mfma_f32_32x32x16_f16 v[98:113], v[230:233], v[200:203], v[98:113]
	v_or_b32_e32 v162, 0x300, v176
	v_mfma_f32_32x32x16_f16 v[114:129], v[234:237], v[200:203], v[114:129]
	v_mfma_f32_32x32x16_f16 v[66:81], v[230:233], v[218:221], v[66:81]
	v_mfma_f32_32x32x16_f16 v[82:97], v[234:237], v[218:221], v[82:97]
	v_mfma_f32_32x32x16_f16 v[34:49], v[230:233], v[222:225], v[34:49]
	v_mfma_f32_32x32x16_f16 v[50:65], v[234:237], v[222:225], v[50:65]
	v_mfma_f32_32x32x16_f16 v[2:17], v[230:233], v[226:229], v[2:17]
	v_mfma_f32_32x32x16_f16 v[18:33], v[234:237], v[226:229], v[18:33]
	ds_read_b128 v[200:203], v171 offset:4608
	ds_read_b128 v[218:221], v171 offset:9216
	ds_read_b128 v[222:225], v171 offset:13824
	ds_read_b128 v[226:229], v1 offset:41472
	ds_read_b128 v[230:233], v171
	ds_read_b128 v[234:237], v171 offset:32
	ds_read_b128 v[238:241], v1 offset:36864
	ds_read_b128 v[242:245], v1 offset:36896
	s_waitcnt lgkmcnt(1)
	v_mfma_f32_32x32x16_f16 v[98:113], v[238:241], v[230:233], v[98:113]
	v_mfma_f32_32x32x16_f16 v[114:129], v[226:229], v[230:233], v[114:129]
	v_mfma_f32_32x32x16_f16 v[66:81], v[238:241], v[200:203], v[66:81]
	v_mfma_f32_32x32x16_f16 v[82:97], v[226:229], v[200:203], v[82:97]
	v_mfma_f32_32x32x16_f16 v[34:49], v[238:241], v[218:221], v[34:49]
	v_mfma_f32_32x32x16_f16 v[50:65], v[226:229], v[218:221], v[50:65]
	v_mfma_f32_32x32x16_f16 v[2:17], v[238:241], v[222:225], v[2:17]
	v_mfma_f32_32x32x16_f16 v[18:33], v[226:229], v[222:225], v[18:33]
	ds_read_b128 v[200:203], v171 offset:4640
	ds_read_b128 v[218:221], v171 offset:9248
	ds_read_b128 v[222:225], v171 offset:13856
	ds_read_b128 v[226:229], v1 offset:41504
	s_waitcnt lgkmcnt(4)
	v_mfma_f32_32x32x16_f16 v[98:113], v[242:245], v[234:237], v[98:113]
	s_waitcnt lgkmcnt(0)
	v_mfma_f32_32x32x16_f16 v[114:129], v[226:229], v[234:237], v[114:129]
	v_mfma_f32_32x32x16_f16 v[66:81], v[242:245], v[200:203], v[66:81]
	v_mfma_f32_32x32x16_f16 v[82:97], v[226:229], v[200:203], v[82:97]
	v_mfma_f32_32x32x16_f16 v[34:49], v[242:245], v[218:221], v[34:49]
	v_mfma_f32_32x32x16_f16 v[50:65], v[226:229], v[218:221], v[50:65]
	v_mfma_f32_32x32x16_f16 v[2:17], v[242:245], v[222:225], v[2:17]
	v_mfma_f32_32x32x16_f16 v[18:33], v[226:229], v[222:225], v[18:33]
	ds_read_b128 v[200:203], v171 offset:64
	ds_read_b128 v[218:221], v171 offset:4672
	ds_read_b128 v[222:225], v171 offset:9280
	ds_read_b128 v[226:229], v171 offset:13888
	ds_read_b128 v[230:233], v1 offset:36928
	ds_read_b128 v[234:237], v1 offset:41536
	s_waitcnt lgkmcnt(1)
	v_mfma_f32_32x32x16_f16 v[98:113], v[230:233], v[200:203], v[98:113]
	s_waitcnt lgkmcnt(0)
	v_mfma_f32_32x32x16_f16 v[114:129], v[234:237], v[200:203], v[114:129]
	v_mfma_f32_32x32x16_f16 v[66:81], v[230:233], v[218:221], v[66:81]
	v_mfma_f32_32x32x16_f16 v[82:97], v[234:237], v[218:221], v[82:97]
	v_mfma_f32_32x32x16_f16 v[34:49], v[230:233], v[222:225], v[34:49]
	v_mfma_f32_32x32x16_f16 v[50:65], v[234:237], v[222:225], v[50:65]
	v_mfma_f32_32x32x16_f16 v[2:17], v[230:233], v[226:229], v[2:17]
	v_mfma_f32_32x32x16_f16 v[18:33], v[234:237], v[226:229], v[18:33]
	ds_read_b128 v[200:203], v171 offset:96
	ds_read_b128 v[218:221], v171 offset:4704
	ds_read_b128 v[222:225], v171 offset:9312
	ds_read_b128 v[226:229], v171 offset:13920
	ds_read_b128 v[230:233], v1 offset:36960
	ds_read_b128 v[234:237], v1 offset:41568
	s_waitcnt lgkmcnt(0)
	s_barrier
; DI f16v mfma32(h8v a, h8v b, f16v c) { return __builtin_amdgcn_mfma_f32_32x32x16_f16(a, b, c, 0, 0, 0); }
; template <bool GATHER>
; DI void gemm256_main(const h16* __restrict__ A, int lda, const int* __restrict__ idx, int m0,
;                      const h16* __restrict__ B, int ldb, int n0, int K, h16* lds, f16v (&acc)[4][2]) {
;     ...
;   for (int kt = 0; kt < nk; ++kt) {
;     const h16* As = lds + (kt & 1) * (512 * LDH);
;     const h16* Bs = As + 256 * LDH;
;     h16* Wn = lds + ((kt & 1) ^ 1) * (512 * LDH);
;     if (kt + 1 < nk) {
; #pragma unroll
;       for (int i = 0; i < 4; ++i) { *(u4v*)&Wn[lr * LDH + lc + 8 * i] = ra[i]; *(u4v*)&Wn[(256 + lr) * LDH + lc + 8 * i] = rb[i]; }
;     }
;     if (kt + 2 < nk) {
; #pragma unroll
;       for (int i = 0; i < 4; ++i) { ra[i] = *(const u4v*)(AP_ + 8 * i); rb[i] = *(const u4v*)(BP_ + 8 * i); }
;       ao += 64; bo += 64;
;     }
; #pragma unroll
;     for (int ks = 0; ks < 4; ++ks) {
;       h8v af[4], bf[2];
; #pragma unroll
;       for (int i = 0; i < 4; ++i) af[i] = *(const h8v*)&As[(wm * 128 + i * 32 + (lane & 31)) * LDH + ks * 16 + 8 * (lane >> 5)];
; #pragma unroll
;       for (int j = 0; j < 2; ++j) bf[j] = *(const h8v*)&Bs[(wn * 64 + j * 32 + (lane & 31)) * LDH + ks * 16 + 8 * (lane >> 5)];
; #pragma unroll
;       for (int i = 0; i < 4; ++i)
; #pragma unroll
;         for (int j = 0; j < 2; ++j) acc[i][j] = mfma32(bf[j], af[i], acc[i][j]);
;     }
;     __syncthreads();
;   }
	s_waitcnt vmcnt(0)
	ds_write_b128 v216, v[158:161]
	ds_write_b128 v216, v[150:153] offset:36864
	ds_write_b128 v216, v[154:157] offset:16
	ds_write_b128 v216, v[142:145] offset:36880
	ds_write_b128 v216, v[146:149] offset:32
	ds_write_b128 v216, v[134:137] offset:36896
	ds_write_b128 v216, v[138:141] offset:48
	ds_write_b128 v216, v[130:133] offset:36912
	v_lshl_add_u64 v[138:139], v[164:165], 1, s[8:9]
	global_load_dwordx4 v[130:133], v[138:139], off offset:48
	global_load_dwordx4 v[134:137], v[138:139], off offset:32
	global_load_dwordx4 v[142:145], v[138:139], off offset:16
	global_load_dwordx4 v[150:153], v[138:139], off
	s_nop 0
	global_load_dwordx4 v[138:141], v[174:175], off offset:1456
	global_load_dwordx4 v[146:149], v[174:175], off offset:1440
	global_load_dwordx4 v[154:157], v[174:175], off offset:1424
	global_load_dwordx4 v[158:161], v[174:175], off offset:1408
	v_mfma_f32_32x32x16_f16 v[98:113], v[230:233], v[200:203], v[98:113]
	v_or_b32_e32 v164, 0x340, v176
	v_mfma_f32_32x32x16_f16 v[114:129], v[234:237], v[200:203], v[114:129]
	v_mfma_f32_32x32x16_f16 v[66:81], v[230:233], v[218:221], v[66:81]
	v_mfma_f32_32x32x16_f16 v[82:97], v[234:237], v[218:221], v[82:97]
	v_mfma_f32_32x32x16_f16 v[34:49], v[230:233], v[222:225], v[34:49]
	v_mfma_f32_32x32x16_f16 v[50:65], v[234:237], v[222:225], v[50:65]
	v_mfma_f32_32x32x16_f16 v[2:17], v[230:233], v[226:229], v[2:17]
	v_mfma_f32_32x32x16_f16 v[18:33], v[234:237], v[226:229], v[18:33]
	ds_read_b128 v[200:203], v178 offset:4608
	ds_read_b128 v[218:221], v178 offset:9216
	ds_read_b128 v[222:225], v178 offset:13824
	ds_read_b128 v[226:229], v179 offset:4608
	ds_read_b128 v[230:233], v178
	ds_read_b128 v[234:237], v178 offset:32
	ds_read_b128 v[238:241], v179
	ds_read_b128 v[242:245], v179 offset:32
	s_waitcnt lgkmcnt(1)
	v_mfma_f32_32x32x16_f16 v[98:113], v[238:241], v[230:233], v[98:113]
	v_mfma_f32_32x32x16_f16 v[114:129], v[226:229], v[230:233], v[114:129]
	v_mfma_f32_32x32x16_f16 v[66:81], v[238:241], v[200:203], v[66:81]
	v_mfma_f32_32x32x16_f16 v[82:97], v[226:229], v[200:203], v[82:97]
	v_mfma_f32_32x32x16_f16 v[34:49], v[238:241], v[218:221], v[34:49]
	v_mfma_f32_32x32x16_f16 v[50:65], v[226:229], v[218:221], v[50:65]
	v_mfma_f32_32x32x16_f16 v[2:17], v[238:241], v[222:225], v[2:17]
	v_mfma_f32_32x32x16_f16 v[18:33], v[226:229], v[222:225], v[18:33]
	ds_read_b128 v[200:203], v178 offset:4640
	ds_read_b128 v[218:221], v178 offset:9248
	ds_read_b128 v[222:225], v178 offset:13856
	ds_read_b128 v[226:229], v179 offset:4640
	s_waitcnt lgkmcnt(4)
	v_mfma_f32_32x32x16_f16 v[98:113], v[242:245], v[234:237], v[98:113]
	s_waitcnt lgkmcnt(0)
	v_mfma_f32_32x32x16_f16 v[114:129], v[226:229], v[234:237], v[114:129]
	v_mfma_f32_32x32x16_f16 v[66:81], v[242:245], v[200:203], v[66:81]
	v_mfma_f32_32x32x16_f16 v[82:97], v[226:229], v[200:203], v[82:97]
	v_mfma_f32_32x32x16_f16 v[34:49], v[242:245], v[218:221], v[34:49]
	v_mfma_f32_32x32x16_f16 v[50:65], v[226:229], v[218:221], v[50:65]
	v_mfma_f32_32x32x16_f16 v[2:17], v[242:245], v[222:225], v[2:17]
	v_mfma_f32_32x32x16_f16 v[18:33], v[226:229], v[222:225], v[18:33]
	ds_read_b128 v[200:203], v178 offset:64
	ds_read_b128 v[218:221], v178 offset:4672
	ds_read_b128 v[222:225], v178 offset:9280
	ds_read_b128 v[226:229], v178 offset:13888
	ds_read_b128 v[230:233], v179 offset:64
	ds_read_b128 v[234:237], v179 offset:4672
	s_waitcnt lgkmcnt(1)
	v_mfma_f32_32x32x16_f16 v[98:113], v[230:233], v[200:203], v[98:113]
	s_waitcnt lgkmcnt(0)
	v_mfma_f32_32x32x16_f16 v[114:129], v[234:237], v[200:203], v[114:129]
	v_mfma_f32_32x32x16_f16 v[66:81], v[230:233], v[218:221], v[66:81]
	v_mfma_f32_32x32x16_f16 v[82:97], v[234:237], v[218:221], v[82:97]
	v_mfma_f32_32x32x16_f16 v[34:49], v[230:233], v[222:225], v[34:49]
	v_mfma_f32_32x32x16_f16 v[50:65], v[234:237], v[222:225], v[50:65]
	v_mfma_f32_32x32x16_f16 v[2:17], v[230:233], v[226:229], v[2:17]
	v_mfma_f32_32x32x16_f16 v[18:33], v[234:237], v[226:229], v[18:33]
	ds_read_b128 v[200:203], v178 offset:96
	ds_read_b128 v[218:221], v178 offset:4704
	ds_read_b128 v[222:225], v178 offset:9312
	ds_read_b128 v[226:229], v178 offset:13920
	ds_read_b128 v[230:233], v179 offset:96
	ds_read_b128 v[234:237], v179 offset:4704
	s_waitcnt lgkmcnt(0)
	s_barrier
; DI f16v mfma32(h8v a, h8v b, f16v c) { return __builtin_amdgcn_mfma_f32_32x32x16_f16(a, b, c, 0, 0, 0); }
; template <bool GATHER>
; DI void gemm256_main(const h16* __restrict__ A, int lda, const int* __restrict__ idx, int m0,
;                      const h16* __restrict__ B, int ldb, int n0, int K, h16* lds, f16v (&acc)[4][2]) {
;     ...
;   for (int kt = 0; kt < nk; ++kt) {
;     const h16* As = lds + (kt & 1) * (512 * LDH);
;     const h16* Bs = As + 256 * LDH;
;     h16* Wn = lds + ((kt & 1) ^ 1) * (512 * LDH);
;     if (kt + 1 < nk) {
; #pragma unroll
;       for (int i = 0; i < 4; ++i) { *(u4v*)&Wn[lr * LDH + lc + 8 * i] = ra[i]; *(u4v*)&Wn[(256 + lr) * LDH + lc + 8 * i] = rb[i]; }
;     }
;     if (kt + 2 < nk) {
; #pragma unroll
;       for (int i = 0; i < 4; ++i) { ra[i] = *(const u4v*)(AP_ + 8 * i); rb[i] = *(const u4v*)(BP_ + 8 * i); }
;       ao += 64; bo += 64;
;     }
; #pragma unroll
;     for (int ks = 0; ks < 4; ++ks) {
;       h8v af[4], bf[2];
; #pragma unroll
;       for (int i = 0; i < 4; ++i) af[i] = *(const h8v*)&As[(wm * 128 + i * 32 + (lane & 31)) * LDH + ks * 16 + 8 * (lane >> 5)];
; #pragma unroll
;       for (int j = 0; j < 2; ++j) bf[j] = *(const h8v*)&Bs[(wn * 64 + j * 32 + (lane & 31)) * LDH + ks * 16 + 8 * (lane >> 5)];
; #pragma unroll
;       for (int i = 0; i < 4; ++i)
; #pragma unroll
;         for (int j = 0; j < 2; ++j) acc[i][j] = mfma32(bf[j], af[i], acc[i][j]);
;     }
;     __syncthreads();
;   }
	s_waitcnt vmcnt(0)
	ds_write_b128 v177, v[158:161]
	ds_write_b128 v215, v[150:153]
	ds_write_b128 v177, v[154:157] offset:16
	ds_write_b128 v215, v[142:145] offset:16
	ds_write_b128 v177, v[146:149] offset:32
	ds_write_b128 v215, v[134:137] offset:32
	ds_write_b128 v177, v[138:141] offset:48
	ds_write_b128 v215, v[130:133] offset:48
	v_lshl_add_u64 v[138:139], v[162:163], 1, s[8:9]
	global_load_dwordx4 v[130:133], v[138:139], off offset:48
	global_load_dwordx4 v[134:137], v[138:139], off offset:32
	global_load_dwordx4 v[142:145], v[138:139], off offset:16
	global_load_dwordx4 v[150:153], v[138:139], off
	s_nop 0
	global_load_dwordx4 v[138:141], v[174:175], off offset:1584
	global_load_dwordx4 v[146:149], v[174:175], off offset:1568
	global_load_dwordx4 v[154:157], v[174:175], off offset:1552
	global_load_dwordx4 v[158:161], v[174:175], off offset:1536
	v_mfma_f32_32x32x16_f16 v[98:113], v[230:233], v[200:203], v[98:113]
	v_or_b32_e32 v162, 0x380, v176
	v_mfma_f32_32x32x16_f16 v[114:129], v[234:237], v[200:203], v[114:129]
	v_mfma_f32_32x32x16_f16 v[66:81], v[230:233], v[218:221], v[66:81]
	v_mfma_f32_32x32x16_f16 v[82:97], v[234:237], v[218:221], v[82:97]
	v_mfma_f32_32x32x16_f16 v[34:49], v[230:233], v[222:225], v[34:49]
	v_mfma_f32_32x32x16_f16 v[50:65], v[234:237], v[222:225], v[50:65]
	v_mfma_f32_32x32x16_f16 v[2:17], v[230:233], v[226:229], v[2:17]
	v_mfma_f32_32x32x16_f16 v[18:33], v[234:237], v[226:229], v[18:33]
	ds_read_b128 v[200:203], v171 offset:4608
	ds_read_b128 v[218:221], v171 offset:9216
	ds_read_b128 v[222:225], v171 offset:13824
	ds_read_b128 v[226:229], v1 offset:41472
	ds_read_b128 v[230:233], v171
	ds_read_b128 v[234:237], v171 offset:32
	ds_read_b128 v[238:241], v1 offset:36864
	ds_read_b128 v[242:245], v1 offset:36896
	s_waitcnt lgkmcnt(1)
	v_mfma_f32_32x32x16_f16 v[98:113], v[238:241], v[230:233], v[98:113]
	v_mfma_f32_32x32x16_f16 v[114:129], v[226:229], v[230:233], v[114:129]
	v_mfma_f32_32x32x16_f16 v[66:81], v[238:241], v[200:203], v[66:81]
	v_mfma_f32_32x32x16_f16 v[82:97], v[226:229], v[200:203], v[82:97]
	v_mfma_f32_32x32x16_f16 v[34:49], v[238:241], v[218:221], v[34:49]
	v_mfma_f32_32x32x16_f16 v[50:65], v[226:229], v[218:221], v[50:65]
	v_mfma_f32_32x32x16_f16 v[2:17], v[238:241], v[222:225], v[2:17]
	v_mfma_f32_32x32x16_f16 v[18:33], v[226:229], v[222:225], v[18:33]
	ds_read_b128 v[200:203], v171 offset:4640
	ds_read_b128 v[218:221], v171 offset:9248
	ds_read_b128 v[222:225], v171 offset:13856
	ds_read_b128 v[226:229], v1 offset:41504
	s_waitcnt lgkmcnt(4)
	v_mfma_f32_32x32x16_f16 v[98:113], v[242:245], v[234:237], v[98:113]
	s_waitcnt lgkmcnt(0)
	v_mfma_f32_32x32x16_f16 v[114:129], v[226:229], v[234:237], v[114:129]
	v_mfma_f32_32x32x16_f16 v[66:81], v[242:245], v[200:203], v[66:81]
	v_mfma_f32_32x32x16_f16 v[82:97], v[226:229], v[200:203], v[82:97]
	v_mfma_f32_32x32x16_f16 v[34:49], v[242:245], v[218:221], v[34:49]
	v_mfma_f32_32x32x16_f16 v[50:65], v[226:229], v[218:221], v[50:65]
	v_mfma_f32_32x32x16_f16 v[2:17], v[242:245], v[222:225], v[2:17]
	v_mfma_f32_32x32x16_f16 v[18:33], v[226:229], v[222:225], v[18:33]
	ds_read_b128 v[200:203], v171 offset:64
	ds_read_b128 v[218:221], v171 offset:4672
	ds_read_b128 v[222:225], v171 offset:9280
	ds_read_b128 v[226:229], v171 offset:13888
	ds_read_b128 v[230:233], v1 offset:36928
	ds_read_b128 v[234:237], v1 offset:41536
	s_waitcnt lgkmcnt(1)
	v_mfma_f32_32x32x16_f16 v[98:113], v[230:233], v[200:203], v[98:113]
	s_waitcnt lgkmcnt(0)
	v_mfma_f32_32x32x16_f16 v[114:129], v[234:237], v[200:203], v[114:129]
	v_mfma_f32_32x32x16_f16 v[66:81], v[230:233], v[218:221], v[66:81]
	v_mfma_f32_32x32x16_f16 v[82:97], v[234:237], v[218:221], v[82:97]
	v_mfma_f32_32x32x16_f16 v[34:49], v[230:233], v[222:225], v[34:49]
	v_mfma_f32_32x32x16_f16 v[50:65], v[234:237], v[222:225], v[50:65]
	v_mfma_f32_32x32x16_f16 v[2:17], v[230:233], v[226:229], v[2:17]
	v_mfma_f32_32x32x16_f16 v[18:33], v[234:237], v[226:229], v[18:33]
	ds_read_b128 v[200:203], v171 offset:96
	ds_read_b128 v[218:221], v171 offset:4704
	ds_read_b128 v[222:225], v171 offset:9312
	ds_read_b128 v[226:229], v171 offset:13920
	ds_read_b128 v[230:233], v1 offset:36960
	ds_read_b128 v[234:237], v1 offset:41568
	s_waitcnt lgkmcnt(0)
	s_barrier
; DI f16v mfma32(h8v a, h8v b, f16v c) { return __builtin_amdgcn_mfma_f32_32x32x16_f16(a, b, c, 0, 0, 0); }
; template <bool GATHER>
; DI void gemm256_main(const h16* __restrict__ A, int lda, const int* __restrict__ idx, int m0,
;                      const h16* __restrict__ B, int ldb, int n0, int K, h16* lds, f16v (&acc)[4][2]) {
;     ...
;   for (int kt = 0; kt < nk; ++kt) {
;     const h16* As = lds + (kt & 1) * (512 * LDH);
;     const h16* Bs = As + 256 * LDH;
;     h16* Wn = lds + ((kt & 1) ^ 1) * (512 * LDH);
;     if (kt + 1 < nk) {
; #pragma unroll
;       for (int i = 0; i < 4; ++i) { *(u4v*)&Wn[lr * LDH + lc + 8 * i] = ra[i]; *(u4v*)&Wn[(256 + lr) * LDH + lc + 8 * i] = rb[i]; }
;     }
;     if (kt + 2 < nk) {
; #pragma unroll
;       for (int i = 0; i < 4; ++i) { ra[i] = *(const u4v*)(AP_ + 8 * i); rb[i] = *(const u4v*)(BP_ + 8 * i); }
;       ao += 64; bo += 64;
;     }
; #pragma unroll
;     for (int ks = 0; ks < 4; ++ks) {
;       h8v af[4], bf[2];
; #pragma unroll
;       for (int i = 0; i < 4; ++i) af[i] = *(const h8v*)&As[(wm * 128 + i * 32 + (lane & 31)) * LDH + ks * 16 + 8 * (lane >> 5)];
; #pragma unroll
;       for (int j = 0; j < 2; ++j) bf[j] = *(const h8v*)&Bs[(wn * 64 + j * 32 + (lane & 31)) * LDH + ks * 16 + 8 * (lane >> 5)];
; #pragma unroll
;       for (int i = 0; i < 4; ++i)
; #pragma unroll
;         for (int j = 0; j < 2; ++j) acc[i][j] = mfma32(bf[j], af[i], acc[i][j]);
;     }
;     __syncthreads();
;   }
	s_waitcnt vmcnt(0)
	ds_write_b128 v216, v[158:161]
	ds_write_b128 v216, v[150:153] offset:36864
	ds_write_b128 v216, v[154:157] offset:16
	ds_write_b128 v216, v[142:145] offset:36880
	ds_write_b128 v216, v[146:149] offset:32
	ds_write_b128 v216, v[134:137] offset:36896
	ds_write_b128 v216, v[138:141] offset:48
	ds_write_b128 v216, v[130:133] offset:36912
	v_lshl_add_u64 v[138:139], v[164:165], 1, s[8:9]
	global_load_dwordx4 v[130:133], v[138:139], off offset:48
	global_load_dwordx4 v[134:137], v[138:139], off offset:32
	global_load_dwordx4 v[142:145], v[138:139], off offset:16
	global_load_dwordx4 v[150:153], v[138:139], off
	s_nop 0
	global_load_dwordx4 v[138:141], v[174:175], off offset:1712
	global_load_dwordx4 v[146:149], v[174:175], off offset:1696
	global_load_dwordx4 v[154:157], v[174:175], off offset:1680
	global_load_dwordx4 v[158:161], v[174:175], off offset:1664
	v_mfma_f32_32x32x16_f16 v[98:113], v[230:233], v[200:203], v[98:113]
	v_or_b32_e32 v164, 0x3c0, v176
	v_mfma_f32_32x32x16_f16 v[114:129], v[234:237], v[200:203], v[114:129]
	v_mfma_f32_32x32x16_f16 v[66:81], v[230:233], v[218:221], v[66:81]
	v_mfma_f32_32x32x16_f16 v[82:97], v[234:237], v[218:221], v[82:97]
	v_mfma_f32_32x32x16_f16 v[34:49], v[230:233], v[222:225], v[34:49]
	v_mfma_f32_32x32x16_f16 v[50:65], v[234:237], v[222:225], v[50:65]
	v_mfma_f32_32x32x16_f16 v[2:17], v[230:233], v[226:229], v[2:17]
	v_mfma_f32_32x32x16_f16 v[18:33], v[234:237], v[226:229], v[18:33]
	ds_read_b128 v[200:203], v178 offset:4608
	ds_read_b128 v[218:221], v178 offset:9216
	ds_read_b128 v[222:225], v178 offset:13824
	ds_read_b128 v[226:229], v179 offset:4608
	ds_read_b128 v[230:233], v178
	ds_read_b128 v[234:237], v178 offset:32
	ds_read_b128 v[238:241], v179
	ds_read_b128 v[242:245], v179 offset:32
	s_waitcnt lgkmcnt(1)
	v_mfma_f32_32x32x16_f16 v[98:113], v[238:241], v[230:233], v[98:113]
	v_mfma_f32_32x32x16_f16 v[114:129], v[226:229], v[230:233], v[114:129]
	v_mfma_f32_32x32x16_f16 v[66:81], v[238:241], v[200:203], v[66:81]
	v_mfma_f32_32x32x16_f16 v[82:97], v[226:229], v[200:203], v[82:97]
	v_mfma_f32_32x32x16_f16 v[34:49], v[238:241], v[218:221], v[34:49]
	v_mfma_f32_32x32x16_f16 v[50:65], v[226:229], v[218:221], v[50:65]
	v_mfma_f32_32x32x16_f16 v[2:17], v[238:241], v[222:225], v[2:17]
	v_mfma_f32_32x32x16_f16 v[18:33], v[226:229], v[222:225], v[18:33]
	ds_read_b128 v[200:203], v178 offset:4640
	ds_read_b128 v[218:221], v178 offset:9248
	ds_read_b128 v[222:225], v178 offset:13856
	ds_read_b128 v[226:229], v179 offset:4640
	s_waitcnt lgkmcnt(4)
	v_mfma_f32_32x32x16_f16 v[98:113], v[242:245], v[234:237], v[98:113]
	s_waitcnt lgkmcnt(0)
	v_mfma_f32_32x32x16_f16 v[114:129], v[226:229], v[234:237], v[114:129]
	v_mfma_f32_32x32x16_f16 v[66:81], v[242:245], v[200:203], v[66:81]
	v_mfma_f32_32x32x16_f16 v[82:97], v[226:229], v[200:203], v[82:97]
	v_mfma_f32_32x32x16_f16 v[34:49], v[242:245], v[218:221], v[34:49]
	v_mfma_f32_32x32x16_f16 v[50:65], v[226:229], v[218:221], v[50:65]
	v_mfma_f32_32x32x16_f16 v[2:17], v[242:245], v[222:225], v[2:17]
	v_mfma_f32_32x32x16_f16 v[18:33], v[226:229], v[222:225], v[18:33]
	ds_read_b128 v[200:203], v178 offset:64
	ds_read_b128 v[218:221], v178 offset:4672
	ds_read_b128 v[222:225], v178 offset:9280
	ds_read_b128 v[226:229], v178 offset:13888
	ds_read_b128 v[230:233], v179 offset:64
	ds_read_b128 v[234:237], v179 offset:4672
	s_waitcnt lgkmcnt(1)
	v_mfma_f32_32x32x16_f16 v[98:113], v[230:233], v[200:203], v[98:113]
	s_waitcnt lgkmcnt(0)
	v_mfma_f32_32x32x16_f16 v[114:129], v[234:237], v[200:203], v[114:129]
	v_mfma_f32_32x32x16_f16 v[66:81], v[230:233], v[218:221], v[66:81]
	v_mfma_f32_32x32x16_f16 v[82:97], v[234:237], v[218:221], v[82:97]
	v_mfma_f32_32x32x16_f16 v[34:49], v[230:233], v[222:225], v[34:49]
	v_mfma_f32_32x32x16_f16 v[50:65], v[234:237], v[222:225], v[50:65]
	v_mfma_f32_32x32x16_f16 v[2:17], v[230:233], v[226:229], v[2:17]
	v_mfma_f32_32x32x16_f16 v[18:33], v[234:237], v[226:229], v[18:33]
	ds_read_b128 v[200:203], v178 offset:96
	ds_read_b128 v[218:221], v178 offset:4704
	ds_read_b128 v[222:225], v178 offset:9312
	ds_read_b128 v[226:229], v178 offset:13920
	ds_read_b128 v[230:233], v179 offset:96
	ds_read_b128 v[234:237], v179 offset:4704
	s_waitcnt lgkmcnt(0)
	s_barrier
; DI f16v mfma32(h8v a, h8v b, f16v c) { return __builtin_amdgcn_mfma_f32_32x32x16_f16(a, b, c, 0, 0, 0); }
; template <bool GATHER>
; DI void gemm256_main(const h16* __restrict__ A, int lda, const int* __restrict__ idx, int m0,
;                      const h16* __restrict__ B, int ldb, int n0, int K, h16* lds, f16v (&acc)[4][2]) {
;     ...
;   for (int kt = 0; kt < nk; ++kt) {
;     const h16* As = lds + (kt & 1) * (512 * LDH);
;     const h16* Bs = As + 256 * LDH;
;     h16* Wn = lds + ((kt & 1) ^ 1) * (512 * LDH);
;     if (kt + 1 < nk) {
; #pragma unroll
;       for (int i = 0; i < 4; ++i) { *(u4v*)&Wn[lr * LDH + lc + 8 * i] = ra[i]; *(u4v*)&Wn[(256 + lr) * LDH + lc + 8 * i] = rb[i]; }
;     }
;     if (kt + 2 < nk) {
; #pragma unroll
;       for (int i = 0; i < 4; ++i) { ra[i] = *(const u4v*)(AP_ + 8 * i); rb[i] = *(const u4v*)(BP_ + 8 * i); }
;       ao += 64; bo += 64;
;     }
; #pragma unroll
;     for (int ks = 0; ks < 4; ++ks) {
;       h8v af[4], bf[2];
; #pragma unroll
;       for (int i = 0; i < 4; ++i) af[i] = *(const h8v*)&As[(wm * 128 + i * 32 + (lane & 31)) * LDH + ks * 16 + 8 * (lane >> 5)];
; #pragma unroll
;       for (int j = 0; j < 2; ++j) bf[j] = *(const h8v*)&Bs[(wn * 64 + j * 32 + (lane & 31)) * LDH + ks * 16 + 8 * (lane >> 5)];
; #pragma unroll
;       for (int i = 0; i < 4; ++i)
; #pragma unroll
;         for (int j = 0; j < 2; ++j) acc[i][j] = mfma32(bf[j], af[i], acc[i][j]);
;     }
;     __syncthreads();
;   }
	s_waitcnt vmcnt(0)
	ds_write_b128 v177, v[158:161]
	ds_write_b128 v215, v[150:153]
	ds_write_b128 v177, v[154:157] offset:16
	ds_write_b128 v215, v[142:145] offset:16
	ds_write_b128 v177, v[146:149] offset:32
	ds_write_b128 v215, v[134:137] offset:32
	ds_write_b128 v177, v[138:141] offset:48
	ds_write_b128 v215, v[130:133] offset:48
	v_lshl_add_u64 v[138:139], v[162:163], 1, s[8:9]
	global_load_dwordx4 v[130:133], v[138:139], off offset:48
	global_load_dwordx4 v[134:137], v[138:139], off offset:32
	global_load_dwordx4 v[142:145], v[138:139], off offset:16
	global_load_dwordx4 v[150:153], v[138:139], off
	s_nop 0
	global_load_dwordx4 v[138:141], v[174:175], off offset:1840
	global_load_dwordx4 v[146:149], v[174:175], off offset:1824
	global_load_dwordx4 v[154:157], v[174:175], off offset:1808
	global_load_dwordx4 v[158:161], v[174:175], off offset:1792
	v_mfma_f32_32x32x16_f16 v[98:113], v[230:233], v[200:203], v[98:113]
	v_mfma_f32_32x32x16_f16 v[114:129], v[234:237], v[200:203], v[114:129]
	v_mfma_f32_32x32x16_f16 v[66:81], v[230:233], v[218:221], v[66:81]
	v_mfma_f32_32x32x16_f16 v[82:97], v[234:237], v[218:221], v[82:97]
	v_mfma_f32_32x32x16_f16 v[34:49], v[230:233], v[222:225], v[34:49]
	v_mfma_f32_32x32x16_f16 v[50:65], v[234:237], v[222:225], v[50:65]
	v_mfma_f32_32x32x16_f16 v[2:17], v[230:233], v[226:229], v[2:17]
	v_mfma_f32_32x32x16_f16 v[18:33], v[234:237], v[226:229], v[18:33]
	ds_read_b128 v[200:203], v171 offset:4608
	ds_read_b128 v[218:221], v171 offset:9216
	ds_read_b128 v[222:225], v171 offset:13824
	ds_read_b128 v[226:229], v1 offset:41472
	ds_read_b128 v[230:233], v171
	ds_read_b128 v[234:237], v171 offset:32
	ds_read_b128 v[238:241], v1 offset:36864
	ds_read_b128 v[242:245], v1 offset:36896
	s_waitcnt lgkmcnt(1)
	v_mfma_f32_32x32x16_f16 v[98:113], v[238:241], v[230:233], v[98:113]
	v_mfma_f32_32x32x16_f16 v[114:129], v[226:229], v[230:233], v[114:129]
	v_mfma_f32_32x32x16_f16 v[66:81], v[238:241], v[200:203], v[66:81]
	v_mfma_f32_32x32x16_f16 v[82:97], v[226:229], v[200:203], v[82:97]
	v_mfma_f32_32x32x16_f16 v[34:49], v[238:241], v[218:221], v[34:49]
	v_mfma_f32_32x32x16_f16 v[50:65], v[226:229], v[218:221], v[50:65]
	v_mfma_f32_32x32x16_f16 v[2:17], v[238:241], v[222:225], v[2:17]
	v_mfma_f32_32x32x16_f16 v[18:33], v[226:229], v[222:225], v[18:33]
	ds_read_b128 v[200:203], v171 offset:4640
	ds_read_b128 v[218:221], v171 offset:9248
	ds_read_b128 v[222:225], v171 offset:13856
	ds_read_b128 v[226:229], v1 offset:41504
	s_waitcnt lgkmcnt(4)
	v_mfma_f32_32x32x16_f16 v[98:113], v[242:245], v[234:237], v[98:113]
	s_waitcnt lgkmcnt(0)
	v_mfma_f32_32x32x16_f16 v[114:129], v[226:229], v[234:237], v[114:129]
	v_mfma_f32_32x32x16_f16 v[66:81], v[242:245], v[200:203], v[66:81]
	v_mfma_f32_32x32x16_f16 v[82:97], v[226:229], v[200:203], v[82:97]
	v_mfma_f32_32x32x16_f16 v[34:49], v[242:245], v[218:221], v[34:49]
	v_mfma_f32_32x32x16_f16 v[50:65], v[226:229], v[218:221], v[50:65]
	v_mfma_f32_32x32x16_f16 v[2:17], v[242:245], v[222:225], v[2:17]
	v_mfma_f32_32x32x16_f16 v[18:33], v[226:229], v[222:225], v[18:33]
	ds_read_b128 v[200:203], v171 offset:64
	ds_read_b128 v[218:221], v171 offset:4672
	ds_read_b128 v[222:225], v171 offset:9280
	ds_read_b128 v[226:229], v171 offset:13888
	ds_read_b128 v[230:233], v1 offset:36928
	ds_read_b128 v[234:237], v1 offset:41536
	s_waitcnt lgkmcnt(1)
	v_mfma_f32_32x32x16_f16 v[98:113], v[230:233], v[200:203], v[98:113]
	s_waitcnt lgkmcnt(0)
	v_mfma_f32_32x32x16_f16 v[114:129], v[234:237], v[200:203], v[114:129]
	v_mfma_f32_32x32x16_f16 v[66:81], v[230:233], v[218:221], v[66:81]
	v_mfma_f32_32x32x16_f16 v[82:97], v[234:237], v[218:221], v[82:97]
	v_mfma_f32_32x32x16_f16 v[34:49], v[230:233], v[222:225], v[34:49]
	v_mfma_f32_32x32x16_f16 v[50:65], v[234:237], v[222:225], v[50:65]
	v_mfma_f32_32x32x16_f16 v[2:17], v[230:233], v[226:229], v[2:17]
	v_mfma_f32_32x32x16_f16 v[18:33], v[234:237], v[226:229], v[18:33]
	ds_read_b128 v[200:203], v171 offset:96
	ds_read_b128 v[218:221], v171 offset:4704
	ds_read_b128 v[222:225], v171 offset:9312
	ds_read_b128 v[226:229], v171 offset:13920
	ds_read_b128 v[230:233], v1 offset:36960
	ds_read_b128 v[234:237], v1 offset:41568
	s_waitcnt lgkmcnt(0)
	s_barrier
	s_waitcnt vmcnt(0)
	ds_write_b128 v216, v[158:161]
	ds_write_b128 v216, v[150:153] offset:36864
	ds_write_b128 v216, v[154:157] offset:16
	ds_write_b128 v216, v[142:145] offset:36880
	ds_write_b128 v216, v[146:149] offset:32
	ds_write_b128 v216, v[134:137] offset:36896
	ds_write_b128 v216, v[138:141] offset:48
	ds_write_b128 v216, v[130:133] offset:36912
	v_lshl_add_u64 v[138:139], v[164:165], 1, s[8:9]
	global_load_dwordx4 v[130:133], v[138:139], off offset:48
	global_load_dwordx4 v[134:137], v[138:139], off offset:32
	global_load_dwordx4 v[142:145], v[138:139], off offset:16
	global_load_dwordx4 v[150:153], v[138:139], off
	s_nop 0
	global_load_dwordx4 v[138:141], v[174:175], off offset:1968
	global_load_dwordx4 v[146:149], v[174:175], off offset:1952
	global_load_dwordx4 v[154:157], v[174:175], off offset:1936
	global_load_dwordx4 v[158:161], v[174:175], off offset:1920
	v_mfma_f32_32x32x16_f16 v[98:113], v[230:233], v[200:203], v[98:113]
	v_mfma_f32_32x32x16_f16 v[114:129], v[234:237], v[200:203], v[114:129]
	v_mfma_f32_32x32x16_f16 v[66:81], v[230:233], v[218:221], v[66:81]
	v_mfma_f32_32x32x16_f16 v[82:97], v[234:237], v[218:221], v[82:97]
	v_mfma_f32_32x32x16_f16 v[34:49], v[230:233], v[222:225], v[34:49]
	v_mfma_f32_32x32x16_f16 v[50:65], v[234:237], v[222:225], v[50:65]
	v_mfma_f32_32x32x16_f16 v[2:17], v[230:233], v[226:229], v[2:17]
	v_mfma_f32_32x32x16_f16 v[18:33], v[234:237], v[226:229], v[18:33]
	ds_read_b128 v[162:165], v178 offset:4608
	ds_read_b128 v[200:203], v178 offset:9216
	ds_read_b128 v[216:219], v178 offset:13824
	ds_read_b128 v[220:223], v179 offset:4608
	ds_read_b128 v[224:227], v178
	ds_read_b128 v[228:231], v178 offset:32
	ds_read_b128 v[232:235], v179
	ds_read_b128 v[236:239], v179 offset:32
	s_waitcnt lgkmcnt(1)
; DI f16v mfma32(h8v a, h8v b, f16v c) { return __builtin_amdgcn_mfma_f32_32x32x16_f16(a, b, c, 0, 0, 0); }
; template <bool GATHER>
; DI void gemm256_main(const h16* __restrict__ A, int lda, const int* __restrict__ idx, int m0,
;                      const h16* __restrict__ B, int ldb, int n0, int K, h16* lds, f16v (&acc)[4][2]) {
;     ...
;   for (int kt = 0; kt < nk; ++kt) {
;     const h16* As = lds + (kt & 1) * (512 * LDH);
;     const h16* Bs = As + 256 * LDH;
;     h16* Wn = lds + ((kt & 1) ^ 1) * (512 * LDH);
;     if (kt + 1 < nk) {
; #pragma unroll
;       for (int i = 0; i < 4; ++i) { *(u4v*)&Wn[lr * LDH + lc + 8 * i] = ra[i]; *(u4v*)&Wn[(256 + lr) * LDH + lc + 8 * i] = rb[i]; }
;     }
;     if (kt + 2 < nk) {
; #pragma unroll
;       for (int i = 0; i < 4; ++i) { ra[i] = *(const u4v*)(AP_ + 8 * i); rb[i] = *(const u4v*)(BP_ + 8 * i); }
;       ao += 64; bo += 64;
;     }
; #pragma unroll
;     for (int ks = 0; ks < 4; ++ks) {
;       h8v af[4], bf[2];
; #pragma unroll
;       for (int i = 0; i < 4; ++i) af[i] = *(const h8v*)&As[(wm * 128 + i * 32 + (lane & 31)) * LDH + ks * 16 + 8 * (lane >> 5)];
; #pragma unroll
;       for (int j = 0; j < 2; ++j) bf[j] = *(const h8v*)&Bs[(wn * 64 + j * 32 + (lane & 31)) * LDH + ks * 16 + 8 * (lane >> 5)];
; #pragma unroll
;       for (int i = 0; i < 4; ++i)
; #pragma unroll
;         for (int j = 0; j < 2; ++j) acc[i][j] = mfma32(bf[j], af[i], acc[i][j]);
;     }
;     __syncthreads();
;   }
	v_mfma_f32_32x32x16_f16 v[98:113], v[232:235], v[224:227], v[98:113]
	v_mfma_f32_32x32x16_f16 v[114:129], v[220:223], v[224:227], v[114:129]
	v_mfma_f32_32x32x16_f16 v[66:81], v[232:235], v[162:165], v[66:81]
	v_mfma_f32_32x32x16_f16 v[82:97], v[220:223], v[162:165], v[82:97]
	v_mfma_f32_32x32x16_f16 v[34:49], v[232:235], v[200:203], v[34:49]
	v_mfma_f32_32x32x16_f16 v[50:65], v[220:223], v[200:203], v[50:65]
	v_mfma_f32_32x32x16_f16 v[2:17], v[232:235], v[216:219], v[2:17]
	v_mfma_f32_32x32x16_f16 v[18:33], v[220:223], v[216:219], v[18:33]
	ds_read_b128 v[162:165], v178 offset:4640
	ds_read_b128 v[200:203], v178 offset:9248
	ds_read_b128 v[216:219], v178 offset:13856
	ds_read_b128 v[220:223], v179 offset:4640
	s_waitcnt lgkmcnt(4)
	v_mfma_f32_32x32x16_f16 v[98:113], v[236:239], v[228:231], v[98:113]
	s_waitcnt lgkmcnt(0)
	v_mfma_f32_32x32x16_f16 v[114:129], v[220:223], v[228:231], v[114:129]
	v_mfma_f32_32x32x16_f16 v[66:81], v[236:239], v[162:165], v[66:81]
	v_mfma_f32_32x32x16_f16 v[82:97], v[220:223], v[162:165], v[82:97]
	v_mfma_f32_32x32x16_f16 v[34:49], v[236:239], v[200:203], v[34:49]
	v_mfma_f32_32x32x16_f16 v[50:65], v[220:223], v[200:203], v[50:65]
	v_mfma_f32_32x32x16_f16 v[2:17], v[236:239], v[216:219], v[2:17]
	v_mfma_f32_32x32x16_f16 v[18:33], v[220:223], v[216:219], v[18:33]
	ds_read_b128 v[162:165], v178 offset:64
	ds_read_b128 v[200:203], v178 offset:4672
	ds_read_b128 v[216:219], v178 offset:9280
	ds_read_b128 v[220:223], v178 offset:13888
	ds_read_b128 v[224:227], v179 offset:64
	ds_read_b128 v[228:231], v179 offset:4672
	s_waitcnt lgkmcnt(1)
	v_mfma_f32_32x32x16_f16 v[98:113], v[224:227], v[162:165], v[98:113]
	s_waitcnt lgkmcnt(0)
	v_mfma_f32_32x32x16_f16 v[114:129], v[228:231], v[162:165], v[114:129]
	v_mfma_f32_32x32x16_f16 v[66:81], v[224:227], v[200:203], v[66:81]
	v_mfma_f32_32x32x16_f16 v[82:97], v[228:231], v[200:203], v[82:97]
	v_mfma_f32_32x32x16_f16 v[34:49], v[224:227], v[216:219], v[34:49]
	v_mfma_f32_32x32x16_f16 v[50:65], v[228:231], v[216:219], v[50:65]
	v_mfma_f32_32x32x16_f16 v[2:17], v[224:227], v[220:223], v[2:17]
	v_mfma_f32_32x32x16_f16 v[18:33], v[228:231], v[220:223], v[18:33]
	ds_read_b128 v[162:165], v178 offset:96
	ds_read_b128 v[200:203], v178 offset:4704
	ds_read_b128 v[216:219], v178 offset:9312
	ds_read_b128 v[220:223], v178 offset:13920
	ds_read_b128 v[224:227], v179 offset:96
	ds_read_b128 v[228:231], v179 offset:4704
	s_waitcnt lgkmcnt(0)
	s_barrier
	s_waitcnt vmcnt(0)
	ds_write_b128 v177, v[158:161]
	ds_write_b128 v215, v[150:153]
	ds_write_b128 v177, v[154:157] offset:16
	ds_write_b128 v215, v[142:145] offset:16
	ds_write_b128 v177, v[146:149] offset:32
	ds_write_b128 v215, v[134:137] offset:32
	ds_write_b128 v177, v[138:141] offset:48
	ds_write_b128 v215, v[130:133] offset:48
	ds_read_b128 v[130:133], v171 offset:4608
	ds_read_b128 v[134:137], v171 offset:9216
	ds_read_b128 v[138:141], v171 offset:13824
	ds_read_b128 v[142:145], v1 offset:41472
	ds_read_b128 v[146:149], v171
	ds_read_b128 v[150:153], v171 offset:32
	ds_read_b128 v[154:157], v1 offset:36864
	ds_read_b128 v[158:161], v1 offset:36896
	v_mfma_f32_32x32x16_f16 v[98:113], v[224:227], v[162:165], v[98:113]
	v_mfma_f32_32x32x16_f16 v[114:129], v[228:231], v[162:165], v[114:129]
	v_mfma_f32_32x32x16_f16 v[66:81], v[224:227], v[200:203], v[66:81]
	v_mfma_f32_32x32x16_f16 v[82:97], v[228:231], v[200:203], v[82:97]
	v_mfma_f32_32x32x16_f16 v[34:49], v[224:227], v[216:219], v[34:49]
	v_mfma_f32_32x32x16_f16 v[50:65], v[228:231], v[216:219], v[50:65]
	v_mfma_f32_32x32x16_f16 v[2:17], v[224:227], v[220:223], v[2:17]
	v_mfma_f32_32x32x16_f16 v[18:33], v[228:231], v[220:223], v[18:33]
	s_waitcnt lgkmcnt(1)
	v_mfma_f32_32x32x16_f16 v[98:113], v[154:157], v[146:149], v[98:113]
	v_mfma_f32_32x32x16_f16 v[114:129], v[142:145], v[146:149], v[114:129]
	v_mfma_f32_32x32x16_f16 v[66:81], v[154:157], v[130:133], v[66:81]
	v_mfma_f32_32x32x16_f16 v[82:97], v[142:145], v[130:133], v[82:97]
	v_mfma_f32_32x32x16_f16 v[34:49], v[154:157], v[134:137], v[34:49]
	v_mfma_f32_32x32x16_f16 v[50:65], v[142:145], v[134:137], v[50:65]
	v_mfma_f32_32x32x16_f16 v[2:17], v[154:157], v[138:141], v[2:17]
	v_mfma_f32_32x32x16_f16 v[18:33], v[142:145], v[138:141], v[18:33]
	ds_read_b128 v[130:133], v171 offset:4640
	ds_read_b128 v[134:137], v171 offset:9248
	ds_read_b128 v[138:141], v171 offset:13856
	ds_read_b128 v[142:145], v1 offset:41504
	s_waitcnt lgkmcnt(4)
	v_mfma_f32_32x32x16_f16 v[98:113], v[158:161], v[150:153], v[98:113]
	s_waitcnt lgkmcnt(0)
	v_mfma_f32_32x32x16_f16 v[114:129], v[142:145], v[150:153], v[114:129]
	v_mfma_f32_32x32x16_f16 v[66:81], v[158:161], v[130:133], v[66:81]
	v_mfma_f32_32x32x16_f16 v[82:97], v[142:145], v[130:133], v[82:97]
	v_mfma_f32_32x32x16_f16 v[34:49], v[158:161], v[134:137], v[34:49]
	v_mfma_f32_32x32x16_f16 v[50:65], v[142:145], v[134:137], v[50:65]
	v_mfma_f32_32x32x16_f16 v[2:17], v[158:161], v[138:141], v[2:17]
	v_mfma_f32_32x32x16_f16 v[18:33], v[142:145], v[138:141], v[18:33]
	ds_read_b128 v[130:133], v171 offset:64
	ds_read_b128 v[134:137], v171 offset:4672
	ds_read_b128 v[138:141], v171 offset:9280
	ds_read_b128 v[142:145], v171 offset:13888
	ds_read_b128 v[146:149], v1 offset:36928
	ds_read_b128 v[150:153], v1 offset:41536
	s_waitcnt lgkmcnt(1)
	v_mfma_f32_32x32x16_f16 v[98:113], v[146:149], v[130:133], v[98:113]
	s_waitcnt lgkmcnt(0)
	v_mfma_f32_32x32x16_f16 v[114:129], v[150:153], v[130:133], v[114:129]
	v_mfma_f32_32x32x16_f16 v[66:81], v[146:149], v[134:137], v[66:81]
	v_mfma_f32_32x32x16_f16 v[82:97], v[150:153], v[134:137], v[82:97]
	v_mfma_f32_32x32x16_f16 v[34:49], v[146:149], v[138:141], v[34:49]
	v_mfma_f32_32x32x16_f16 v[50:65], v[150:153], v[138:141], v[50:65]
	v_mfma_f32_32x32x16_f16 v[2:17], v[146:149], v[142:145], v[2:17]
	v_mfma_f32_32x32x16_f16 v[18:33], v[150:153], v[142:145], v[18:33]
	ds_read_b128 v[130:133], v171 offset:96
	ds_read_b128 v[134:137], v171 offset:4704
	ds_read_b128 v[138:141], v171 offset:9312
	ds_read_b128 v[142:145], v171 offset:13920
	ds_read_b128 v[146:149], v1 offset:36960
	ds_read_b128 v[150:153], v1 offset:41568
	s_waitcnt lgkmcnt(0)
	s_barrier
; DI float silu_(float x) { return x / (1.f + __expf(-x)); }
; DI f16v mfma32(h8v a, h8v b, f16v c) { return __builtin_amdgcn_mfma_f32_32x32x16_f16(a, b, c, 0, 0, 0); }
; template <bool GATHER>
; DI void gemm256_main(const h16* __restrict__ A, int lda, const int* __restrict__ idx, int m0,
;                      const h16* __restrict__ B, int ldb, int n0, int K, h16* lds, f16v (&acc)[4][2]) {
;     ...
; #pragma unroll
;     for (int ks = 0; ks < 4; ++ks) {
;       h8v af[4], bf[2];
; #pragma unroll
;       for (int i = 0; i < 4; ++i) af[i] = *(const h8v*)&As[(wm * 128 + i * 32 + (lane & 31)) * LDH + ks * 16 + 8 * (lane >> 5)];
; #pragma unroll
;       for (int j = 0; j < 2; ++j) bf[j] = *(const h8v*)&Bs[(wn * 64 + j * 32 + (lane & 31)) * LDH + ks * 16 + 8 * (lane >> 5)];
; #pragma unroll
;       for (int i = 0; i < 4; ++i)
; #pragma unroll
;         for (int j = 0; j < 2; ++j) acc[i][j] = mfma32(bf[j], af[i], acc[i][j]);
;     }
;     __syncthreads();
; DI void phase_ffn1_dense(const Params& p, int bid, int nb, h16* lds) {
;     ...
;     gemm256_epilogue(acc, m0, n0, [&](int m, int n, f4v v0, f4v v1) {
;       f4v hq;
; #pragma unroll
;       for (int i = 0; i < 4; ++i) hq[i] = silu_(v0[i]) * v1[i];
;       st_h4(&H[(size_t)m * 2816 + (n >> 6) * 32 + (n & 31)], hq);
	v_mfma_f32_32x32x16_f16 v[98:113], v[146:149], v[130:133], v[98:113]
	v_mfma_f32_32x32x16_f16 v[114:129], v[150:153], v[130:133], v[114:129]
	v_mfma_f32_32x32x16_f16 v[66:81], v[146:149], v[134:137], v[66:81]
	v_mfma_f32_32x32x16_f16 v[82:97], v[150:153], v[134:137], v[82:97]
	v_mfma_f32_32x32x16_f16 v[34:49], v[146:149], v[138:141], v[34:49]
	v_mfma_f32_32x32x16_f16 v[50:65], v[150:153], v[138:141], v[50:65]
	v_mfma_f32_32x32x16_f16 v[2:17], v[146:149], v[142:145], v[2:17]
	v_mfma_f32_32x32x16_f16 v[18:33], v[150:153], v[142:145], v[18:33]
	ds_read_b128 v[130:133], v178 offset:4608
	ds_read_b128 v[134:137], v178 offset:9216
	ds_read_b128 v[138:141], v178 offset:13824
	ds_read_b128 v[142:145], v179 offset:4608
	ds_read_b128 v[146:149], v178
	ds_read_b128 v[150:153], v178 offset:32
	ds_read_b128 v[154:157], v179
	ds_read_b128 v[158:161], v179 offset:32
	s_waitcnt lgkmcnt(1)
	v_mfma_f32_32x32x16_f16 v[98:113], v[154:157], v[146:149], v[98:113]
	v_mfma_f32_32x32x16_f16 v[114:129], v[142:145], v[146:149], v[114:129]
	v_mfma_f32_32x32x16_f16 v[66:81], v[154:157], v[130:133], v[66:81]
	v_mfma_f32_32x32x16_f16 v[82:97], v[142:145], v[130:133], v[82:97]
	v_mfma_f32_32x32x16_f16 v[34:49], v[154:157], v[134:137], v[34:49]
	v_mfma_f32_32x32x16_f16 v[50:65], v[142:145], v[134:137], v[50:65]
	v_mfma_f32_32x32x16_f16 v[2:17], v[154:157], v[138:141], v[2:17]
	v_mfma_f32_32x32x16_f16 v[18:33], v[142:145], v[138:141], v[18:33]
	ds_read_b128 v[130:133], v178 offset:4640
	ds_read_b128 v[134:137], v178 offset:9248
	ds_read_b128 v[138:141], v178 offset:13856
	ds_read_b128 v[142:145], v179 offset:4640
	s_waitcnt lgkmcnt(4)
	v_mfma_f32_32x32x16_f16 v[98:113], v[158:161], v[150:153], v[98:113]
	s_waitcnt lgkmcnt(0)
	v_mfma_f32_32x32x16_f16 v[114:129], v[142:145], v[150:153], v[114:129]
	v_mfma_f32_32x32x16_f16 v[66:81], v[158:161], v[130:133], v[66:81]
	v_mfma_f32_32x32x16_f16 v[82:97], v[142:145], v[130:133], v[82:97]
	v_mfma_f32_32x32x16_f16 v[34:49], v[158:161], v[134:137], v[34:49]
	v_mfma_f32_32x32x16_f16 v[50:65], v[142:145], v[134:137], v[50:65]
	v_mfma_f32_32x32x16_f16 v[2:17], v[158:161], v[138:141], v[2:17]
	v_mfma_f32_32x32x16_f16 v[18:33], v[142:145], v[138:141], v[18:33]
	ds_read_b128 v[130:133], v178 offset:64
	ds_read_b128 v[134:137], v178 offset:4672
	ds_read_b128 v[138:141], v178 offset:9280
	ds_read_b128 v[142:145], v178 offset:13888
	ds_read_b128 v[146:149], v179 offset:64
	ds_read_b128 v[150:153], v179 offset:4672
	s_waitcnt lgkmcnt(1)
	v_mfma_f32_32x32x16_f16 v[98:113], v[146:149], v[130:133], v[98:113]
	s_waitcnt lgkmcnt(0)
	v_mfma_f32_32x32x16_f16 v[114:129], v[150:153], v[130:133], v[114:129]
	v_mfma_f32_32x32x16_f16 v[66:81], v[146:149], v[134:137], v[66:81]
	v_mfma_f32_32x32x16_f16 v[82:97], v[150:153], v[134:137], v[82:97]
	v_mfma_f32_32x32x16_f16 v[34:49], v[146:149], v[138:141], v[34:49]
	v_mfma_f32_32x32x16_f16 v[50:65], v[150:153], v[138:141], v[50:65]
	v_mfma_f32_32x32x16_f16 v[2:17], v[146:149], v[142:145], v[2:17]
	v_mfma_f32_32x32x16_f16 v[18:33], v[150:153], v[142:145], v[18:33]
	ds_read_b128 v[130:133], v178 offset:96
	ds_read_b128 v[134:137], v178 offset:4704
	ds_read_b128 v[138:141], v178 offset:9312
	ds_read_b128 v[142:145], v178 offset:13920
	ds_read_b128 v[146:149], v179 offset:96
	ds_read_b128 v[150:153], v179 offset:4704
	s_waitcnt lgkmcnt(0)
	s_barrier
	v_mfma_f32_32x32x16_f16 v[98:113], v[146:149], v[130:133], v[98:113]
	v_mfma_f32_32x32x16_f16 v[2:17], v[146:149], v[142:145], v[2:17]
	v_mfma_f32_32x32x16_f16 v[18:33], v[150:153], v[142:145], v[18:33]
	v_mfma_f32_32x32x16_f16 v[114:129], v[150:153], v[130:133], v[114:129]
	v_mfma_f32_32x32x16_f16 v[66:81], v[146:149], v[134:137], v[66:81]
	v_mfma_f32_32x32x16_f16 v[82:97], v[150:153], v[134:137], v[82:97]
	v_mfma_f32_32x32x16_f16 v[34:49], v[146:149], v[138:141], v[34:49]
	v_mfma_f32_32x32x16_f16 v[50:65], v[150:153], v[138:141], v[50:65]
	s_nop 15
	s_barrier
	v_readfirstlane_b32 s66, v180
	s_sub_i32 s69, s2, s5
	s_mov_b32 s65, s4
	s_lshr_b32 s66, s66, 6
	s_and_b32 s67, s66, 3
	s_lshr_b32 s68, s66, 2
	s_lshr_b32 s70, s69, 1
	s_lshl_b32 s67, s67, 5
	s_add_i32 s70, s70, s67
	s_lshl_b32 s71, s68, 7
	s_add_i32 s71, s71, s65
	s_mul_i32 s72, s66, 0x2800
	s_add_i32 s72, s72, 16
	s_mov_b32 s73, 0x1600
	v_and_b32_e32 v146, 63, v180
	v_and_b32_e32 v148, 31, v146
	v_lshrrev_b32_e32 v147, 5, v146
	v_mul_u32_u24_e32 v130, 0x50, v148
	v_lshl_add_u32 v130, v147, 3, v130
	v_add_u32_e32 v130, s72, v130
	v_lshrrev_b32_e32 v149, 2, v146
	v_and_b32_e32 v138, 3, v146
	v_mul_u32_u24_e32 v131, 0x50, v149
	v_lshl_add_u32 v131, v138, 4, v131
	v_add_u32_e32 v131, s72, v131
	v_add_u32_e32 v140, s71, v149
	v_lshl_add_u32 v138, v138, 3, s70
	v_mov_b64_e32 v[132:133], s[0:1]
	v_mad_u64_u32 v[132:133], s[74:75], v140, s73, v[132:133]
	v_lshlrev_b32_e32 v138, 1, v138
	v_mov_b32_e32 v139, v0
	v_lshl_add_u64 v[132:133], v[132:133], 0, v[138:139]
	s_mov_b32 s76, 0x16000
	s_mov_b32 s77, 0
	v_mul_f32_e32 v232, 0xbfb8aa3b, v98
	v_mul_f32_e32 v233, 0xbfb8aa3b, v99
	v_mul_f32_e32 v234, 0xbfb8aa3b, v100
	v_mul_f32_e32 v235, 0xbfb8aa3b, v101
	v_exp_f32_e32 v232, v232
	v_exp_f32_e32 v233, v233
	v_exp_f32_e32 v234, v234
	v_exp_f32_e32 v235, v235
	v_add_f32_e32 v232, 1.0, v232
	v_add_f32_e32 v233, 1.0, v233
	v_add_f32_e32 v234, 1.0, v234
	v_add_f32_e32 v235, 1.0, v235
	v_rcp_f32_e32 v232, v232
	v_rcp_f32_e32 v233, v233
	v_rcp_f32_e32 v234, v234
	v_rcp_f32_e32 v235, v235
	v_mul_f32_e32 v98, v98, v232
	v_mul_f32_e32 v99, v99, v233
	v_mul_f32_e32 v100, v100, v234
	v_mul_f32_e32 v101, v101, v235
	v_mul_f32_e32 v98, v98, v114
	v_mul_f32_e32 v99, v99, v115
	v_mul_f32_e32 v100, v100, v116
	v_mul_f32_e32 v101, v101, v117
; DI int otid512() { int t = threadIdx.x; asm volatile("" : "+v"(t)); return t; }
; DI float silu_(float x) { return x / (1.f + __expf(-x)); }
; template <class Epi>
; DI void gemm256_epilogue(f16v (&acc)[4][2], int m0, int n0, Epi epi) {
;   const int tid = otid512(), lane = tid & 63, wv = tid >> 6, wm = wv >> 2, wn = wv & 3, h = lane >> 5;
; #pragma unroll
;   for (int i = 0; i < 4; ++i) {
;     const int m = m0 + wm * 128 + i * 32 + (lane & 31);
; #pragma unroll
;     for (int g = 0; g < 4; ++g) {
;       const int n = n0 + wn * 64 + 8 * g + 4 * h;
;       f4v v0 = {acc[i][0][4 * g], acc[i][0][4 * g + 1], acc[i][0][4 * g + 2], acc[i][0][4 * g + 3]};
;       f4v v1 = {acc[i][1][4 * g], acc[i][1][4 * g + 1], acc[i][1][4 * g + 2], acc[i][1][4 * g + 3]};
;       epi(m, n, v0, v1);
;     }
;   }
; }
; DI void phase_ffn1_dense(const Params& p, int bid, int nb, h16* lds) {
;     ...
;     gemm256_epilogue(acc, m0, n0, [&](int m, int n, f4v v0, f4v v1) {
;       f4v hq;
; #pragma unroll
;       for (int i = 0; i < 4; ++i) hq[i] = silu_(v0[i]) * v1[i];
;       st_h4(&H[(size_t)m * 2816 + (n >> 6) * 32 + (n & 31)], hq);
	v_cvt_pk_f16_f32 v138, v98, v99
	v_cvt_pk_f16_f32 v139, v100, v101
	ds_write_b64 v130, v[138:139] offset:0
	v_mul_f32_e32 v232, 0xbfb8aa3b, v102
	v_mul_f32_e32 v233, 0xbfb8aa3b, v103
	v_mul_f32_e32 v234, 0xbfb8aa3b, v104
	v_mul_f32_e32 v235, 0xbfb8aa3b, v105
	v_exp_f32_e32 v232, v232
	v_exp_f32_e32 v233, v233
	v_exp_f32_e32 v234, v234
	v_exp_f32_e32 v235, v235
	v_add_f32_e32 v232, 1.0, v232
	v_add_f32_e32 v233, 1.0, v233
	v_add_f32_e32 v234, 1.0, v234
	v_add_f32_e32 v235, 1.0, v235
	v_rcp_f32_e32 v232, v232
	v_rcp_f32_e32 v233, v233
	v_rcp_f32_e32 v234, v234
	v_rcp_f32_e32 v235, v235
	v_mul_f32_e32 v102, v102, v232
	v_mul_f32_e32 v103, v103, v233
	v_mul_f32_e32 v104, v104, v234
	v_mul_f32_e32 v105, v105, v235
	v_mul_f32_e32 v102, v102, v118
	v_mul_f32_e32 v103, v103, v119
	v_mul_f32_e32 v104, v104, v120
	v_mul_f32_e32 v105, v105, v121
	v_cvt_pk_f16_f32 v140, v102, v103
	v_cvt_pk_f16_f32 v141, v104, v105
	ds_write_b64 v130, v[140:141] offset:16
	v_mul_f32_e32 v232, 0xbfb8aa3b, v106
	v_mul_f32_e32 v233, 0xbfb8aa3b, v107
	v_mul_f32_e32 v234, 0xbfb8aa3b, v108
	v_mul_f32_e32 v235, 0xbfb8aa3b, v109
	v_exp_f32_e32 v232, v232
	v_exp_f32_e32 v233, v233
	v_exp_f32_e32 v234, v234
	v_exp_f32_e32 v235, v235
	v_add_f32_e32 v232, 1.0, v232
	v_add_f32_e32 v233, 1.0, v233
	v_add_f32_e32 v234, 1.0, v234
	v_add_f32_e32 v235, 1.0, v235
	v_rcp_f32_e32 v232, v232
	v_rcp_f32_e32 v233, v233
	v_rcp_f32_e32 v234, v234
	v_rcp_f32_e32 v235, v235
	v_mul_f32_e32 v106, v106, v232
	v_mul_f32_e32 v107, v107, v233
	v_mul_f32_e32 v108, v108, v234
	v_mul_f32_e32 v109, v109, v235
	v_mul_f32_e32 v106, v106, v122
	v_mul_f32_e32 v107, v107, v123
	v_mul_f32_e32 v108, v108, v124
	v_mul_f32_e32 v109, v109, v125
	v_cvt_pk_f16_f32 v142, v106, v107
	v_cvt_pk_f16_f32 v143, v108, v109
	ds_write_b64 v130, v[142:143] offset:32
	v_mul_f32_e32 v232, 0xbfb8aa3b, v110
	v_mul_f32_e32 v233, 0xbfb8aa3b, v111
	v_mul_f32_e32 v234, 0xbfb8aa3b, v112
	v_mul_f32_e32 v235, 0xbfb8aa3b, v113
	v_exp_f32_e32 v232, v232
	v_exp_f32_e32 v233, v233
	v_exp_f32_e32 v234, v234
	v_exp_f32_e32 v235, v235
	v_add_f32_e32 v232, 1.0, v232
	v_add_f32_e32 v233, 1.0, v233
	v_add_f32_e32 v234, 1.0, v234
	v_add_f32_e32 v235, 1.0, v235
	v_rcp_f32_e32 v232, v232
	v_rcp_f32_e32 v233, v233
	v_rcp_f32_e32 v234, v234
	v_rcp_f32_e32 v235, v235
	v_mul_f32_e32 v110, v110, v232
	v_mul_f32_e32 v111, v111, v233
	v_mul_f32_e32 v112, v112, v234
	v_mul_f32_e32 v113, v113, v235
	v_mul_f32_e32 v110, v110, v126
	v_mul_f32_e32 v111, v111, v127
	v_mul_f32_e32 v112, v112, v128
	v_mul_f32_e32 v113, v113, v129
	v_cvt_pk_f16_f32 v144, v110, v111
	v_cvt_pk_f16_f32 v145, v112, v113
	ds_write_b64 v130, v[144:145] offset:48
	v_mul_f32_e32 v232, 0xbfb8aa3b, v66
	v_mul_f32_e32 v233, 0xbfb8aa3b, v67
	v_mul_f32_e32 v234, 0xbfb8aa3b, v68
	v_mul_f32_e32 v235, 0xbfb8aa3b, v69
	v_exp_f32_e32 v232, v232
	v_exp_f32_e32 v233, v233
	v_exp_f32_e32 v234, v234
	v_exp_f32_e32 v235, v235
	v_add_f32_e32 v232, 1.0, v232
	v_add_f32_e32 v233, 1.0, v233
	v_add_f32_e32 v234, 1.0, v234
	v_add_f32_e32 v235, 1.0, v235
	v_rcp_f32_e32 v232, v232
	v_rcp_f32_e32 v233, v233
	v_rcp_f32_e32 v234, v234
	v_rcp_f32_e32 v235, v235
	v_mul_f32_e32 v66, v66, v232
	v_mul_f32_e32 v67, v67, v233
	v_mul_f32_e32 v68, v68, v234
	v_mul_f32_e32 v69, v69, v235
	v_mul_f32_e32 v66, v66, v82
	v_mul_f32_e32 v67, v67, v83
	v_mul_f32_e32 v68, v68, v84
	v_mul_f32_e32 v69, v69, v85
	v_cvt_pk_f16_f32 v138, v66, v67
	v_cvt_pk_f16_f32 v139, v68, v69
	ds_write_b64 v130, v[138:139] offset:2560
	v_mul_f32_e32 v232, 0xbfb8aa3b, v70
	v_mul_f32_e32 v233, 0xbfb8aa3b, v71
	v_mul_f32_e32 v234, 0xbfb8aa3b, v72
	v_mul_f32_e32 v235, 0xbfb8aa3b, v73
	v_exp_f32_e32 v232, v232
	v_exp_f32_e32 v233, v233
	v_exp_f32_e32 v234, v234
	v_exp_f32_e32 v235, v235
	v_add_f32_e32 v232, 1.0, v232
	v_add_f32_e32 v233, 1.0, v233
	v_add_f32_e32 v234, 1.0, v234
	v_add_f32_e32 v235, 1.0, v235
	v_rcp_f32_e32 v232, v232
	v_rcp_f32_e32 v233, v233
	v_rcp_f32_e32 v234, v234
	v_rcp_f32_e32 v235, v235
	v_mul_f32_e32 v70, v70, v232
	v_mul_f32_e32 v71, v71, v233
	v_mul_f32_e32 v72, v72, v234
	v_mul_f32_e32 v73, v73, v235
	v_mul_f32_e32 v70, v70, v86
	v_mul_f32_e32 v71, v71, v87
	v_mul_f32_e32 v72, v72, v88
	v_mul_f32_e32 v73, v73, v89
	v_cvt_pk_f16_f32 v140, v70, v71
	v_cvt_pk_f16_f32 v141, v72, v73
	ds_write_b64 v130, v[140:141] offset:2576
	v_mul_f32_e32 v232, 0xbfb8aa3b, v74
	v_mul_f32_e32 v233, 0xbfb8aa3b, v75
	v_mul_f32_e32 v234, 0xbfb8aa3b, v76
	v_mul_f32_e32 v235, 0xbfb8aa3b, v77
	v_exp_f32_e32 v232, v232
	v_exp_f32_e32 v233, v233
	v_exp_f32_e32 v234, v234
	v_exp_f32_e32 v235, v235
	v_add_f32_e32 v232, 1.0, v232
	v_add_f32_e32 v233, 1.0, v233
	v_add_f32_e32 v234, 1.0, v234
	v_add_f32_e32 v235, 1.0, v235
	v_rcp_f32_e32 v232, v232
	v_rcp_f32_e32 v233, v233
	v_rcp_f32_e32 v234, v234
	v_rcp_f32_e32 v235, v235
	v_mul_f32_e32 v74, v74, v232
	v_mul_f32_e32 v75, v75, v233
	v_mul_f32_e32 v76, v76, v234
	v_mul_f32_e32 v77, v77, v235
	v_mul_f32_e32 v74, v74, v90
	v_mul_f32_e32 v75, v75, v91
	v_mul_f32_e32 v76, v76, v92
	v_mul_f32_e32 v77, v77, v93
	v_cvt_pk_f16_f32 v142, v74, v75
	v_cvt_pk_f16_f32 v143, v76, v77
	ds_write_b64 v130, v[142:143] offset:2592
	v_mul_f32_e32 v232, 0xbfb8aa3b, v78
	v_mul_f32_e32 v233, 0xbfb8aa3b, v79
	v_mul_f32_e32 v234, 0xbfb8aa3b, v80
	v_mul_f32_e32 v235, 0xbfb8aa3b, v81
	v_exp_f32_e32 v232, v232
	v_exp_f32_e32 v233, v233
	v_exp_f32_e32 v234, v234
	v_exp_f32_e32 v235, v235
	v_add_f32_e32 v232, 1.0, v232
	v_add_f32_e32 v233, 1.0, v233
	v_add_f32_e32 v234, 1.0, v234
	v_add_f32_e32 v235, 1.0, v235
	v_rcp_f32_e32 v232, v232
	v_rcp_f32_e32 v233, v233
	v_rcp_f32_e32 v234, v234
	v_rcp_f32_e32 v235, v235
	v_mul_f32_e32 v78, v78, v232
; DI int otid512() { int t = threadIdx.x; asm volatile("" : "+v"(t)); return t; }
; DI float silu_(float x) { return x / (1.f + __expf(-x)); }
; template <class Epi>
; DI void gemm256_epilogue(f16v (&acc)[4][2], int m0, int n0, Epi epi) {
;   const int tid = otid512(), lane = tid & 63, wv = tid >> 6, wm = wv >> 2, wn = wv & 3, h = lane >> 5;
; #pragma unroll
;   for (int i = 0; i < 4; ++i) {
;     const int m = m0 + wm * 128 + i * 32 + (lane & 31);
; #pragma unroll
;     for (int g = 0; g < 4; ++g) {
;       const int n = n0 + wn * 64 + 8 * g + 4 * h;
;       f4v v0 = {acc[i][0][4 * g], acc[i][0][4 * g + 1], acc[i][0][4 * g + 2], acc[i][0][4 * g + 3]};
;       f4v v1 = {acc[i][1][4 * g], acc[i][1][4 * g + 1], acc[i][1][4 * g + 2], acc[i][1][4 * g + 3]};
;       epi(m, n, v0, v1);
;     }
;   }
; }
; DI void phase_ffn1_dense(const Params& p, int bid, int nb, h16* lds) {
;     ...
;     gemm256_epilogue(acc, m0, n0, [&](int m, int n, f4v v0, f4v v1) {
;       f4v hq;
; #pragma unroll
;       for (int i = 0; i < 4; ++i) hq[i] = silu_(v0[i]) * v1[i];
;       st_h4(&H[(size_t)m * 2816 + (n >> 6) * 32 + (n & 31)], hq);
	v_mul_f32_e32 v79, v79, v233
	v_mul_f32_e32 v80, v80, v234
	v_mul_f32_e32 v81, v81, v235
	v_mul_f32_e32 v78, v78, v94
	v_mul_f32_e32 v79, v79, v95
	v_mul_f32_e32 v80, v80, v96
	v_mul_f32_e32 v81, v81, v97
	v_cvt_pk_f16_f32 v144, v78, v79
	v_cvt_pk_f16_f32 v145, v80, v81
	ds_write_b64 v130, v[144:145] offset:2608
	v_mul_f32_e32 v232, 0xbfb8aa3b, v34
	v_mul_f32_e32 v233, 0xbfb8aa3b, v35
	v_mul_f32_e32 v234, 0xbfb8aa3b, v36
	v_mul_f32_e32 v235, 0xbfb8aa3b, v37
	v_exp_f32_e32 v232, v232
	v_exp_f32_e32 v233, v233
	v_exp_f32_e32 v234, v234
	v_exp_f32_e32 v235, v235
	v_add_f32_e32 v232, 1.0, v232
	v_add_f32_e32 v233, 1.0, v233
	v_add_f32_e32 v234, 1.0, v234
	v_add_f32_e32 v235, 1.0, v235
	v_rcp_f32_e32 v232, v232
	v_rcp_f32_e32 v233, v233
	v_rcp_f32_e32 v234, v234
	v_rcp_f32_e32 v235, v235
	v_mul_f32_e32 v34, v34, v232
	v_mul_f32_e32 v35, v35, v233
	v_mul_f32_e32 v36, v36, v234
	v_mul_f32_e32 v37, v37, v235
	v_mul_f32_e32 v34, v34, v50
	v_mul_f32_e32 v35, v35, v51
	v_mul_f32_e32 v36, v36, v52
	v_mul_f32_e32 v37, v37, v53
	v_cvt_pk_f16_f32 v138, v34, v35
	v_cvt_pk_f16_f32 v139, v36, v37
	ds_write_b64 v130, v[138:139] offset:5120
	v_mul_f32_e32 v232, 0xbfb8aa3b, v38
	v_mul_f32_e32 v233, 0xbfb8aa3b, v39
	v_mul_f32_e32 v234, 0xbfb8aa3b, v40
	v_mul_f32_e32 v235, 0xbfb8aa3b, v41
	v_exp_f32_e32 v232, v232
	v_exp_f32_e32 v233, v233
	v_exp_f32_e32 v234, v234
	v_exp_f32_e32 v235, v235
	v_add_f32_e32 v232, 1.0, v232
	v_add_f32_e32 v233, 1.0, v233
	v_add_f32_e32 v234, 1.0, v234
	v_add_f32_e32 v235, 1.0, v235
	v_rcp_f32_e32 v232, v232
	v_rcp_f32_e32 v233, v233
	v_rcp_f32_e32 v234, v234
	v_rcp_f32_e32 v235, v235
	v_mul_f32_e32 v38, v38, v232
	v_mul_f32_e32 v39, v39, v233
	v_mul_f32_e32 v40, v40, v234
	v_mul_f32_e32 v41, v41, v235
	v_mul_f32_e32 v38, v38, v54
	v_mul_f32_e32 v39, v39, v55
	v_mul_f32_e32 v40, v40, v56
	v_mul_f32_e32 v41, v41, v57
	v_cvt_pk_f16_f32 v140, v38, v39
	v_cvt_pk_f16_f32 v141, v40, v41
	ds_write_b64 v130, v[140:141] offset:5136
	v_mul_f32_e32 v232, 0xbfb8aa3b, v42
	v_mul_f32_e32 v233, 0xbfb8aa3b, v43
	v_mul_f32_e32 v234, 0xbfb8aa3b, v44
	v_mul_f32_e32 v235, 0xbfb8aa3b, v45
	v_exp_f32_e32 v232, v232
	v_exp_f32_e32 v233, v233
	v_exp_f32_e32 v234, v234
	v_exp_f32_e32 v235, v235
	v_add_f32_e32 v232, 1.0, v232
	v_add_f32_e32 v233, 1.0, v233
	v_add_f32_e32 v234, 1.0, v234
	v_add_f32_e32 v235, 1.0, v235
	v_rcp_f32_e32 v232, v232
	v_rcp_f32_e32 v233, v233
	v_rcp_f32_e32 v234, v234
	v_rcp_f32_e32 v235, v235
	v_mul_f32_e32 v42, v42, v232
	v_mul_f32_e32 v43, v43, v233
	v_mul_f32_e32 v44, v44, v234
	v_mul_f32_e32 v45, v45, v235
	v_mul_f32_e32 v42, v42, v58
	v_mul_f32_e32 v43, v43, v59
	v_mul_f32_e32 v44, v44, v60
	v_mul_f32_e32 v45, v45, v61
	v_cvt_pk_f16_f32 v142, v42, v43
	v_cvt_pk_f16_f32 v143, v44, v45
	ds_write_b64 v130, v[142:143] offset:5152
	v_mul_f32_e32 v232, 0xbfb8aa3b, v46
	v_mul_f32_e32 v233, 0xbfb8aa3b, v47
	v_mul_f32_e32 v234, 0xbfb8aa3b, v48
	v_mul_f32_e32 v235, 0xbfb8aa3b, v49
	v_exp_f32_e32 v232, v232
	v_exp_f32_e32 v233, v233
	v_exp_f32_e32 v234, v234
	v_exp_f32_e32 v235, v235
	v_add_f32_e32 v232, 1.0, v232
	v_add_f32_e32 v233, 1.0, v233
	v_add_f32_e32 v234, 1.0, v234
	v_add_f32_e32 v235, 1.0, v235
	v_rcp_f32_e32 v232, v232
	v_rcp_f32_e32 v233, v233
	v_rcp_f32_e32 v234, v234
	v_rcp_f32_e32 v235, v235
	v_mul_f32_e32 v46, v46, v232
	v_mul_f32_e32 v47, v47, v233
	v_mul_f32_e32 v48, v48, v234
	v_mul_f32_e32 v49, v49, v235
	v_mul_f32_e32 v46, v46, v62
	v_mul_f32_e32 v47, v47, v63
	v_mul_f32_e32 v48, v48, v64
	v_mul_f32_e32 v49, v49, v65
	v_cvt_pk_f16_f32 v144, v46, v47
	v_cvt_pk_f16_f32 v145, v48, v49
	ds_write_b64 v130, v[144:145] offset:5168
	v_mul_f32_e32 v232, 0xbfb8aa3b, v2
	v_mul_f32_e32 v233, 0xbfb8aa3b, v3
	v_mul_f32_e32 v234, 0xbfb8aa3b, v4
	v_mul_f32_e32 v235, 0xbfb8aa3b, v5
	v_exp_f32_e32 v232, v232
	v_exp_f32_e32 v233, v233
	v_exp_f32_e32 v234, v234
	v_exp_f32_e32 v235, v235
	v_add_f32_e32 v232, 1.0, v232
	v_add_f32_e32 v233, 1.0, v233
	v_add_f32_e32 v234, 1.0, v234
	v_add_f32_e32 v235, 1.0, v235
	v_rcp_f32_e32 v232, v232
	v_rcp_f32_e32 v233, v233
	v_rcp_f32_e32 v234, v234
	v_rcp_f32_e32 v235, v235
	v_mul_f32_e32 v2, v2, v232
	v_mul_f32_e32 v3, v3, v233
; DI int otid512() { int t = threadIdx.x; asm volatile("" : "+v"(t)); return t; }
; DI float silu_(float x) { return x / (1.f + __expf(-x)); }
; template <class Epi>
; DI void gemm256_epilogue(f16v (&acc)[4][2], int m0, int n0, Epi epi) {
;   const int tid = otid512(), lane = tid & 63, wv = tid >> 6, wm = wv >> 2, wn = wv & 3, h = lane >> 5;
; #pragma unroll
;   for (int i = 0; i < 4; ++i) {
;     const int m = m0 + wm * 128 + i * 32 + (lane & 31);
; #pragma unroll
;     for (int g = 0; g < 4; ++g) {
;       const int n = n0 + wn * 64 + 8 * g + 4 * h;
;       f4v v0 = {acc[i][0][4 * g], acc[i][0][4 * g + 1], acc[i][0][4 * g + 2], acc[i][0][4 * g + 3]};
;       f4v v1 = {acc[i][1][4 * g], acc[i][1][4 * g + 1], acc[i][1][4 * g + 2], acc[i][1][4 * g + 3]};
;       epi(m, n, v0, v1);
;     }
;   }
; }
; DI void phase_ffn1_dense(const Params& p, int bid, int nb, h16* lds) {
;     ...
;     gemm256_epilogue(acc, m0, n0, [&](int m, int n, f4v v0, f4v v1) {
;       f4v hq;
; #pragma unroll
;       for (int i = 0; i < 4; ++i) hq[i] = silu_(v0[i]) * v1[i];
;       st_h4(&H[(size_t)m * 2816 + (n >> 6) * 32 + (n & 31)], hq);
	v_mul_f32_e32 v4, v4, v234
	v_mul_f32_e32 v5, v5, v235
	v_mul_f32_e32 v2, v2, v18
	v_mul_f32_e32 v3, v3, v19
	v_mul_f32_e32 v4, v4, v20
	v_mul_f32_e32 v5, v5, v21
	v_cvt_pk_f16_f32 v138, v2, v3
	v_cvt_pk_f16_f32 v139, v4, v5
	ds_write_b64 v130, v[138:139] offset:7680
	v_mul_f32_e32 v232, 0xbfb8aa3b, v6
	v_mul_f32_e32 v233, 0xbfb8aa3b, v7
	v_mul_f32_e32 v234, 0xbfb8aa3b, v8
	v_mul_f32_e32 v235, 0xbfb8aa3b, v9
	v_exp_f32_e32 v232, v232
	v_exp_f32_e32 v233, v233
	v_exp_f32_e32 v234, v234
	v_exp_f32_e32 v235, v235
	v_add_f32_e32 v232, 1.0, v232
	v_add_f32_e32 v233, 1.0, v233
	v_add_f32_e32 v234, 1.0, v234
	v_add_f32_e32 v235, 1.0, v235
	v_rcp_f32_e32 v232, v232
	v_rcp_f32_e32 v233, v233
	v_rcp_f32_e32 v234, v234
	v_rcp_f32_e32 v235, v235
	v_mul_f32_e32 v6, v6, v232
	v_mul_f32_e32 v7, v7, v233
	v_mul_f32_e32 v8, v8, v234
	v_mul_f32_e32 v9, v9, v235
	v_mul_f32_e32 v6, v6, v22
	v_mul_f32_e32 v7, v7, v23
	v_mul_f32_e32 v8, v8, v24
	v_mul_f32_e32 v9, v9, v25
	v_cvt_pk_f16_f32 v140, v6, v7
	v_cvt_pk_f16_f32 v141, v8, v9
	ds_write_b64 v130, v[140:141] offset:7696
	v_mul_f32_e32 v232, 0xbfb8aa3b, v10
	v_mul_f32_e32 v233, 0xbfb8aa3b, v11
	v_mul_f32_e32 v234, 0xbfb8aa3b, v12
	v_mul_f32_e32 v235, 0xbfb8aa3b, v13
	v_exp_f32_e32 v232, v232
	v_exp_f32_e32 v233, v233
	v_exp_f32_e32 v234, v234
	v_exp_f32_e32 v235, v235
	v_add_f32_e32 v232, 1.0, v232
	v_add_f32_e32 v233, 1.0, v233
	v_add_f32_e32 v234, 1.0, v234
	v_add_f32_e32 v235, 1.0, v235
	v_rcp_f32_e32 v232, v232
	v_rcp_f32_e32 v233, v233
	v_rcp_f32_e32 v234, v234
	v_rcp_f32_e32 v235, v235
	v_mul_f32_e32 v10, v10, v232
	v_mul_f32_e32 v11, v11, v233
	v_mul_f32_e32 v12, v12, v234
	v_mul_f32_e32 v13, v13, v235
	v_mul_f32_e32 v10, v10, v26
	v_mul_f32_e32 v11, v11, v27
	v_mul_f32_e32 v12, v12, v28
	v_mul_f32_e32 v13, v13, v29
	v_cvt_pk_f16_f32 v142, v10, v11
	v_cvt_pk_f16_f32 v143, v12, v13
	ds_write_b64 v130, v[142:143] offset:7712
	v_mul_f32_e32 v232, 0xbfb8aa3b, v14
	v_mul_f32_e32 v233, 0xbfb8aa3b, v15
	v_mul_f32_e32 v234, 0xbfb8aa3b, v16
	v_mul_f32_e32 v235, 0xbfb8aa3b, v17
	v_exp_f32_e32 v232, v232
	v_exp_f32_e32 v233, v233
	v_exp_f32_e32 v234, v234
	v_exp_f32_e32 v235, v235
	v_add_f32_e32 v232, 1.0, v232
	v_add_f32_e32 v233, 1.0, v233
	v_add_f32_e32 v234, 1.0, v234
	v_add_f32_e32 v235, 1.0, v235
	v_rcp_f32_e32 v232, v232
	v_rcp_f32_e32 v233, v233
	v_rcp_f32_e32 v234, v234
	v_rcp_f32_e32 v235, v235
	v_mul_f32_e32 v14, v14, v232
	v_mul_f32_e32 v15, v15, v233
	v_mul_f32_e32 v16, v16, v234
	v_mul_f32_e32 v17, v17, v235
	v_mul_f32_e32 v14, v14, v30
	v_mul_f32_e32 v15, v15, v31
	v_mul_f32_e32 v16, v16, v32
	v_mul_f32_e32 v17, v17, v33
	v_cvt_pk_f16_f32 v144, v14, v15
	v_cvt_pk_f16_f32 v145, v16, v17
	ds_write_b64 v130, v[144:145] offset:7728
	ds_read_b128 v[150:153], v131 offset:0
	ds_read_b128 v[154:157], v131 offset:1280
	ds_read_b128 v[158:161], v131 offset:2560
	ds_read_b128 v[162:165], v131 offset:3840
	ds_read_b128 v[216:219], v131 offset:5120
	ds_read_b128 v[220:223], v131 offset:6400
	ds_read_b128 v[224:227], v131 offset:7680
	ds_read_b128 v[228:231], v131 offset:8960
	s_waitcnt lgkmcnt(7)
	global_store_dwordx4 v[132:133], v[150:153], off
	v_lshl_add_u64 v[132:133], v[132:133], 0, s[76:77]
	s_waitcnt lgkmcnt(6)
	global_store_dwordx4 v[132:133], v[154:157], off
	v_lshl_add_u64 v[132:133], v[132:133], 0, s[76:77]
	s_waitcnt lgkmcnt(5)
	global_store_dwordx4 v[132:133], v[158:161], off
	v_lshl_add_u64 v[132:133], v[132:133], 0, s[76:77]
	s_waitcnt lgkmcnt(4)
	global_store_dwordx4 v[132:133], v[162:165], off
	v_lshl_add_u64 v[132:133], v[132:133], 0, s[76:77]
	s_waitcnt lgkmcnt(3)
	global_store_dwordx4 v[132:133], v[216:219], off
	v_lshl_add_u64 v[132:133], v[132:133], 0, s[76:77]
	s_waitcnt lgkmcnt(2)
	global_store_dwordx4 v[132:133], v[220:223], off
	v_lshl_add_u64 v[132:133], v[132:133], 0, s[76:77]
	s_waitcnt lgkmcnt(1)
	global_store_dwordx4 v[132:133], v[224:227], off
	v_lshl_add_u64 v[132:133], v[132:133], 0, s[76:77]
	s_waitcnt lgkmcnt(0)
	global_store_dwordx4 v[132:133], v[228:231], off
	v_lshl_add_u64 v[132:133], v[132:133], 0, s[76:77]
	s_add_i32 s2, s2, s16
	s_cmpk_lt_i32 s3, 0x580
	s_cbranch_scc1 .LBB0_1626
